# GEMM compute blocks: the back-to-back s_setprio 0 / s_setprio 1 pair between the two 16-MFMA groups deleted (A/B of a no-op flip)
# speedup vs baseline: 1.0053x; 1.0053x over previous
; #define PG8_STAGE(bufoff, gbase, voff) do { _Pragma("unroll") for (int _i = 0; _i < 2; ++_i) \
;         __builtin_amdgcn_global_load_lds((const unsigned*)((const char*)(gbase) + (voff)[_i]), (LAS unsigned*)(lds + (bufoff) + ldsw + _i * 8192), 16, 0, 0); } while (0)
; #define PG8_LDA(dst, b, h) do { _Pragma("unroll") for (int m = 0; m < 4; ++m) _Pragma("unroll") for (int k = 0; k < 2; ++k) dst[m][k] = *(const LAS bf16x8*)(lds + PG8_SA(b, h) + aoff + m * 2048 + k * 1024); } while (0)
; #define PG8_LDB(dst, b, h) do { _Pragma("unroll") for (int n = 0; n < 2; ++n) _Pragma("unroll") for (int k = 0; k < 2; ++k) dst[n][k] = *(const LAS bf16x8*)(lds + PG8_SB(b, h) + boff + n * 2048 + k * 1024); } while (0)
; #define PG8_MMA(ai, bj, At, Bt) do { __builtin_amdgcn_s_setprio(1); _Pragma("unroll") for (int m = 0; m < 4; ++m) _Pragma("unroll") for (int n = 0; n < 2; ++n) _Pragma("unroll") for (int k = 0; k < 2; ++k) \
;         acc[ai][bj][m][n] = __builtin_amdgcn_mfma_f32_16x16x32_bf16(Bt[n][k], At[m][k], acc[ai][bj][m][n], 0, 0, 0); __builtin_amdgcn_s_setprio(0); } while (0)
; #define PG8_WAIT_V(n) asm volatile("s_waitcnt vmcnt(" #n ")" ::: "memory")
; #define PG8_WAIT_L(n) asm volatile("s_waitcnt lgkmcnt(" #n ")" ::: "memory")
; #define PG8_BAR __builtin_amdgcn_s_barrier()
; template <class Epi, class Sched, bool ALIGN_EPI = true, bool SP2 = true>
; __device__ __forceinline__ void gemm_phase(LAS unsigned char* lds, const bf16_t* Ag, const bf16_t* Btg, const int K, const int lda, const int ldb, const Sched& S, const Epi& E) {
;     ...
;             const char* a1 = cA + (size_t)(t + 1) * kstep;
;             const char* a2 = last ? nA : cA + (size_t)(t + 2) * kstep; const char* b2 = last ? nB : cB + (size_t)(t + 2) * kstep;
;             const char* a3 = a2 + kstep; const char* b3 = b2 + kstep;
;             if constexpr (SP2) {
;             PG8_LDB(B0, 0, 0); PG8_LDB(B1, 0, 1); PG8_SCHED; PG8_LDA(At, 0, 0); PG8_STAGE(PG8_SA(1, 1), a1 + hstepA, voffA);
;             PG8_WAIT_V(8); PG8_WAIT_L(0); PG8_BAR; PG8_MMA(0, 0, At, B0); PG8_MMA(0, 1, At, B1); PG8_BAR; PG8_SCHED;
;             PG8_LDA(At, 0, 1); PG8_STAGE(PG8_SB(0, 0), b2, voffB); PG8_STAGE(PG8_SB(0, 1), b2 + hstepB, voffB); PG8_STAGE(PG8_SA(0, 0), a2, voffA);
;             PG8_WAIT_V(8); PG8_WAIT_L(0); PG8_BAR; PG8_MMA(1, 0, At, B0); PG8_MMA(1, 1, At, B1); PG8_BAR; PG8_SCHED;
.LBB0_119:
	ds_read_b128 v[152:155], v149
	ds_read_b128 v[156:159], v149 offset:1024
	ds_read_b128 v[160:163], v149 offset:2048
	ds_read_b128 v[164:167], v149 offset:3072
	ds_read_b128 v[168:171], v150
	ds_read_b128 v[172:175], v150 offset:1024
	ds_read_b128 v[178:181], v150 offset:2048
	ds_read_b128 v[182:185], v150 offset:3072
	s_add_u32 s10, s34, 0xfff80080
	s_addc_u32 s11, s35, -1
	s_cmp_eq_u32 s60, 28
	s_cselect_b32 s51, s8, s11
	s_cselect_b32 s50, s9, s10
	s_cselect_b32 s39, s33, s59
	s_cselect_b32 s38, s6, s7
	v_lshl_add_u64 v[146:147], s[34:35], 0, v[138:139]
	s_add_i32 m0, s46, 0xc000
	ds_read_b128 v[186:189], v151
	ds_read_b128 v[190:193], v151 offset:1024
	ds_read_b128 v[194:197], v151 offset:2048
	ds_read_b128 v[198:201], v151 offset:3072
	ds_read_b128 v[202:205], v151 offset:4096
	ds_read_b128 v[206:209], v151 offset:5120
	ds_read_b128 v[210:213], v151 offset:6144
	ds_read_b128 v[214:217], v151 offset:7168
	global_load_lds_dwordx4 v[146:147], off
	v_lshl_add_u64 v[146:147], s[34:35], 0, v[140:141]
	s_add_i32 m0, s46, 0xe000
	s_nop 0
	global_load_lds_dwordx4 v[146:147], off
	s_waitcnt vmcnt(8)
	s_waitcnt lgkmcnt(0)
	s_barrier
	s_setprio 1
	s_waitcnt lgkmcnt(0)
	v_mfma_f32_16x16x32_bf16 v[124:127], v[152:155], v[186:189], v[124:127]
	v_mfma_f32_16x16x32_bf16 v[116:119], v[160:163], v[186:189], v[116:119]
	v_mfma_f32_16x16x32_bf16 v[108:111], v[152:155], v[194:197], v[108:111]
	v_mfma_f32_16x16x32_bf16 v[100:103], v[160:163], v[194:197], v[100:103]
	v_mfma_f32_16x16x32_bf16 v[92:95], v[152:155], v[202:205], v[92:95]
	v_mfma_f32_16x16x32_bf16 v[84:87], v[160:163], v[202:205], v[84:87]
	v_mfma_f32_16x16x32_bf16 v[76:79], v[152:155], v[210:213], v[76:79]
	v_mfma_f32_16x16x32_bf16 v[68:71], v[160:163], v[210:213], v[68:71]
	v_mfma_f32_16x16x32_bf16 v[124:127], v[156:159], v[190:193], v[124:127]
	v_mfma_f32_16x16x32_bf16 v[116:119], v[164:167], v[190:193], v[116:119]
	v_mfma_f32_16x16x32_bf16 v[108:111], v[156:159], v[198:201], v[108:111]
	v_mfma_f32_16x16x32_bf16 v[100:103], v[164:167], v[198:201], v[100:103]
	v_mfma_f32_16x16x32_bf16 v[92:95], v[156:159], v[206:209], v[92:95]
	v_mfma_f32_16x16x32_bf16 v[84:87], v[164:167], v[206:209], v[84:87]
	v_mfma_f32_16x16x32_bf16 v[76:79], v[156:159], v[214:217], v[76:79]
	v_mfma_f32_16x16x32_bf16 v[68:71], v[164:167], v[214:217], v[68:71]
	v_mfma_f32_16x16x32_bf16 v[120:123], v[168:171], v[186:189], v[120:123]
	v_mfma_f32_16x16x32_bf16 v[112:115], v[178:181], v[186:189], v[112:115]
	v_mfma_f32_16x16x32_bf16 v[104:107], v[168:171], v[194:197], v[104:107]
	v_mfma_f32_16x16x32_bf16 v[96:99], v[178:181], v[194:197], v[96:99]
	v_mfma_f32_16x16x32_bf16 v[88:91], v[168:171], v[202:205], v[88:91]
	v_mfma_f32_16x16x32_bf16 v[80:83], v[178:181], v[202:205], v[80:83]
	v_mfma_f32_16x16x32_bf16 v[72:75], v[168:171], v[210:213], v[72:75]
	v_mfma_f32_16x16x32_bf16 v[64:67], v[178:181], v[210:213], v[64:67]
	v_mfma_f32_16x16x32_bf16 v[120:123], v[172:175], v[190:193], v[120:123]
	v_mfma_f32_16x16x32_bf16 v[112:115], v[182:185], v[190:193], v[112:115]
	v_mfma_f32_16x16x32_bf16 v[104:107], v[172:175], v[198:201], v[104:107]
	v_mfma_f32_16x16x32_bf16 v[96:99], v[182:185], v[198:201], v[96:99]
	v_mfma_f32_16x16x32_bf16 v[88:91], v[172:175], v[206:209], v[88:91]
	v_mfma_f32_16x16x32_bf16 v[80:83], v[182:185], v[206:209], v[80:83]
	s_setprio 2
	s_barrier
	v_mfma_f32_16x16x32_bf16 v[72:75], v[172:175], v[214:217], v[72:75]
	v_mfma_f32_16x16x32_bf16 v[64:67], v[182:185], v[214:217], v[64:67]
	s_setprio 0
	s_add_i32 s10, s57, s37
	v_lshl_add_u64 v[146:147], s[38:39], 0, v[132:133]
	s_mov_b32 m0, s10
	ds_read_b128 v[186:189], v151 offset:16384
	ds_read_b128 v[190:193], v151 offset:17408
	ds_read_b128 v[194:197], v151 offset:18432
	ds_read_b128 v[198:201], v151 offset:19456
	ds_read_b128 v[202:205], v151 offset:20480
	ds_read_b128 v[206:209], v151 offset:21504
	ds_read_b128 v[210:213], v151 offset:22528
	ds_read_b128 v[214:217], v151 offset:23552
	global_load_lds_dwordx4 v[146:147], off
	s_add_i32 m0, s10, 0x2000
	s_add_u32 s62, s38, 0x80000
	v_lshl_add_u64 v[218:219], s[38:39], 0, v[128:129]
	s_addc_u32 s63, s39, 0
	s_add_i32 s10, s58, s37
	global_load_lds_dwordx4 v[218:219], off
	v_lshl_add_u64 v[220:221], s[62:63], 0, v[132:133]
	s_mov_b32 m0, s10
	v_lshl_add_u64 v[222:223], s[50:51], 0, v[130:131]
	global_load_lds_dwordx4 v[220:221], off
	v_lshl_add_u64 v[220:221], s[62:63], 0, v[128:129]
	s_add_i32 m0, s10, 0x2000
	s_nop 0
	global_load_lds_dwordx4 v[220:221], off
	v_lshl_add_u64 v[220:221], s[50:51], 0, v[134:135]
	s_mov_b32 m0, s46
	s_nop 0
	global_load_lds_dwordx4 v[220:221], off
	s_mov_b32 m0, s47
	s_nop 0
	global_load_lds_dwordx4 v[222:223], off
	s_waitcnt vmcnt(8)
	s_waitcnt lgkmcnt(0)
	s_barrier
; #define PG8_STAGE(bufoff, gbase, voff) do { _Pragma("unroll") for (int _i = 0; _i < 2; ++_i) \
;         __builtin_amdgcn_global_load_lds((const unsigned*)((const char*)(gbase) + (voff)[_i]), (LAS unsigned*)(lds + (bufoff) + ldsw + _i * 8192), 16, 0, 0); } while (0)
; #define PG8_LDA(dst, b, h) do { _Pragma("unroll") for (int m = 0; m < 4; ++m) _Pragma("unroll") for (int k = 0; k < 2; ++k) dst[m][k] = *(const LAS bf16x8*)(lds + PG8_SA(b, h) + aoff + m * 2048 + k * 1024); } while (0)
; #define PG8_LDB(dst, b, h) do { _Pragma("unroll") for (int n = 0; n < 2; ++n) _Pragma("unroll") for (int k = 0; k < 2; ++k) dst[n][k] = *(const LAS bf16x8*)(lds + PG8_SB(b, h) + boff + n * 2048 + k * 1024); } while (0)
; #define PG8_MMA(ai, bj, At, Bt) do { __builtin_amdgcn_s_setprio(1); _Pragma("unroll") for (int m = 0; m < 4; ++m) _Pragma("unroll") for (int n = 0; n < 2; ++n) _Pragma("unroll") for (int k = 0; k < 2; ++k) \
;         acc[ai][bj][m][n] = __builtin_amdgcn_mfma_f32_16x16x32_bf16(Bt[n][k], At[m][k], acc[ai][bj][m][n], 0, 0, 0); __builtin_amdgcn_s_setprio(0); } while (0)
; #define PG8_WAIT_V(n) asm volatile("s_waitcnt vmcnt(" #n ")" ::: "memory")
; #define PG8_WAIT_L(n) asm volatile("s_waitcnt lgkmcnt(" #n ")" ::: "memory")
; #define PG8_BAR __builtin_amdgcn_s_barrier()
; #define PG8_SCHED __builtin_amdgcn_sched_barrier(0)
; template <class Epi, class Sched, bool ALIGN_EPI = true, bool SP2 = true>
; __device__ __forceinline__ void gemm_phase(LAS unsigned char* lds, const bf16_t* Ag, const bf16_t* Btg, const int K, const int lda, const int ldb, const Sched& S, const Epi& E) {
;     ...
;             PG8_WAIT_V(8); PG8_WAIT_L(0); PG8_BAR; PG8_MMA(1, 0, At, B0); PG8_MMA(1, 1, At, B1); PG8_BAR; PG8_SCHED;
;             PG8_LDB(B0, 1, 0); PG8_LDB(B1, 1, 1); PG8_SCHED; PG8_LDA(At, 1, 0); PG8_STAGE(PG8_SA(0, 1), a2 + hstepA, voffA);
;             PG8_WAIT_V(8); PG8_WAIT_L(0); PG8_BAR; PG8_MMA(0, 0, At, B0); PG8_MMA(0, 1, At, B1); PG8_BAR; PG8_SCHED;
	s_setprio 1
	s_waitcnt lgkmcnt(0)
	v_mfma_f32_16x16x32_bf16 v[60:63], v[152:155], v[186:189], v[60:63]
	v_mfma_f32_16x16x32_bf16 v[52:55], v[160:163], v[186:189], v[52:55]
	v_mfma_f32_16x16x32_bf16 v[44:47], v[152:155], v[194:197], v[44:47]
	v_mfma_f32_16x16x32_bf16 v[36:39], v[160:163], v[194:197], v[36:39]
	v_mfma_f32_16x16x32_bf16 v[28:31], v[152:155], v[202:205], v[28:31]
	v_mfma_f32_16x16x32_bf16 v[20:23], v[160:163], v[202:205], v[20:23]
	v_mfma_f32_16x16x32_bf16 v[12:15], v[152:155], v[210:213], v[12:15]
	v_mfma_f32_16x16x32_bf16 v[4:7], v[160:163], v[210:213], v[4:7]
	v_mfma_f32_16x16x32_bf16 v[60:63], v[156:159], v[190:193], v[60:63]
	v_mfma_f32_16x16x32_bf16 v[52:55], v[164:167], v[190:193], v[52:55]
	v_mfma_f32_16x16x32_bf16 v[44:47], v[156:159], v[198:201], v[44:47]
	v_mfma_f32_16x16x32_bf16 v[36:39], v[164:167], v[198:201], v[36:39]
	v_mfma_f32_16x16x32_bf16 v[28:31], v[156:159], v[206:209], v[28:31]
	v_mfma_f32_16x16x32_bf16 v[20:23], v[164:167], v[206:209], v[20:23]
	v_mfma_f32_16x16x32_bf16 v[12:15], v[156:159], v[214:217], v[12:15]
	v_mfma_f32_16x16x32_bf16 v[4:7], v[164:167], v[214:217], v[4:7]
	v_mfma_f32_16x16x32_bf16 v[56:59], v[168:171], v[186:189], v[56:59]
	v_mfma_f32_16x16x32_bf16 v[48:51], v[178:181], v[186:189], v[48:51]
	v_mfma_f32_16x16x32_bf16 v[40:43], v[168:171], v[194:197], v[40:43]
	v_mfma_f32_16x16x32_bf16 v[32:35], v[178:181], v[194:197], v[32:35]
	v_mfma_f32_16x16x32_bf16 v[24:27], v[168:171], v[202:205], v[24:27]
	v_mfma_f32_16x16x32_bf16 v[16:19], v[178:181], v[202:205], v[16:19]
	v_mfma_f32_16x16x32_bf16 v[8:11], v[168:171], v[210:213], v[8:11]
	v_mfma_f32_16x16x32_bf16 v[0:3], v[178:181], v[210:213], v[0:3]
	v_mfma_f32_16x16x32_bf16 v[56:59], v[172:175], v[190:193], v[56:59]
	v_mfma_f32_16x16x32_bf16 v[48:51], v[182:185], v[190:193], v[48:51]
	v_mfma_f32_16x16x32_bf16 v[40:43], v[172:175], v[198:201], v[40:43]
	v_mfma_f32_16x16x32_bf16 v[32:35], v[182:185], v[198:201], v[32:35]
	v_mfma_f32_16x16x32_bf16 v[24:27], v[172:175], v[206:209], v[24:27]
	v_mfma_f32_16x16x32_bf16 v[16:19], v[182:185], v[206:209], v[16:19]
	s_setprio 2
	s_barrier
	v_mfma_f32_16x16x32_bf16 v[8:11], v[172:175], v[214:217], v[8:11]
	v_mfma_f32_16x16x32_bf16 v[0:3], v[182:185], v[214:217], v[0:3]
	s_setprio 0
	s_add_i32 s10, 0, 0x18000
	s_add_i32 s11, 0, 0x1c000
	v_add_u32_e32 v164, s10, v148
	v_add_u32_e32 v182, s11, v148
	ds_read_b128 v[152:155], v164
	ds_read_b128 v[156:159], v164 offset:1024
	ds_read_b128 v[160:163], v164 offset:2048
	ds_read_b128 v[164:167], v164 offset:3072
	ds_read_b128 v[168:171], v182
	ds_read_b128 v[172:175], v182 offset:1024
	ds_read_b128 v[178:181], v182 offset:2048
	ds_read_b128 v[182:185], v182 offset:3072
	s_add_u32 s50, s50, 0x80000
	s_addc_u32 s51, s51, 0
	s_mov_b32 m0, s52
	v_lshl_add_u64 v[224:225], s[50:51], 0, v[134:135]
	ds_read_b128 v[186:189], v151 offset:32768
	ds_read_b128 v[190:193], v151 offset:33792
	ds_read_b128 v[194:197], v151 offset:34816
	ds_read_b128 v[198:201], v151 offset:35840
	ds_read_b128 v[202:205], v151 offset:36864
	ds_read_b128 v[206:209], v151 offset:37888
	ds_read_b128 v[210:213], v151 offset:38912
	ds_read_b128 v[214:217], v151 offset:39936
	global_load_lds_dwordx4 v[224:225], off
	v_lshl_add_u64 v[224:225], s[50:51], 0, v[130:131]
	s_mov_b32 m0, s53
	s_nop 0
	global_load_lds_dwordx4 v[224:225], off
	s_waitcnt vmcnt(8)
	s_waitcnt lgkmcnt(0)
	s_barrier
	s_setprio 1
	s_waitcnt lgkmcnt(0)
	v_mfma_f32_16x16x32_bf16 v[124:127], v[152:155], v[186:189], v[124:127]
	v_mfma_f32_16x16x32_bf16 v[116:119], v[160:163], v[186:189], v[116:119]
	v_mfma_f32_16x16x32_bf16 v[108:111], v[152:155], v[194:197], v[108:111]
	v_mfma_f32_16x16x32_bf16 v[100:103], v[160:163], v[194:197], v[100:103]
	v_mfma_f32_16x16x32_bf16 v[92:95], v[152:155], v[202:205], v[92:95]
	v_mfma_f32_16x16x32_bf16 v[84:87], v[160:163], v[202:205], v[84:87]
	v_mfma_f32_16x16x32_bf16 v[76:79], v[152:155], v[210:213], v[76:79]
	v_mfma_f32_16x16x32_bf16 v[68:71], v[160:163], v[210:213], v[68:71]
	v_mfma_f32_16x16x32_bf16 v[124:127], v[156:159], v[190:193], v[124:127]
	v_mfma_f32_16x16x32_bf16 v[116:119], v[164:167], v[190:193], v[116:119]
	v_mfma_f32_16x16x32_bf16 v[108:111], v[156:159], v[198:201], v[108:111]
	v_mfma_f32_16x16x32_bf16 v[100:103], v[164:167], v[198:201], v[100:103]
	v_mfma_f32_16x16x32_bf16 v[92:95], v[156:159], v[206:209], v[92:95]
	v_mfma_f32_16x16x32_bf16 v[84:87], v[164:167], v[206:209], v[84:87]
	v_mfma_f32_16x16x32_bf16 v[76:79], v[156:159], v[214:217], v[76:79]
	v_mfma_f32_16x16x32_bf16 v[68:71], v[164:167], v[214:217], v[68:71]
	v_mfma_f32_16x16x32_bf16 v[120:123], v[168:171], v[186:189], v[120:123]
	v_mfma_f32_16x16x32_bf16 v[112:115], v[178:181], v[186:189], v[112:115]
	v_mfma_f32_16x16x32_bf16 v[104:107], v[168:171], v[194:197], v[104:107]
	v_mfma_f32_16x16x32_bf16 v[96:99], v[178:181], v[194:197], v[96:99]
	v_mfma_f32_16x16x32_bf16 v[88:91], v[168:171], v[202:205], v[88:91]
	v_mfma_f32_16x16x32_bf16 v[80:83], v[178:181], v[202:205], v[80:83]
	v_mfma_f32_16x16x32_bf16 v[72:75], v[168:171], v[210:213], v[72:75]
	v_mfma_f32_16x16x32_bf16 v[64:67], v[178:181], v[210:213], v[64:67]
	v_mfma_f32_16x16x32_bf16 v[120:123], v[172:175], v[190:193], v[120:123]
	v_mfma_f32_16x16x32_bf16 v[112:115], v[182:185], v[190:193], v[112:115]
	v_mfma_f32_16x16x32_bf16 v[104:107], v[172:175], v[198:201], v[104:107]
	v_mfma_f32_16x16x32_bf16 v[96:99], v[182:185], v[198:201], v[96:99]
	v_mfma_f32_16x16x32_bf16 v[88:91], v[172:175], v[206:209], v[88:91]
	v_mfma_f32_16x16x32_bf16 v[80:83], v[182:185], v[206:209], v[80:83]
	s_setprio 2
	s_barrier
; #define PG8_STAGE(bufoff, gbase, voff) do { _Pragma("unroll") for (int _i = 0; _i < 2; ++_i) \
;         __builtin_amdgcn_global_load_lds((const unsigned*)((const char*)(gbase) + (voff)[_i]), (LAS unsigned*)(lds + (bufoff) + ldsw + _i * 8192), 16, 0, 0); } while (0)
; #define PG8_LDA(dst, b, h) do { _Pragma("unroll") for (int m = 0; m < 4; ++m) _Pragma("unroll") for (int k = 0; k < 2; ++k) dst[m][k] = *(const LAS bf16x8*)(lds + PG8_SA(b, h) + aoff + m * 2048 + k * 1024); } while (0)
; #define PG8_MMA(ai, bj, At, Bt) do { __builtin_amdgcn_s_setprio(1); _Pragma("unroll") for (int m = 0; m < 4; ++m) _Pragma("unroll") for (int n = 0; n < 2; ++n) _Pragma("unroll") for (int k = 0; k < 2; ++k) \
;         acc[ai][bj][m][n] = __builtin_amdgcn_mfma_f32_16x16x32_bf16(Bt[n][k], At[m][k], acc[ai][bj][m][n], 0, 0, 0); __builtin_amdgcn_s_setprio(0); } while (0)
; #define PG8_WAIT_V(n) asm volatile("s_waitcnt vmcnt(" #n ")" ::: "memory")
; #define PG8_WAIT_L(n) asm volatile("s_waitcnt lgkmcnt(" #n ")" ::: "memory")
; #define PG8_BAR __builtin_amdgcn_s_barrier()
; #define PG8_SCHED __builtin_amdgcn_sched_barrier(0)
; template <class Epi, class Sched, bool ALIGN_EPI = true, bool SP2 = true>
; __device__ __forceinline__ void gemm_phase(LAS unsigned char* lds, const bf16_t* Ag, const bf16_t* Btg, const int K, const int lda, const int ldb, const Sched& S, const Epi& E) {
;     ...
;             PG8_WAIT_V(8); PG8_WAIT_L(0); PG8_BAR; PG8_MMA(0, 0, At, B0); PG8_MMA(0, 1, At, B1); PG8_BAR; PG8_SCHED;
;             PG8_LDA(At, 1, 1); PG8_STAGE(PG8_SB(1, 0), b3, voffB); PG8_STAGE(PG8_SB(1, 1), b3 + hstepB, voffB); PG8_STAGE(PG8_SA(1, 0), a3, voffA);
;             PG8_WAIT_V(8); PG8_WAIT_L(0); PG8_BAR; PG8_MMA(1, 0, At, B0); PG8_MMA(1, 1, At, B1); PG8_BAR; PG8_SCHED;
	v_mfma_f32_16x16x32_bf16 v[72:75], v[172:175], v[214:217], v[72:75]
	v_mfma_f32_16x16x32_bf16 v[64:67], v[182:185], v[214:217], v[64:67]
	s_setprio 0
	s_add_i32 s10, s10, s37
	v_lshl_add_u64 v[146:147], v[146:147], 0, s[16:17]
	s_mov_b32 m0, s10
	ds_read_b128 v[186:189], v151 offset:49152
	ds_read_b128 v[190:193], v151 offset:50176
	ds_read_b128 v[194:197], v151 offset:51200
	ds_read_b128 v[198:201], v151 offset:52224
	ds_read_b128 v[202:205], v151 offset:53248
	ds_read_b128 v[206:209], v151 offset:54272
	ds_read_b128 v[210:213], v151 offset:55296
	ds_read_b128 v[214:217], v151 offset:56320
	global_load_lds_dwordx4 v[146:147], off
	s_add_i32 m0, s10, 0x2000
	s_add_u32 s38, s38, 0x80080
	v_lshl_add_u64 v[146:147], v[218:219], 0, s[16:17]
	s_addc_u32 s39, s39, 0
	s_add_i32 s10, s11, s37
	global_load_lds_dwordx4 v[146:147], off
	v_lshl_add_u64 v[146:147], s[38:39], 0, v[132:133]
	s_mov_b32 m0, s10
	s_nop 0
	global_load_lds_dwordx4 v[146:147], off
	v_lshl_add_u64 v[146:147], s[38:39], 0, v[128:129]
	s_add_i32 m0, s10, 0x2000
	s_nop 0
	global_load_lds_dwordx4 v[146:147], off
	v_lshl_add_u64 v[146:147], v[220:221], 0, s[16:17]
	s_mov_b32 m0, s54
	s_nop 0
	global_load_lds_dwordx4 v[146:147], off
	v_lshl_add_u64 v[146:147], v[222:223], 0, s[16:17]
	s_mov_b32 m0, s55
	s_nop 0
	global_load_lds_dwordx4 v[146:147], off
	s_waitcnt vmcnt(8)
	s_waitcnt lgkmcnt(0)
	s_barrier
	s_setprio 1
	s_waitcnt lgkmcnt(0)
	v_mfma_f32_16x16x32_bf16 v[60:63], v[152:155], v[186:189], v[60:63]
	v_mfma_f32_16x16x32_bf16 v[52:55], v[160:163], v[186:189], v[52:55]
	v_mfma_f32_16x16x32_bf16 v[44:47], v[152:155], v[194:197], v[44:47]
	v_mfma_f32_16x16x32_bf16 v[36:39], v[160:163], v[194:197], v[36:39]
	v_mfma_f32_16x16x32_bf16 v[28:31], v[152:155], v[202:205], v[28:31]
	v_mfma_f32_16x16x32_bf16 v[20:23], v[160:163], v[202:205], v[20:23]
	v_mfma_f32_16x16x32_bf16 v[12:15], v[152:155], v[210:213], v[12:15]
	v_mfma_f32_16x16x32_bf16 v[4:7], v[160:163], v[210:213], v[4:7]
	v_mfma_f32_16x16x32_bf16 v[60:63], v[156:159], v[190:193], v[60:63]
	v_mfma_f32_16x16x32_bf16 v[52:55], v[164:167], v[190:193], v[52:55]
	v_mfma_f32_16x16x32_bf16 v[44:47], v[156:159], v[198:201], v[44:47]
	v_mfma_f32_16x16x32_bf16 v[36:39], v[164:167], v[198:201], v[36:39]
	v_mfma_f32_16x16x32_bf16 v[28:31], v[156:159], v[206:209], v[28:31]
	v_mfma_f32_16x16x32_bf16 v[20:23], v[164:167], v[206:209], v[20:23]
	v_mfma_f32_16x16x32_bf16 v[12:15], v[156:159], v[214:217], v[12:15]
	v_mfma_f32_16x16x32_bf16 v[4:7], v[164:167], v[214:217], v[4:7]
	v_mfma_f32_16x16x32_bf16 v[56:59], v[168:171], v[186:189], v[56:59]
	v_mfma_f32_16x16x32_bf16 v[48:51], v[178:181], v[186:189], v[48:51]
	v_mfma_f32_16x16x32_bf16 v[40:43], v[168:171], v[194:197], v[40:43]
	v_mfma_f32_16x16x32_bf16 v[32:35], v[178:181], v[194:197], v[32:35]
	v_mfma_f32_16x16x32_bf16 v[24:27], v[168:171], v[202:205], v[24:27]
	v_mfma_f32_16x16x32_bf16 v[16:19], v[178:181], v[202:205], v[16:19]
	v_mfma_f32_16x16x32_bf16 v[8:11], v[168:171], v[210:213], v[8:11]
	v_mfma_f32_16x16x32_bf16 v[0:3], v[178:181], v[210:213], v[0:3]
	v_mfma_f32_16x16x32_bf16 v[56:59], v[172:175], v[190:193], v[56:59]
	v_mfma_f32_16x16x32_bf16 v[48:51], v[182:185], v[190:193], v[48:51]
	v_mfma_f32_16x16x32_bf16 v[40:43], v[172:175], v[198:201], v[40:43]
	v_mfma_f32_16x16x32_bf16 v[32:35], v[182:185], v[198:201], v[32:35]
	v_mfma_f32_16x16x32_bf16 v[24:27], v[172:175], v[206:209], v[24:27]
	v_mfma_f32_16x16x32_bf16 v[16:19], v[182:185], v[206:209], v[16:19]
	s_setprio 2
	s_barrier
	v_mfma_f32_16x16x32_bf16 v[8:11], v[172:175], v[214:217], v[8:11]
	v_mfma_f32_16x16x32_bf16 v[0:3], v[182:185], v[214:217], v[0:3]
	s_setprio 0
	s_add_i32 s60, s60, 2
	s_add_u32 s34, s34, 0x100
	s_addc_u32 s35, s35, 0
	s_add_u32 s7, s7, 0x100
	s_addc_u32 s59, s59, 0
	s_cmp_gt_u32 s60, 29
	s_cbranch_scc0 .LBB0_119
	s_and_b64 vcc, exec, s[18:19]
	s_cbranch_vccz .LBB0_122
	s_barrier

; #define PG8_STAGE(bufoff, gbase, voff) do { _Pragma("unroll") for (int _i = 0; _i < 2; ++_i) \
;         __builtin_amdgcn_global_load_lds((const unsigned*)((const char*)(gbase) + (voff)[_i]), (LAS unsigned*)(lds + (bufoff) + ldsw + _i * 8192), 16, 0, 0); } while (0)
; #define PG8_LDA(dst, b, h) do { _Pragma("unroll") for (int m = 0; m < 4; ++m) _Pragma("unroll") for (int k = 0; k < 2; ++k) dst[m][k] = *(const LAS bf16x8*)(lds + PG8_SA(b, h) + aoff + m * 2048 + k * 1024); } while (0)
; #define PG8_LDB(dst, b, h) do { _Pragma("unroll") for (int n = 0; n < 2; ++n) _Pragma("unroll") for (int k = 0; k < 2; ++k) dst[n][k] = *(const LAS bf16x8*)(lds + PG8_SB(b, h) + boff + n * 2048 + k * 1024); } while (0)
; #define PG8_MMA(ai, bj, At, Bt) do { __builtin_amdgcn_s_setprio(1); _Pragma("unroll") for (int m = 0; m < 4; ++m) _Pragma("unroll") for (int n = 0; n < 2; ++n) _Pragma("unroll") for (int k = 0; k < 2; ++k) \
;         acc[ai][bj][m][n] = __builtin_amdgcn_mfma_f32_16x16x32_bf16(Bt[n][k], At[m][k], acc[ai][bj][m][n], 0, 0, 0); __builtin_amdgcn_s_setprio(0); } while (0)
; #define PG8_WAIT_V(n) asm volatile("s_waitcnt vmcnt(" #n ")" ::: "memory")
; #define PG8_WAIT_L(n) asm volatile("s_waitcnt lgkmcnt(" #n ")" ::: "memory")
; #define PG8_BAR __builtin_amdgcn_s_barrier()
; template <class Epi, class Sched, bool ALIGN_EPI = true, bool SP2 = true>
; __device__ __forceinline__ void gemm_phase(LAS unsigned char* lds, const bf16_t* Ag, const bf16_t* Btg, const int K, const int lda, const int ldb, const Sched& S, const Epi& E) {
;     ...
;             const char* a1 = cA + (size_t)(t + 1) * kstep;
;             const char* a2 = last ? nA : cA + (size_t)(t + 2) * kstep; const char* b2 = last ? nB : cB + (size_t)(t + 2) * kstep;
;             const char* a3 = a2 + kstep; const char* b3 = b2 + kstep;
;             if constexpr (SP2) {
;             PG8_LDB(B0, 0, 0); PG8_LDB(B1, 0, 1); PG8_SCHED; PG8_LDA(At, 0, 0); PG8_STAGE(PG8_SA(1, 1), a1 + hstepA, voffA);
;             PG8_WAIT_V(8); PG8_WAIT_L(0); PG8_BAR; PG8_MMA(0, 0, At, B0); PG8_MMA(0, 1, At, B1); PG8_BAR; PG8_SCHED;
;             PG8_LDA(At, 0, 1); PG8_STAGE(PG8_SB(0, 0), b2, voffB); PG8_STAGE(PG8_SB(0, 1), b2 + hstepB, voffB); PG8_STAGE(PG8_SA(0, 0), a2, voffA);
;             PG8_WAIT_V(8); PG8_WAIT_L(0); PG8_BAR; PG8_MMA(1, 0, At, B0); PG8_MMA(1, 1, At, B1); PG8_BAR; PG8_SCHED;
.LBB0_199:
	ds_read_b128 v[146:149], v151
	ds_read_b128 v[154:157], v151 offset:1024
	ds_read_b128 v[158:161], v151 offset:2048
	ds_read_b128 v[162:165], v151 offset:3072
	ds_read_b128 v[166:169], v152
	ds_read_b128 v[170:173], v152 offset:1024
	ds_read_b128 v[178:181], v152 offset:2048
	ds_read_b128 v[182:185], v152 offset:3072
	s_add_u32 s1, s84, 0xffea0080
	s_addc_u32 s10, s85, -1
	s_cmpk_eq_i32 s0, 0x54
	s_cselect_b32 s71, vcc_lo, s10
	s_cselect_b32 s70, vcc_hi, s1
	s_cselect_b32 s67, s6, s73
	s_cselect_b32 s66, s7, s72
	v_lshl_add_u64 v[174:175], s[84:85], 0, v[138:139]
	s_add_i32 m0, s40, 0xc000
	ds_read_b128 v[186:189], v153
	ds_read_b128 v[190:193], v153 offset:1024
	ds_read_b128 v[194:197], v153 offset:2048
	ds_read_b128 v[198:201], v153 offset:3072
	ds_read_b128 v[202:205], v153 offset:4096
	ds_read_b128 v[206:209], v153 offset:5120
	ds_read_b128 v[210:213], v153 offset:6144
	ds_read_b128 v[214:217], v153 offset:7168
	global_load_lds_dwordx4 v[174:175], off
	v_lshl_add_u64 v[174:175], s[84:85], 0, v[140:141]
	s_add_i32 m0, s40, 0xe000
	s_nop 0
	global_load_lds_dwordx4 v[174:175], off
	s_waitcnt vmcnt(8)
	s_waitcnt lgkmcnt(0)
	s_barrier
	s_setprio 1
	s_waitcnt lgkmcnt(0)
	v_mfma_f32_16x16x32_bf16 v[124:127], v[146:149], v[186:189], v[124:127]
	v_mfma_f32_16x16x32_bf16 v[120:123], v[158:161], v[186:189], v[120:123]
	v_mfma_f32_16x16x32_bf16 v[116:119], v[146:149], v[194:197], v[116:119]
	v_mfma_f32_16x16x32_bf16 v[104:107], v[158:161], v[194:197], v[104:107]
	v_mfma_f32_16x16x32_bf16 v[100:103], v[146:149], v[202:205], v[100:103]
	v_mfma_f32_16x16x32_bf16 v[88:91], v[158:161], v[202:205], v[88:91]
	v_mfma_f32_16x16x32_bf16 v[84:87], v[146:149], v[210:213], v[84:87]
	v_mfma_f32_16x16x32_bf16 v[72:75], v[158:161], v[210:213], v[72:75]
	v_mfma_f32_16x16x32_bf16 v[124:127], v[154:157], v[190:193], v[124:127]
	v_mfma_f32_16x16x32_bf16 v[120:123], v[162:165], v[190:193], v[120:123]
	v_mfma_f32_16x16x32_bf16 v[116:119], v[154:157], v[198:201], v[116:119]
	v_mfma_f32_16x16x32_bf16 v[104:107], v[162:165], v[198:201], v[104:107]
	v_mfma_f32_16x16x32_bf16 v[100:103], v[154:157], v[206:209], v[100:103]
	v_mfma_f32_16x16x32_bf16 v[88:91], v[162:165], v[206:209], v[88:91]
	v_mfma_f32_16x16x32_bf16 v[84:87], v[154:157], v[214:217], v[84:87]
	v_mfma_f32_16x16x32_bf16 v[72:75], v[162:165], v[214:217], v[72:75]
	v_mfma_f32_16x16x32_bf16 v[112:115], v[166:169], v[186:189], v[112:115]
	v_mfma_f32_16x16x32_bf16 v[108:111], v[178:181], v[186:189], v[108:111]
	v_mfma_f32_16x16x32_bf16 v[96:99], v[166:169], v[194:197], v[96:99]
	v_mfma_f32_16x16x32_bf16 v[92:95], v[178:181], v[194:197], v[92:95]
	v_mfma_f32_16x16x32_bf16 v[80:83], v[166:169], v[202:205], v[80:83]
	v_mfma_f32_16x16x32_bf16 v[76:79], v[178:181], v[202:205], v[76:79]
	v_mfma_f32_16x16x32_bf16 v[68:71], v[166:169], v[210:213], v[68:71]
	v_mfma_f32_16x16x32_bf16 v[64:67], v[178:181], v[210:213], v[64:67]
	v_mfma_f32_16x16x32_bf16 v[112:115], v[170:173], v[190:193], v[112:115]
	v_mfma_f32_16x16x32_bf16 v[108:111], v[182:185], v[190:193], v[108:111]
	v_mfma_f32_16x16x32_bf16 v[96:99], v[170:173], v[198:201], v[96:99]
	v_mfma_f32_16x16x32_bf16 v[92:95], v[182:185], v[198:201], v[92:95]
	v_mfma_f32_16x16x32_bf16 v[80:83], v[170:173], v[206:209], v[80:83]
	v_mfma_f32_16x16x32_bf16 v[76:79], v[182:185], v[206:209], v[76:79]
	s_setprio 2
	s_barrier
	v_mfma_f32_16x16x32_bf16 v[68:71], v[170:173], v[214:217], v[68:71]
	v_mfma_f32_16x16x32_bf16 v[64:67], v[182:185], v[214:217], v[64:67]
	s_setprio 0
	s_add_i32 s1, s79, s37
	v_lshl_add_u64 v[174:175], s[66:67], 0, v[130:131]
	s_mov_b32 m0, s1
	ds_read_b128 v[186:189], v153 offset:16384
	ds_read_b128 v[190:193], v153 offset:17408
	ds_read_b128 v[194:197], v153 offset:18432
	ds_read_b128 v[198:201], v153 offset:19456
	ds_read_b128 v[202:205], v153 offset:20480
	ds_read_b128 v[206:209], v153 offset:21504
	ds_read_b128 v[210:213], v153 offset:22528
	ds_read_b128 v[214:217], v153 offset:23552
	global_load_lds_dwordx4 v[174:175], off
	s_add_i32 m0, s1, 0x2000
	s_add_u32 s10, s66, 0x160000
	v_lshl_add_u64 v[218:219], s[66:67], 0, v[134:135]
	s_addc_u32 s11, s67, 0
	s_add_i32 s1, s82, s37
	global_load_lds_dwordx4 v[218:219], off
	v_lshl_add_u64 v[220:221], s[10:11], 0, v[130:131]
	s_mov_b32 m0, s1
	v_lshl_add_u64 v[222:223], s[70:71], 0, v[132:133]
	global_load_lds_dwordx4 v[220:221], off
	v_lshl_add_u64 v[220:221], s[10:11], 0, v[134:135]
	s_add_i32 m0, s1, 0x2000
	s_nop 0
	global_load_lds_dwordx4 v[220:221], off
	v_lshl_add_u64 v[220:221], s[70:71], 0, v[128:129]
	s_mov_b32 m0, s40
	s_nop 0
	global_load_lds_dwordx4 v[220:221], off
	s_mov_b32 m0, s41
	s_nop 0
	global_load_lds_dwordx4 v[222:223], off
	s_waitcnt vmcnt(8)
	s_waitcnt lgkmcnt(0)
	s_barrier
; #define PG8_STAGE(bufoff, gbase, voff) do { _Pragma("unroll") for (int _i = 0; _i < 2; ++_i) \
;         __builtin_amdgcn_global_load_lds((const unsigned*)((const char*)(gbase) + (voff)[_i]), (LAS unsigned*)(lds + (bufoff) + ldsw + _i * 8192), 16, 0, 0); } while (0)
; #define PG8_LDA(dst, b, h) do { _Pragma("unroll") for (int m = 0; m < 4; ++m) _Pragma("unroll") for (int k = 0; k < 2; ++k) dst[m][k] = *(const LAS bf16x8*)(lds + PG8_SA(b, h) + aoff + m * 2048 + k * 1024); } while (0)
; #define PG8_LDB(dst, b, h) do { _Pragma("unroll") for (int n = 0; n < 2; ++n) _Pragma("unroll") for (int k = 0; k < 2; ++k) dst[n][k] = *(const LAS bf16x8*)(lds + PG8_SB(b, h) + boff + n * 2048 + k * 1024); } while (0)
; #define PG8_MMA(ai, bj, At, Bt) do { __builtin_amdgcn_s_setprio(1); _Pragma("unroll") for (int m = 0; m < 4; ++m) _Pragma("unroll") for (int n = 0; n < 2; ++n) _Pragma("unroll") for (int k = 0; k < 2; ++k) \
;         acc[ai][bj][m][n] = __builtin_amdgcn_mfma_f32_16x16x32_bf16(Bt[n][k], At[m][k], acc[ai][bj][m][n], 0, 0, 0); __builtin_amdgcn_s_setprio(0); } while (0)
; #define PG8_WAIT_V(n) asm volatile("s_waitcnt vmcnt(" #n ")" ::: "memory")
; #define PG8_WAIT_L(n) asm volatile("s_waitcnt lgkmcnt(" #n ")" ::: "memory")
; #define PG8_BAR __builtin_amdgcn_s_barrier()
; #define PG8_SCHED __builtin_amdgcn_sched_barrier(0)
; template <class Epi, class Sched, bool ALIGN_EPI = true, bool SP2 = true>
; __device__ __forceinline__ void gemm_phase(LAS unsigned char* lds, const bf16_t* Ag, const bf16_t* Btg, const int K, const int lda, const int ldb, const Sched& S, const Epi& E) {
;     ...
;             PG8_WAIT_V(8); PG8_WAIT_L(0); PG8_BAR; PG8_MMA(1, 0, At, B0); PG8_MMA(1, 1, At, B1); PG8_BAR; PG8_SCHED;
;             PG8_LDB(B0, 1, 0); PG8_LDB(B1, 1, 1); PG8_SCHED; PG8_LDA(At, 1, 0); PG8_STAGE(PG8_SA(0, 1), a2 + hstepA, voffA);
;             PG8_WAIT_V(8); PG8_WAIT_L(0); PG8_BAR; PG8_MMA(0, 0, At, B0); PG8_MMA(0, 1, At, B1); PG8_BAR; PG8_SCHED;
	s_setprio 1
	s_waitcnt lgkmcnt(0)
	v_mfma_f32_16x16x32_bf16 v[60:63], v[146:149], v[186:189], v[60:63]
	v_mfma_f32_16x16x32_bf16 v[56:59], v[158:161], v[186:189], v[56:59]
	v_mfma_f32_16x16x32_bf16 v[52:55], v[146:149], v[194:197], v[52:55]
	v_mfma_f32_16x16x32_bf16 v[40:43], v[158:161], v[194:197], v[40:43]
	v_mfma_f32_16x16x32_bf16 v[36:39], v[146:149], v[202:205], v[36:39]
	v_mfma_f32_16x16x32_bf16 v[24:27], v[158:161], v[202:205], v[24:27]
	v_mfma_f32_16x16x32_bf16 v[16:19], v[146:149], v[210:213], v[16:19]
	v_mfma_f32_16x16x32_bf16 v[8:11], v[158:161], v[210:213], v[8:11]
	v_mfma_f32_16x16x32_bf16 v[60:63], v[154:157], v[190:193], v[60:63]
	v_mfma_f32_16x16x32_bf16 v[56:59], v[162:165], v[190:193], v[56:59]
	v_mfma_f32_16x16x32_bf16 v[52:55], v[154:157], v[198:201], v[52:55]
	v_mfma_f32_16x16x32_bf16 v[40:43], v[162:165], v[198:201], v[40:43]
	v_mfma_f32_16x16x32_bf16 v[36:39], v[154:157], v[206:209], v[36:39]
	v_mfma_f32_16x16x32_bf16 v[24:27], v[162:165], v[206:209], v[24:27]
	v_mfma_f32_16x16x32_bf16 v[16:19], v[154:157], v[214:217], v[16:19]
	v_mfma_f32_16x16x32_bf16 v[8:11], v[162:165], v[214:217], v[8:11]
	v_mfma_f32_16x16x32_bf16 v[48:51], v[166:169], v[186:189], v[48:51]
	v_mfma_f32_16x16x32_bf16 v[44:47], v[178:181], v[186:189], v[44:47]
	v_mfma_f32_16x16x32_bf16 v[32:35], v[166:169], v[194:197], v[32:35]
	v_mfma_f32_16x16x32_bf16 v[28:31], v[178:181], v[194:197], v[28:31]
	v_mfma_f32_16x16x32_bf16 v[20:23], v[166:169], v[202:205], v[20:23]
	v_mfma_f32_16x16x32_bf16 v[12:15], v[178:181], v[202:205], v[12:15]
	v_mfma_f32_16x16x32_bf16 v[4:7], v[166:169], v[210:213], v[4:7]
	v_mfma_f32_16x16x32_bf16 v[0:3], v[178:181], v[210:213], v[0:3]
	v_mfma_f32_16x16x32_bf16 v[48:51], v[170:173], v[190:193], v[48:51]
	v_mfma_f32_16x16x32_bf16 v[44:47], v[182:185], v[190:193], v[44:47]
	v_mfma_f32_16x16x32_bf16 v[32:35], v[170:173], v[198:201], v[32:35]
	v_mfma_f32_16x16x32_bf16 v[28:31], v[182:185], v[198:201], v[28:31]
	v_mfma_f32_16x16x32_bf16 v[20:23], v[170:173], v[206:209], v[20:23]
	v_mfma_f32_16x16x32_bf16 v[12:15], v[182:185], v[206:209], v[12:15]
	s_setprio 2
	s_barrier
	v_mfma_f32_16x16x32_bf16 v[4:7], v[170:173], v[214:217], v[4:7]
	v_mfma_f32_16x16x32_bf16 v[0:3], v[182:185], v[214:217], v[0:3]
	s_setprio 0
	s_add_i32 s1, 0, 0x18000
	s_add_i32 s12, 0, 0x1c000
	v_add_u32_e32 v162, s1, v150
	v_add_u32_e32 v182, s12, v150
	ds_read_b128 v[146:149], v162
	ds_read_b128 v[154:157], v162 offset:1024
	ds_read_b128 v[158:161], v162 offset:2048
	ds_read_b128 v[162:165], v162 offset:3072
	ds_read_b128 v[166:169], v182
	ds_read_b128 v[170:173], v182 offset:1024
	ds_read_b128 v[178:181], v182 offset:2048
	ds_read_b128 v[182:185], v182 offset:3072
	s_add_u32 s10, s70, 0x160000
	s_addc_u32 s11, s71, 0
	s_mov_b32 m0, s46
	v_lshl_add_u64 v[224:225], s[10:11], 0, v[128:129]
	ds_read_b128 v[186:189], v153 offset:32768
	ds_read_b128 v[190:193], v153 offset:33792
	ds_read_b128 v[194:197], v153 offset:34816
	ds_read_b128 v[198:201], v153 offset:35840
	ds_read_b128 v[202:205], v153 offset:36864
	ds_read_b128 v[206:209], v153 offset:37888
	ds_read_b128 v[210:213], v153 offset:38912
	ds_read_b128 v[214:217], v153 offset:39936
	global_load_lds_dwordx4 v[224:225], off
	v_lshl_add_u64 v[224:225], s[10:11], 0, v[132:133]
	s_mov_b32 m0, s47
	s_nop 0
	global_load_lds_dwordx4 v[224:225], off
	s_waitcnt vmcnt(8)
	s_waitcnt lgkmcnt(0)
	s_barrier
	s_setprio 1
	s_waitcnt lgkmcnt(0)
	v_mfma_f32_16x16x32_bf16 v[124:127], v[146:149], v[186:189], v[124:127]
	v_mfma_f32_16x16x32_bf16 v[120:123], v[158:161], v[186:189], v[120:123]
	v_mfma_f32_16x16x32_bf16 v[116:119], v[146:149], v[194:197], v[116:119]
	v_mfma_f32_16x16x32_bf16 v[104:107], v[158:161], v[194:197], v[104:107]
	v_mfma_f32_16x16x32_bf16 v[100:103], v[146:149], v[202:205], v[100:103]
	v_mfma_f32_16x16x32_bf16 v[88:91], v[158:161], v[202:205], v[88:91]
	v_mfma_f32_16x16x32_bf16 v[84:87], v[146:149], v[210:213], v[84:87]
	v_mfma_f32_16x16x32_bf16 v[72:75], v[158:161], v[210:213], v[72:75]
	v_mfma_f32_16x16x32_bf16 v[124:127], v[154:157], v[190:193], v[124:127]
	v_mfma_f32_16x16x32_bf16 v[120:123], v[162:165], v[190:193], v[120:123]
	v_mfma_f32_16x16x32_bf16 v[116:119], v[154:157], v[198:201], v[116:119]
	v_mfma_f32_16x16x32_bf16 v[104:107], v[162:165], v[198:201], v[104:107]
	v_mfma_f32_16x16x32_bf16 v[100:103], v[154:157], v[206:209], v[100:103]
	v_mfma_f32_16x16x32_bf16 v[88:91], v[162:165], v[206:209], v[88:91]
	v_mfma_f32_16x16x32_bf16 v[84:87], v[154:157], v[214:217], v[84:87]
	v_mfma_f32_16x16x32_bf16 v[72:75], v[162:165], v[214:217], v[72:75]
	v_mfma_f32_16x16x32_bf16 v[112:115], v[166:169], v[186:189], v[112:115]
	v_mfma_f32_16x16x32_bf16 v[108:111], v[178:181], v[186:189], v[108:111]
	v_mfma_f32_16x16x32_bf16 v[96:99], v[166:169], v[194:197], v[96:99]
	v_mfma_f32_16x16x32_bf16 v[92:95], v[178:181], v[194:197], v[92:95]
	v_mfma_f32_16x16x32_bf16 v[80:83], v[166:169], v[202:205], v[80:83]
	v_mfma_f32_16x16x32_bf16 v[76:79], v[178:181], v[202:205], v[76:79]
	v_mfma_f32_16x16x32_bf16 v[68:71], v[166:169], v[210:213], v[68:71]
	v_mfma_f32_16x16x32_bf16 v[64:67], v[178:181], v[210:213], v[64:67]
	v_mfma_f32_16x16x32_bf16 v[112:115], v[170:173], v[190:193], v[112:115]
	v_mfma_f32_16x16x32_bf16 v[108:111], v[182:185], v[190:193], v[108:111]
	v_mfma_f32_16x16x32_bf16 v[96:99], v[170:173], v[198:201], v[96:99]
	v_mfma_f32_16x16x32_bf16 v[92:95], v[182:185], v[198:201], v[92:95]
	v_mfma_f32_16x16x32_bf16 v[80:83], v[170:173], v[206:209], v[80:83]
	v_mfma_f32_16x16x32_bf16 v[76:79], v[182:185], v[206:209], v[76:79]
	s_setprio 2
	s_barrier
; #define PG8_STAGE(bufoff, gbase, voff) do { _Pragma("unroll") for (int _i = 0; _i < 2; ++_i) \
;         __builtin_amdgcn_global_load_lds((const unsigned*)((const char*)(gbase) + (voff)[_i]), (LAS unsigned*)(lds + (bufoff) + ldsw + _i * 8192), 16, 0, 0); } while (0)
; #define PG8_LDA(dst, b, h) do { _Pragma("unroll") for (int m = 0; m < 4; ++m) _Pragma("unroll") for (int k = 0; k < 2; ++k) dst[m][k] = *(const LAS bf16x8*)(lds + PG8_SA(b, h) + aoff + m * 2048 + k * 1024); } while (0)
; #define PG8_MMA(ai, bj, At, Bt) do { __builtin_amdgcn_s_setprio(1); _Pragma("unroll") for (int m = 0; m < 4; ++m) _Pragma("unroll") for (int n = 0; n < 2; ++n) _Pragma("unroll") for (int k = 0; k < 2; ++k) \
;         acc[ai][bj][m][n] = __builtin_amdgcn_mfma_f32_16x16x32_bf16(Bt[n][k], At[m][k], acc[ai][bj][m][n], 0, 0, 0); __builtin_amdgcn_s_setprio(0); } while (0)
; #define PG8_WAIT_V(n) asm volatile("s_waitcnt vmcnt(" #n ")" ::: "memory")
; #define PG8_WAIT_L(n) asm volatile("s_waitcnt lgkmcnt(" #n ")" ::: "memory")
; #define PG8_BAR __builtin_amdgcn_s_barrier()
; #define PG8_SCHED __builtin_amdgcn_sched_barrier(0)
; template <class Epi, class Sched, bool ALIGN_EPI = true, bool SP2 = true>
; __device__ __forceinline__ void gemm_phase(LAS unsigned char* lds, const bf16_t* Ag, const bf16_t* Btg, const int K, const int lda, const int ldb, const Sched& S, const Epi& E) {
;     ...
;             PG8_WAIT_V(8); PG8_WAIT_L(0); PG8_BAR; PG8_MMA(0, 0, At, B0); PG8_MMA(0, 1, At, B1); PG8_BAR; PG8_SCHED;
;             PG8_LDA(At, 1, 1); PG8_STAGE(PG8_SB(1, 0), b3, voffB); PG8_STAGE(PG8_SB(1, 1), b3 + hstepB, voffB); PG8_STAGE(PG8_SA(1, 0), a3, voffA);
;             PG8_WAIT_V(8); PG8_WAIT_L(0); PG8_BAR; PG8_MMA(1, 0, At, B0); PG8_MMA(1, 1, At, B1); PG8_BAR; PG8_SCHED;
	v_mfma_f32_16x16x32_bf16 v[68:71], v[170:173], v[214:217], v[68:71]
	v_mfma_f32_16x16x32_bf16 v[64:67], v[182:185], v[214:217], v[64:67]
	s_setprio 0
	s_add_i32 s1, s1, s37
	v_lshl_add_u64 v[174:175], v[174:175], 0, s[14:15]
	s_mov_b32 m0, s1
	ds_read_b128 v[186:189], v153 offset:49152
	ds_read_b128 v[190:193], v153 offset:50176
	ds_read_b128 v[194:197], v153 offset:51200
	ds_read_b128 v[198:201], v153 offset:52224
	ds_read_b128 v[202:205], v153 offset:53248
	ds_read_b128 v[206:209], v153 offset:54272
	ds_read_b128 v[210:213], v153 offset:55296
	ds_read_b128 v[214:217], v153 offset:56320
	global_load_lds_dwordx4 v[174:175], off
	s_add_i32 m0, s1, 0x2000
	s_add_u32 s10, s66, 0x160080
	v_lshl_add_u64 v[174:175], v[218:219], 0, s[14:15]
	s_addc_u32 s11, s67, 0
	s_add_i32 s1, s12, s37
	global_load_lds_dwordx4 v[174:175], off
	v_lshl_add_u64 v[174:175], s[10:11], 0, v[130:131]
	s_mov_b32 m0, s1
	s_nop 0
	global_load_lds_dwordx4 v[174:175], off
	v_lshl_add_u64 v[174:175], s[10:11], 0, v[134:135]
	s_add_i32 m0, s1, 0x2000
	s_nop 0
	global_load_lds_dwordx4 v[174:175], off
	v_lshl_add_u64 v[174:175], v[220:221], 0, s[14:15]
	s_mov_b32 m0, s75
	s_nop 0
	global_load_lds_dwordx4 v[174:175], off
	v_lshl_add_u64 v[174:175], v[222:223], 0, s[14:15]
	s_mov_b32 m0, s76
	s_nop 0
	global_load_lds_dwordx4 v[174:175], off
	s_waitcnt vmcnt(8)
	s_waitcnt lgkmcnt(0)
	s_barrier
	s_setprio 1
	s_waitcnt lgkmcnt(0)
	v_mfma_f32_16x16x32_bf16 v[60:63], v[146:149], v[186:189], v[60:63]
	v_mfma_f32_16x16x32_bf16 v[56:59], v[158:161], v[186:189], v[56:59]
	v_mfma_f32_16x16x32_bf16 v[52:55], v[146:149], v[194:197], v[52:55]
	v_mfma_f32_16x16x32_bf16 v[40:43], v[158:161], v[194:197], v[40:43]
	v_mfma_f32_16x16x32_bf16 v[36:39], v[146:149], v[202:205], v[36:39]
	v_mfma_f32_16x16x32_bf16 v[24:27], v[158:161], v[202:205], v[24:27]
	v_mfma_f32_16x16x32_bf16 v[16:19], v[146:149], v[210:213], v[16:19]
	v_mfma_f32_16x16x32_bf16 v[8:11], v[158:161], v[210:213], v[8:11]
	v_mfma_f32_16x16x32_bf16 v[60:63], v[154:157], v[190:193], v[60:63]
	v_mfma_f32_16x16x32_bf16 v[56:59], v[162:165], v[190:193], v[56:59]
	v_mfma_f32_16x16x32_bf16 v[52:55], v[154:157], v[198:201], v[52:55]
	v_mfma_f32_16x16x32_bf16 v[40:43], v[162:165], v[198:201], v[40:43]
	v_mfma_f32_16x16x32_bf16 v[36:39], v[154:157], v[206:209], v[36:39]
	v_mfma_f32_16x16x32_bf16 v[24:27], v[162:165], v[206:209], v[24:27]
	v_mfma_f32_16x16x32_bf16 v[16:19], v[154:157], v[214:217], v[16:19]
	v_mfma_f32_16x16x32_bf16 v[8:11], v[162:165], v[214:217], v[8:11]
	v_mfma_f32_16x16x32_bf16 v[48:51], v[166:169], v[186:189], v[48:51]
	v_mfma_f32_16x16x32_bf16 v[44:47], v[178:181], v[186:189], v[44:47]
	v_mfma_f32_16x16x32_bf16 v[32:35], v[166:169], v[194:197], v[32:35]
	v_mfma_f32_16x16x32_bf16 v[28:31], v[178:181], v[194:197], v[28:31]
	v_mfma_f32_16x16x32_bf16 v[20:23], v[166:169], v[202:205], v[20:23]
	v_mfma_f32_16x16x32_bf16 v[12:15], v[178:181], v[202:205], v[12:15]
	v_mfma_f32_16x16x32_bf16 v[4:7], v[166:169], v[210:213], v[4:7]
	v_mfma_f32_16x16x32_bf16 v[0:3], v[178:181], v[210:213], v[0:3]
	v_mfma_f32_16x16x32_bf16 v[48:51], v[170:173], v[190:193], v[48:51]
	v_mfma_f32_16x16x32_bf16 v[44:47], v[182:185], v[190:193], v[44:47]
	v_mfma_f32_16x16x32_bf16 v[32:35], v[170:173], v[198:201], v[32:35]
	v_mfma_f32_16x16x32_bf16 v[28:31], v[182:185], v[198:201], v[28:31]
	v_mfma_f32_16x16x32_bf16 v[20:23], v[170:173], v[206:209], v[20:23]
	v_mfma_f32_16x16x32_bf16 v[12:15], v[182:185], v[206:209], v[12:15]
	s_setprio 2
	s_barrier
	v_mfma_f32_16x16x32_bf16 v[4:7], v[170:173], v[214:217], v[4:7]
	v_mfma_f32_16x16x32_bf16 v[0:3], v[182:185], v[214:217], v[0:3]
	s_setprio 0
	s_add_i32 s0, s0, 2
	s_add_u32 s84, s84, 0x100
	s_addc_u32 s85, s85, 0
	s_add_u32 s72, s72, 0x100
	s_addc_u32 s73, s73, 0
	s_cmpk_gt_u32 s0, 0x55
	s_cbranch_scc0 .LBB0_199
	s_and_b64 vcc, exec, s[48:49]
	s_cbranch_vccz .LBB0_202
	s_barrier

; #define PG8_STAGE(bufoff, gbase, voff) do { _Pragma("unroll") for (int _i = 0; _i < 2; ++_i) \
;         __builtin_amdgcn_global_load_lds((const unsigned*)((const char*)(gbase) + (voff)[_i]), (LAS unsigned*)(lds + (bufoff) + ldsw + _i * 8192), 16, 0, 0); } while (0)
; #define PG8_LDA(dst, b, h) do { _Pragma("unroll") for (int m = 0; m < 4; ++m) _Pragma("unroll") for (int k = 0; k < 2; ++k) dst[m][k] = *(const LAS bf16x8*)(lds + PG8_SA(b, h) + aoff + m * 2048 + k * 1024); } while (0)
; #define PG8_LDB(dst, b, h) do { _Pragma("unroll") for (int n = 0; n < 2; ++n) _Pragma("unroll") for (int k = 0; k < 2; ++k) dst[n][k] = *(const LAS bf16x8*)(lds + PG8_SB(b, h) + boff + n * 2048 + k * 1024); } while (0)
; #define PG8_MMA(ai, bj, At, Bt) do { __builtin_amdgcn_s_setprio(1); _Pragma("unroll") for (int m = 0; m < 4; ++m) _Pragma("unroll") for (int n = 0; n < 2; ++n) _Pragma("unroll") for (int k = 0; k < 2; ++k) \
;         acc[ai][bj][m][n] = __builtin_amdgcn_mfma_f32_16x16x32_bf16(Bt[n][k], At[m][k], acc[ai][bj][m][n], 0, 0, 0); __builtin_amdgcn_s_setprio(0); } while (0)
; #define PG8_WAIT_V(n) asm volatile("s_waitcnt vmcnt(" #n ")" ::: "memory")
; #define PG8_WAIT_L(n) asm volatile("s_waitcnt lgkmcnt(" #n ")" ::: "memory")
; #define PG8_BAR __builtin_amdgcn_s_barrier()
; template <class Epi, class Sched, bool ALIGN_EPI = true, bool SP2 = true>
; __device__ __forceinline__ void gemm_phase(LAS unsigned char* lds, const bf16_t* Ag, const bf16_t* Btg, const int K, const int lda, const int ldb, const Sched& S, const Epi& E) {
;     ...
;             const char* a1 = cA + (size_t)(t + 1) * kstep;
;             const char* a2 = last ? nA : cA + (size_t)(t + 2) * kstep; const char* b2 = last ? nB : cB + (size_t)(t + 2) * kstep;
;             const char* a3 = a2 + kstep; const char* b3 = b2 + kstep;
;             if constexpr (SP2) {
;             PG8_LDB(B0, 0, 0); PG8_LDB(B1, 0, 1); PG8_SCHED; PG8_LDA(At, 0, 0); PG8_STAGE(PG8_SA(1, 1), a1 + hstepA, voffA);
;             PG8_WAIT_V(8); PG8_WAIT_L(0); PG8_BAR; PG8_MMA(0, 0, At, B0); PG8_MMA(0, 1, At, B1); PG8_BAR; PG8_SCHED;
;             PG8_LDA(At, 0, 1); PG8_STAGE(PG8_SB(0, 0), b2, voffB); PG8_STAGE(PG8_SB(0, 1), b2 + hstepB, voffB); PG8_STAGE(PG8_SA(0, 0), a2, voffA);
;             PG8_WAIT_V(8); PG8_WAIT_L(0); PG8_BAR; PG8_MMA(1, 0, At, B0); PG8_MMA(1, 1, At, B1); PG8_BAR; PG8_SCHED;
.LBB0_278:
	ds_read_b128 v[152:155], v137
	ds_read_b128 v[156:159], v137 offset:1024
	ds_read_b128 v[160:163], v137 offset:2048
	ds_read_b128 v[164:167], v137 offset:3072
	ds_read_b128 v[168:171], v150
	ds_read_b128 v[172:175], v150 offset:1024
	ds_read_b128 v[180:183], v150 offset:2048
	ds_read_b128 v[184:187], v150 offset:3072
	s_add_u32 s34, s30, 0xfff80080
	s_addc_u32 s35, s31, -1
	s_cmp_eq_u32 s59, 28
	s_cselect_b32 s39, s55, s35
	s_cselect_b32 s38, s56, s34
	s_cselect_b32 s35, s6, s58
	s_cselect_b32 s34, s7, s57
	v_lshl_add_u64 v[220:221], s[30:31], 0, v[140:141]
	s_add_i32 m0, s33, 0xc000
	ds_read_b128 v[188:191], v151
	ds_read_b128 v[192:195], v151 offset:1024
	ds_read_b128 v[196:199], v151 offset:2048
	ds_read_b128 v[200:203], v151 offset:3072
	ds_read_b128 v[204:207], v151 offset:4096
	ds_read_b128 v[208:211], v151 offset:5120
	ds_read_b128 v[212:215], v151 offset:6144
	ds_read_b128 v[216:219], v151 offset:7168
	global_load_lds_dwordx4 v[220:221], off
	v_lshl_add_u64 v[220:221], s[30:31], 0, v[142:143]
	s_add_i32 m0, s33, 0xe000
	s_nop 0
	global_load_lds_dwordx4 v[220:221], off
	s_waitcnt vmcnt(8)
	s_waitcnt lgkmcnt(0)
	s_barrier
	s_setprio 1
	s_waitcnt lgkmcnt(0)
	v_mfma_f32_16x16x32_bf16 v[124:127], v[152:155], v[188:191], v[124:127]
	v_mfma_f32_16x16x32_bf16 v[120:123], v[160:163], v[188:191], v[120:123]
	v_mfma_f32_16x16x32_bf16 v[116:119], v[152:155], v[196:199], v[116:119]
	v_mfma_f32_16x16x32_bf16 v[112:115], v[160:163], v[196:199], v[112:115]
	v_mfma_f32_16x16x32_bf16 v[100:103], v[152:155], v[204:207], v[100:103]
	v_mfma_f32_16x16x32_bf16 v[96:99], v[160:163], v[204:207], v[96:99]
	v_mfma_f32_16x16x32_bf16 v[84:87], v[152:155], v[212:215], v[84:87]
	v_mfma_f32_16x16x32_bf16 v[80:83], v[160:163], v[212:215], v[80:83]
	v_mfma_f32_16x16x32_bf16 v[124:127], v[156:159], v[192:195], v[124:127]
	v_mfma_f32_16x16x32_bf16 v[120:123], v[164:167], v[192:195], v[120:123]
	v_mfma_f32_16x16x32_bf16 v[116:119], v[156:159], v[200:203], v[116:119]
	v_mfma_f32_16x16x32_bf16 v[112:115], v[164:167], v[200:203], v[112:115]
	v_mfma_f32_16x16x32_bf16 v[100:103], v[156:159], v[208:211], v[100:103]
	v_mfma_f32_16x16x32_bf16 v[96:99], v[164:167], v[208:211], v[96:99]
	v_mfma_f32_16x16x32_bf16 v[84:87], v[156:159], v[216:219], v[84:87]
	v_mfma_f32_16x16x32_bf16 v[80:83], v[164:167], v[216:219], v[80:83]
	v_mfma_f32_16x16x32_bf16 v[108:111], v[168:171], v[188:191], v[108:111]
	v_mfma_f32_16x16x32_bf16 v[104:107], v[180:183], v[188:191], v[104:107]
	v_mfma_f32_16x16x32_bf16 v[92:95], v[168:171], v[196:199], v[92:95]
	v_mfma_f32_16x16x32_bf16 v[88:91], v[180:183], v[196:199], v[88:91]
	v_mfma_f32_16x16x32_bf16 v[76:79], v[168:171], v[204:207], v[76:79]
	v_mfma_f32_16x16x32_bf16 v[72:75], v[180:183], v[204:207], v[72:75]
	v_mfma_f32_16x16x32_bf16 v[68:71], v[168:171], v[212:215], v[68:71]
	v_mfma_f32_16x16x32_bf16 v[64:67], v[180:183], v[212:215], v[64:67]
	v_mfma_f32_16x16x32_bf16 v[108:111], v[172:175], v[192:195], v[108:111]
	v_mfma_f32_16x16x32_bf16 v[104:107], v[184:187], v[192:195], v[104:107]
	v_mfma_f32_16x16x32_bf16 v[92:95], v[172:175], v[200:203], v[92:95]
	v_mfma_f32_16x16x32_bf16 v[88:91], v[184:187], v[200:203], v[88:91]
	v_mfma_f32_16x16x32_bf16 v[76:79], v[172:175], v[208:211], v[76:79]
	v_mfma_f32_16x16x32_bf16 v[72:75], v[184:187], v[208:211], v[72:75]
	s_setprio 2
	s_barrier
	v_mfma_f32_16x16x32_bf16 v[68:71], v[172:175], v[216:219], v[68:71]
	v_mfma_f32_16x16x32_bf16 v[64:67], v[184:187], v[216:219], v[64:67]
	s_setprio 0
	s_add_i32 s60, s0, s9
	v_lshl_add_u64 v[220:221], s[34:35], 0, v[130:131]
	s_mov_b32 m0, s60
	ds_read_b128 v[188:191], v151 offset:16384
	ds_read_b128 v[192:195], v151 offset:17408
	ds_read_b128 v[196:199], v151 offset:18432
	ds_read_b128 v[200:203], v151 offset:19456
	ds_read_b128 v[204:207], v151 offset:20480
	ds_read_b128 v[208:211], v151 offset:21504
	ds_read_b128 v[212:215], v151 offset:22528
	ds_read_b128 v[216:219], v151 offset:23552
	global_load_lds_dwordx4 v[220:221], off
	s_add_i32 m0, s60, 0x2000
	s_add_u32 s60, s34, 0x80000
	v_lshl_add_u64 v[222:223], s[34:35], 0, v[134:135]
	s_addc_u32 s61, s35, 0
	s_add_i32 s62, s54, s9
	global_load_lds_dwordx4 v[222:223], off
	v_lshl_add_u64 v[224:225], s[60:61], 0, v[130:131]
	s_mov_b32 m0, s62
	v_lshl_add_u64 v[226:227], s[38:39], 0, v[132:133]
	global_load_lds_dwordx4 v[224:225], off
	v_lshl_add_u64 v[224:225], s[60:61], 0, v[134:135]
	s_add_i32 m0, s62, 0x2000
	s_nop 0
	global_load_lds_dwordx4 v[224:225], off
	v_lshl_add_u64 v[224:225], s[38:39], 0, v[128:129]
	s_mov_b32 m0, s33
	s_nop 0
	global_load_lds_dwordx4 v[224:225], off
	s_mov_b32 m0, s41
	s_nop 0
	global_load_lds_dwordx4 v[226:227], off
	s_waitcnt vmcnt(8)
	s_waitcnt lgkmcnt(0)
	s_barrier
; #define PG8_STAGE(bufoff, gbase, voff) do { _Pragma("unroll") for (int _i = 0; _i < 2; ++_i) \
;         __builtin_amdgcn_global_load_lds((const unsigned*)((const char*)(gbase) + (voff)[_i]), (LAS unsigned*)(lds + (bufoff) + ldsw + _i * 8192), 16, 0, 0); } while (0)
; #define PG8_LDA(dst, b, h) do { _Pragma("unroll") for (int m = 0; m < 4; ++m) _Pragma("unroll") for (int k = 0; k < 2; ++k) dst[m][k] = *(const LAS bf16x8*)(lds + PG8_SA(b, h) + aoff + m * 2048 + k * 1024); } while (0)
; #define PG8_LDB(dst, b, h) do { _Pragma("unroll") for (int n = 0; n < 2; ++n) _Pragma("unroll") for (int k = 0; k < 2; ++k) dst[n][k] = *(const LAS bf16x8*)(lds + PG8_SB(b, h) + boff + n * 2048 + k * 1024); } while (0)
; #define PG8_MMA(ai, bj, At, Bt) do { __builtin_amdgcn_s_setprio(1); _Pragma("unroll") for (int m = 0; m < 4; ++m) _Pragma("unroll") for (int n = 0; n < 2; ++n) _Pragma("unroll") for (int k = 0; k < 2; ++k) \
;         acc[ai][bj][m][n] = __builtin_amdgcn_mfma_f32_16x16x32_bf16(Bt[n][k], At[m][k], acc[ai][bj][m][n], 0, 0, 0); __builtin_amdgcn_s_setprio(0); } while (0)
; #define PG8_WAIT_V(n) asm volatile("s_waitcnt vmcnt(" #n ")" ::: "memory")
; #define PG8_WAIT_L(n) asm volatile("s_waitcnt lgkmcnt(" #n ")" ::: "memory")
; #define PG8_BAR __builtin_amdgcn_s_barrier()
; #define PG8_SCHED __builtin_amdgcn_sched_barrier(0)
; template <class Epi, class Sched, bool ALIGN_EPI = true, bool SP2 = true>
; __device__ __forceinline__ void gemm_phase(LAS unsigned char* lds, const bf16_t* Ag, const bf16_t* Btg, const int K, const int lda, const int ldb, const Sched& S, const Epi& E) {
;     ...
;             PG8_WAIT_V(8); PG8_WAIT_L(0); PG8_BAR; PG8_MMA(1, 0, At, B0); PG8_MMA(1, 1, At, B1); PG8_BAR; PG8_SCHED;
;             PG8_LDB(B0, 1, 0); PG8_LDB(B1, 1, 1); PG8_SCHED; PG8_LDA(At, 1, 0); PG8_STAGE(PG8_SA(0, 1), a2 + hstepA, voffA);
;             PG8_WAIT_V(8); PG8_WAIT_L(0); PG8_BAR; PG8_MMA(0, 0, At, B0); PG8_MMA(0, 1, At, B1); PG8_BAR; PG8_SCHED;
	s_setprio 1
	s_waitcnt lgkmcnt(0)
	v_mfma_f32_16x16x32_bf16 v[60:63], v[152:155], v[188:191], v[60:63]
	v_mfma_f32_16x16x32_bf16 v[56:59], v[160:163], v[188:191], v[56:59]
	v_mfma_f32_16x16x32_bf16 v[52:55], v[152:155], v[196:199], v[52:55]
	v_mfma_f32_16x16x32_bf16 v[48:51], v[160:163], v[196:199], v[48:51]
	v_mfma_f32_16x16x32_bf16 v[36:39], v[152:155], v[204:207], v[36:39]
	v_mfma_f32_16x16x32_bf16 v[32:35], v[160:163], v[204:207], v[32:35]
	v_mfma_f32_16x16x32_bf16 v[20:23], v[152:155], v[212:215], v[20:23]
	v_mfma_f32_16x16x32_bf16 v[16:19], v[160:163], v[212:215], v[16:19]
	v_mfma_f32_16x16x32_bf16 v[60:63], v[156:159], v[192:195], v[60:63]
	v_mfma_f32_16x16x32_bf16 v[56:59], v[164:167], v[192:195], v[56:59]
	v_mfma_f32_16x16x32_bf16 v[52:55], v[156:159], v[200:203], v[52:55]
	v_mfma_f32_16x16x32_bf16 v[48:51], v[164:167], v[200:203], v[48:51]
	v_mfma_f32_16x16x32_bf16 v[36:39], v[156:159], v[208:211], v[36:39]
	v_mfma_f32_16x16x32_bf16 v[32:35], v[164:167], v[208:211], v[32:35]
	v_mfma_f32_16x16x32_bf16 v[20:23], v[156:159], v[216:219], v[20:23]
	v_mfma_f32_16x16x32_bf16 v[16:19], v[164:167], v[216:219], v[16:19]
	v_mfma_f32_16x16x32_bf16 v[44:47], v[168:171], v[188:191], v[44:47]
	v_mfma_f32_16x16x32_bf16 v[40:43], v[180:183], v[188:191], v[40:43]
	v_mfma_f32_16x16x32_bf16 v[28:31], v[168:171], v[196:199], v[28:31]
	v_mfma_f32_16x16x32_bf16 v[24:27], v[180:183], v[196:199], v[24:27]
	v_mfma_f32_16x16x32_bf16 v[12:15], v[168:171], v[204:207], v[12:15]
	v_mfma_f32_16x16x32_bf16 v[8:11], v[180:183], v[204:207], v[8:11]
	v_mfma_f32_16x16x32_bf16 v[4:7], v[168:171], v[212:215], v[4:7]
	v_mfma_f32_16x16x32_bf16 v[0:3], v[180:183], v[212:215], v[0:3]
	v_mfma_f32_16x16x32_bf16 v[44:47], v[172:175], v[192:195], v[44:47]
	v_mfma_f32_16x16x32_bf16 v[40:43], v[184:187], v[192:195], v[40:43]
	v_mfma_f32_16x16x32_bf16 v[28:31], v[172:175], v[200:203], v[28:31]
	v_mfma_f32_16x16x32_bf16 v[24:27], v[184:187], v[200:203], v[24:27]
	v_mfma_f32_16x16x32_bf16 v[12:15], v[172:175], v[208:211], v[12:15]
	v_mfma_f32_16x16x32_bf16 v[8:11], v[184:187], v[208:211], v[8:11]
	s_setprio 2
	s_barrier
	v_mfma_f32_16x16x32_bf16 v[4:7], v[172:175], v[216:219], v[4:7]
	v_mfma_f32_16x16x32_bf16 v[0:3], v[184:187], v[216:219], v[0:3]
	s_setprio 0
	s_add_i32 s60, 0, 0x18000
	s_add_i32 s61, 0, 0x1c000
	v_add_u32_e32 v164, s60, v149
	v_add_u32_e32 v184, s61, v149
	ds_read_b128 v[152:155], v164
	ds_read_b128 v[156:159], v164 offset:1024
	ds_read_b128 v[160:163], v164 offset:2048
	ds_read_b128 v[164:167], v164 offset:3072
	ds_read_b128 v[168:171], v184
	ds_read_b128 v[172:175], v184 offset:1024
	ds_read_b128 v[180:183], v184 offset:2048
	ds_read_b128 v[184:187], v184 offset:3072
	s_add_u32 s38, s38, 0x80000
	s_addc_u32 s39, s39, 0
	s_mov_b32 m0, s46
	v_lshl_add_u64 v[228:229], s[38:39], 0, v[128:129]
	ds_read_b128 v[188:191], v151 offset:32768
	ds_read_b128 v[192:195], v151 offset:33792
	ds_read_b128 v[196:199], v151 offset:34816
	ds_read_b128 v[200:203], v151 offset:35840
	ds_read_b128 v[204:207], v151 offset:36864
	ds_read_b128 v[208:211], v151 offset:37888
	ds_read_b128 v[212:215], v151 offset:38912
	ds_read_b128 v[216:219], v151 offset:39936
	global_load_lds_dwordx4 v[228:229], off
	v_lshl_add_u64 v[228:229], s[38:39], 0, v[132:133]
	s_mov_b32 m0, s47
	s_nop 0
	global_load_lds_dwordx4 v[228:229], off
	s_waitcnt vmcnt(8)
	s_waitcnt lgkmcnt(0)
	s_barrier
	s_setprio 1
	s_waitcnt lgkmcnt(0)
	v_mfma_f32_16x16x32_bf16 v[124:127], v[152:155], v[188:191], v[124:127]
	v_mfma_f32_16x16x32_bf16 v[120:123], v[160:163], v[188:191], v[120:123]
	v_mfma_f32_16x16x32_bf16 v[116:119], v[152:155], v[196:199], v[116:119]
	v_mfma_f32_16x16x32_bf16 v[112:115], v[160:163], v[196:199], v[112:115]
	v_mfma_f32_16x16x32_bf16 v[100:103], v[152:155], v[204:207], v[100:103]
	v_mfma_f32_16x16x32_bf16 v[96:99], v[160:163], v[204:207], v[96:99]
	v_mfma_f32_16x16x32_bf16 v[84:87], v[152:155], v[212:215], v[84:87]
	v_mfma_f32_16x16x32_bf16 v[80:83], v[160:163], v[212:215], v[80:83]
	v_mfma_f32_16x16x32_bf16 v[124:127], v[156:159], v[192:195], v[124:127]
	v_mfma_f32_16x16x32_bf16 v[120:123], v[164:167], v[192:195], v[120:123]
	v_mfma_f32_16x16x32_bf16 v[116:119], v[156:159], v[200:203], v[116:119]
	v_mfma_f32_16x16x32_bf16 v[112:115], v[164:167], v[200:203], v[112:115]
	v_mfma_f32_16x16x32_bf16 v[100:103], v[156:159], v[208:211], v[100:103]
	v_mfma_f32_16x16x32_bf16 v[96:99], v[164:167], v[208:211], v[96:99]
	v_mfma_f32_16x16x32_bf16 v[84:87], v[156:159], v[216:219], v[84:87]
	v_mfma_f32_16x16x32_bf16 v[80:83], v[164:167], v[216:219], v[80:83]
	v_mfma_f32_16x16x32_bf16 v[108:111], v[168:171], v[188:191], v[108:111]
	v_mfma_f32_16x16x32_bf16 v[104:107], v[180:183], v[188:191], v[104:107]
	v_mfma_f32_16x16x32_bf16 v[92:95], v[168:171], v[196:199], v[92:95]
	v_mfma_f32_16x16x32_bf16 v[88:91], v[180:183], v[196:199], v[88:91]
	v_mfma_f32_16x16x32_bf16 v[76:79], v[168:171], v[204:207], v[76:79]
	v_mfma_f32_16x16x32_bf16 v[72:75], v[180:183], v[204:207], v[72:75]
	v_mfma_f32_16x16x32_bf16 v[68:71], v[168:171], v[212:215], v[68:71]
	v_mfma_f32_16x16x32_bf16 v[64:67], v[180:183], v[212:215], v[64:67]
	v_mfma_f32_16x16x32_bf16 v[108:111], v[172:175], v[192:195], v[108:111]
	v_mfma_f32_16x16x32_bf16 v[104:107], v[184:187], v[192:195], v[104:107]
	v_mfma_f32_16x16x32_bf16 v[92:95], v[172:175], v[200:203], v[92:95]
	v_mfma_f32_16x16x32_bf16 v[88:91], v[184:187], v[200:203], v[88:91]
	v_mfma_f32_16x16x32_bf16 v[76:79], v[172:175], v[208:211], v[76:79]
	v_mfma_f32_16x16x32_bf16 v[72:75], v[184:187], v[208:211], v[72:75]
	s_setprio 2
	s_barrier
; #define PG8_STAGE(bufoff, gbase, voff) do { _Pragma("unroll") for (int _i = 0; _i < 2; ++_i) \
;         __builtin_amdgcn_global_load_lds((const unsigned*)((const char*)(gbase) + (voff)[_i]), (LAS unsigned*)(lds + (bufoff) + ldsw + _i * 8192), 16, 0, 0); } while (0)
; #define PG8_LDA(dst, b, h) do { _Pragma("unroll") for (int m = 0; m < 4; ++m) _Pragma("unroll") for (int k = 0; k < 2; ++k) dst[m][k] = *(const LAS bf16x8*)(lds + PG8_SA(b, h) + aoff + m * 2048 + k * 1024); } while (0)
; #define PG8_MMA(ai, bj, At, Bt) do { __builtin_amdgcn_s_setprio(1); _Pragma("unroll") for (int m = 0; m < 4; ++m) _Pragma("unroll") for (int n = 0; n < 2; ++n) _Pragma("unroll") for (int k = 0; k < 2; ++k) \
;         acc[ai][bj][m][n] = __builtin_amdgcn_mfma_f32_16x16x32_bf16(Bt[n][k], At[m][k], acc[ai][bj][m][n], 0, 0, 0); __builtin_amdgcn_s_setprio(0); } while (0)
; #define PG8_WAIT_V(n) asm volatile("s_waitcnt vmcnt(" #n ")" ::: "memory")
; #define PG8_WAIT_L(n) asm volatile("s_waitcnt lgkmcnt(" #n ")" ::: "memory")
; #define PG8_BAR __builtin_amdgcn_s_barrier()
; #define PG8_SCHED __builtin_amdgcn_sched_barrier(0)
; template <class Epi, class Sched, bool ALIGN_EPI = true, bool SP2 = true>
; __device__ __forceinline__ void gemm_phase(LAS unsigned char* lds, const bf16_t* Ag, const bf16_t* Btg, const int K, const int lda, const int ldb, const Sched& S, const Epi& E) {
;     ...
;             PG8_WAIT_V(8); PG8_WAIT_L(0); PG8_BAR; PG8_MMA(0, 0, At, B0); PG8_MMA(0, 1, At, B1); PG8_BAR; PG8_SCHED;
;             PG8_LDA(At, 1, 1); PG8_STAGE(PG8_SB(1, 0), b3, voffB); PG8_STAGE(PG8_SB(1, 1), b3 + hstepB, voffB); PG8_STAGE(PG8_SA(1, 0), a3, voffA);
;             PG8_WAIT_V(8); PG8_WAIT_L(0); PG8_BAR; PG8_MMA(1, 0, At, B0); PG8_MMA(1, 1, At, B1); PG8_BAR; PG8_SCHED;
	v_mfma_f32_16x16x32_bf16 v[68:71], v[172:175], v[216:219], v[68:71]
	v_mfma_f32_16x16x32_bf16 v[64:67], v[184:187], v[216:219], v[64:67]
	s_setprio 0
	s_add_i32 s38, s60, s9
	v_lshl_add_u64 v[220:221], v[220:221], 0, s[12:13]
	s_mov_b32 m0, s38
	ds_read_b128 v[188:191], v151 offset:49152
	ds_read_b128 v[192:195], v151 offset:50176
	ds_read_b128 v[196:199], v151 offset:51200
	ds_read_b128 v[200:203], v151 offset:52224
	ds_read_b128 v[204:207], v151 offset:53248
	ds_read_b128 v[208:211], v151 offset:54272
	ds_read_b128 v[212:215], v151 offset:55296
	ds_read_b128 v[216:219], v151 offset:56320
	global_load_lds_dwordx4 v[220:221], off
	s_add_i32 m0, s38, 0x2000
	s_add_u32 s34, s34, 0x80080
	v_lshl_add_u64 v[220:221], v[222:223], 0, s[12:13]
	s_addc_u32 s35, s35, 0
	s_add_i32 s38, s61, s9
	global_load_lds_dwordx4 v[220:221], off
	v_lshl_add_u64 v[220:221], s[34:35], 0, v[130:131]
	s_mov_b32 m0, s38
	s_nop 0
	global_load_lds_dwordx4 v[220:221], off
	v_lshl_add_u64 v[220:221], s[34:35], 0, v[134:135]
	s_add_i32 m0, s38, 0x2000
	s_nop 0
	global_load_lds_dwordx4 v[220:221], off
	v_lshl_add_u64 v[220:221], v[224:225], 0, s[12:13]
	s_mov_b32 m0, s50
	s_nop 0
	global_load_lds_dwordx4 v[220:221], off
	v_lshl_add_u64 v[220:221], v[226:227], 0, s[12:13]
	s_mov_b32 m0, s51
	s_nop 0
	global_load_lds_dwordx4 v[220:221], off
	s_waitcnt vmcnt(8)
	s_waitcnt lgkmcnt(0)
	s_barrier
	s_setprio 1
	s_waitcnt lgkmcnt(0)
	v_mfma_f32_16x16x32_bf16 v[60:63], v[152:155], v[188:191], v[60:63]
	v_mfma_f32_16x16x32_bf16 v[56:59], v[160:163], v[188:191], v[56:59]
	v_mfma_f32_16x16x32_bf16 v[52:55], v[152:155], v[196:199], v[52:55]
	v_mfma_f32_16x16x32_bf16 v[48:51], v[160:163], v[196:199], v[48:51]
	v_mfma_f32_16x16x32_bf16 v[36:39], v[152:155], v[204:207], v[36:39]
	v_mfma_f32_16x16x32_bf16 v[32:35], v[160:163], v[204:207], v[32:35]
	v_mfma_f32_16x16x32_bf16 v[20:23], v[152:155], v[212:215], v[20:23]
	v_mfma_f32_16x16x32_bf16 v[16:19], v[160:163], v[212:215], v[16:19]
	v_mfma_f32_16x16x32_bf16 v[60:63], v[156:159], v[192:195], v[60:63]
	v_mfma_f32_16x16x32_bf16 v[56:59], v[164:167], v[192:195], v[56:59]
	v_mfma_f32_16x16x32_bf16 v[52:55], v[156:159], v[200:203], v[52:55]
	v_mfma_f32_16x16x32_bf16 v[48:51], v[164:167], v[200:203], v[48:51]
	v_mfma_f32_16x16x32_bf16 v[36:39], v[156:159], v[208:211], v[36:39]
	v_mfma_f32_16x16x32_bf16 v[32:35], v[164:167], v[208:211], v[32:35]
	v_mfma_f32_16x16x32_bf16 v[20:23], v[156:159], v[216:219], v[20:23]
	v_mfma_f32_16x16x32_bf16 v[16:19], v[164:167], v[216:219], v[16:19]
	v_mfma_f32_16x16x32_bf16 v[44:47], v[168:171], v[188:191], v[44:47]
	v_mfma_f32_16x16x32_bf16 v[40:43], v[180:183], v[188:191], v[40:43]
	v_mfma_f32_16x16x32_bf16 v[28:31], v[168:171], v[196:199], v[28:31]
	v_mfma_f32_16x16x32_bf16 v[24:27], v[180:183], v[196:199], v[24:27]
	v_mfma_f32_16x16x32_bf16 v[12:15], v[168:171], v[204:207], v[12:15]
	v_mfma_f32_16x16x32_bf16 v[8:11], v[180:183], v[204:207], v[8:11]
	v_mfma_f32_16x16x32_bf16 v[4:7], v[168:171], v[212:215], v[4:7]
	v_mfma_f32_16x16x32_bf16 v[0:3], v[180:183], v[212:215], v[0:3]
	v_mfma_f32_16x16x32_bf16 v[44:47], v[172:175], v[192:195], v[44:47]
	v_mfma_f32_16x16x32_bf16 v[40:43], v[184:187], v[192:195], v[40:43]
	v_mfma_f32_16x16x32_bf16 v[28:31], v[172:175], v[200:203], v[28:31]
	v_mfma_f32_16x16x32_bf16 v[24:27], v[184:187], v[200:203], v[24:27]
	v_mfma_f32_16x16x32_bf16 v[12:15], v[172:175], v[208:211], v[12:15]
	v_mfma_f32_16x16x32_bf16 v[8:11], v[184:187], v[208:211], v[8:11]
	s_setprio 2
	s_barrier
	v_mfma_f32_16x16x32_bf16 v[4:7], v[172:175], v[216:219], v[4:7]
	v_mfma_f32_16x16x32_bf16 v[0:3], v[184:187], v[216:219], v[0:3]
	s_setprio 0
	s_add_i32 s59, s59, 2
	s_add_u32 s30, s30, 0x100
	s_addc_u32 s31, s31, 0
	s_add_u32 s57, s57, 0x100
	s_addc_u32 s58, s58, 0
	s_cmp_gt_u32 s59, 29
	s_cbranch_scc0 .LBB0_278
	s_and_b64 vcc, exec, s[14:15]
	s_cbranch_vccz .LBB0_281
	s_barrier

; #define PG8_STAGE(bufoff, gbase, voff) do { _Pragma("unroll") for (int _i = 0; _i < 2; ++_i) \
;         __builtin_amdgcn_global_load_lds((const unsigned*)((const char*)(gbase) + (voff)[_i]), (LAS unsigned*)(lds + (bufoff) + ldsw + _i * 8192), 16, 0, 0); } while (0)
; #define PG8_LDA(dst, b, h) do { _Pragma("unroll") for (int m = 0; m < 4; ++m) _Pragma("unroll") for (int k = 0; k < 2; ++k) dst[m][k] = *(const LAS bf16x8*)(lds + PG8_SA(b, h) + aoff + m * 2048 + k * 1024); } while (0)
; #define PG8_LDB(dst, b, h) do { _Pragma("unroll") for (int n = 0; n < 2; ++n) _Pragma("unroll") for (int k = 0; k < 2; ++k) dst[n][k] = *(const LAS bf16x8*)(lds + PG8_SB(b, h) + boff + n * 2048 + k * 1024); } while (0)
; #define PG8_MMA(ai, bj, At, Bt) do { __builtin_amdgcn_s_setprio(1); _Pragma("unroll") for (int m = 0; m < 4; ++m) _Pragma("unroll") for (int n = 0; n < 2; ++n) _Pragma("unroll") for (int k = 0; k < 2; ++k) \
;         acc[ai][bj][m][n] = __builtin_amdgcn_mfma_f32_16x16x32_bf16(Bt[n][k], At[m][k], acc[ai][bj][m][n], 0, 0, 0); __builtin_amdgcn_s_setprio(0); } while (0)
; #define PG8_WAIT_V(n) asm volatile("s_waitcnt vmcnt(" #n ")" ::: "memory")
; #define PG8_WAIT_L(n) asm volatile("s_waitcnt lgkmcnt(" #n ")" ::: "memory")
; #define PG8_BAR __builtin_amdgcn_s_barrier()
; template <class Epi, class Sched, bool ALIGN_EPI = true, bool SP2 = true>
; __device__ __forceinline__ void gemm_phase(LAS unsigned char* lds, const bf16_t* Ag, const bf16_t* Btg, const int K, const int lda, const int ldb, const Sched& S, const Epi& E) {
;     ...
;             const char* a1 = cA + (size_t)(t + 1) * kstep;
;             const char* a2 = last ? nA : cA + (size_t)(t + 2) * kstep; const char* b2 = last ? nB : cB + (size_t)(t + 2) * kstep;
;             const char* a3 = a2 + kstep; const char* b3 = b2 + kstep;
;             if constexpr (SP2) {
;             PG8_LDB(B0, 0, 0); PG8_LDB(B1, 0, 1); PG8_SCHED; PG8_LDA(At, 0, 0); PG8_STAGE(PG8_SA(1, 1), a1 + hstepA, voffA);
;             PG8_WAIT_V(8); PG8_WAIT_L(0); PG8_BAR; PG8_MMA(0, 0, At, B0); PG8_MMA(0, 1, At, B1); PG8_BAR; PG8_SCHED;
;             PG8_LDA(At, 0, 1); PG8_STAGE(PG8_SB(0, 0), b2, voffB); PG8_STAGE(PG8_SB(0, 1), b2 + hstepB, voffB); PG8_STAGE(PG8_SA(0, 0), a2, voffA);
;             PG8_WAIT_V(8); PG8_WAIT_L(0); PG8_BAR; PG8_MMA(1, 0, At, B0); PG8_MMA(1, 1, At, B1); PG8_BAR; PG8_SCHED;
.LBB0_302:
	ds_read_b128 v[146:149], v143
	ds_read_b128 v[150:153], v143 offset:1024
	ds_read_b128 v[154:157], v143 offset:2048
	ds_read_b128 v[158:161], v143 offset:3072
	ds_read_b128 v[162:165], v144
	ds_read_b128 v[166:169], v144 offset:1024
	ds_read_b128 v[170:173], v144 offset:2048
	ds_read_b128 v[180:183], v144 offset:3072
	s_add_u32 s30, s28, 0xfff80080
	s_addc_u32 s31, s29, -1
	s_cmp_eq_u32 s62, 28
	s_cselect_b32 s35, s56, s31
	s_cselect_b32 s34, s57, s30
	s_cselect_b32 s31, s58, s61
	s_cselect_b32 s30, s59, s60
	v_lshl_add_u64 v[174:175], s[28:29], 0, v[138:139]
	s_add_i32 m0, s41, 0xc000
	ds_read_b128 v[184:187], v145
	ds_read_b128 v[188:191], v145 offset:1024
	ds_read_b128 v[192:195], v145 offset:2048
	ds_read_b128 v[196:199], v145 offset:3072
	ds_read_b128 v[200:203], v145 offset:4096
	ds_read_b128 v[204:207], v145 offset:5120
	ds_read_b128 v[208:211], v145 offset:6144
	ds_read_b128 v[212:215], v145 offset:7168
	global_load_lds_dwordx4 v[174:175], off
	v_lshl_add_u64 v[174:175], s[28:29], 0, v[140:141]
	s_add_i32 m0, s41, 0xe000
	s_nop 0
	global_load_lds_dwordx4 v[174:175], off
	s_waitcnt vmcnt(8)
	s_waitcnt lgkmcnt(0)
	s_barrier
	s_setprio 1
	s_waitcnt lgkmcnt(0)
	v_mfma_f32_16x16x32_bf16 v[124:127], v[146:149], v[184:187], v[124:127]
	v_mfma_f32_16x16x32_bf16 v[120:123], v[154:157], v[184:187], v[120:123]
	v_mfma_f32_16x16x32_bf16 v[116:119], v[146:149], v[192:195], v[116:119]
	v_mfma_f32_16x16x32_bf16 v[112:115], v[154:157], v[192:195], v[112:115]
	v_mfma_f32_16x16x32_bf16 v[100:103], v[146:149], v[200:203], v[100:103]
	v_mfma_f32_16x16x32_bf16 v[96:99], v[154:157], v[200:203], v[96:99]
	v_mfma_f32_16x16x32_bf16 v[84:87], v[146:149], v[208:211], v[84:87]
	v_mfma_f32_16x16x32_bf16 v[80:83], v[154:157], v[208:211], v[80:83]
	v_mfma_f32_16x16x32_bf16 v[124:127], v[150:153], v[188:191], v[124:127]
	v_mfma_f32_16x16x32_bf16 v[120:123], v[158:161], v[188:191], v[120:123]
	v_mfma_f32_16x16x32_bf16 v[116:119], v[150:153], v[196:199], v[116:119]
	v_mfma_f32_16x16x32_bf16 v[112:115], v[158:161], v[196:199], v[112:115]
	v_mfma_f32_16x16x32_bf16 v[100:103], v[150:153], v[204:207], v[100:103]
	v_mfma_f32_16x16x32_bf16 v[96:99], v[158:161], v[204:207], v[96:99]
	v_mfma_f32_16x16x32_bf16 v[84:87], v[150:153], v[212:215], v[84:87]
	v_mfma_f32_16x16x32_bf16 v[80:83], v[158:161], v[212:215], v[80:83]
	v_mfma_f32_16x16x32_bf16 v[108:111], v[162:165], v[184:187], v[108:111]
	v_mfma_f32_16x16x32_bf16 v[104:107], v[170:173], v[184:187], v[104:107]
	v_mfma_f32_16x16x32_bf16 v[92:95], v[162:165], v[192:195], v[92:95]
	v_mfma_f32_16x16x32_bf16 v[88:91], v[170:173], v[192:195], v[88:91]
	v_mfma_f32_16x16x32_bf16 v[76:79], v[162:165], v[200:203], v[76:79]
	v_mfma_f32_16x16x32_bf16 v[72:75], v[170:173], v[200:203], v[72:75]
	v_mfma_f32_16x16x32_bf16 v[68:71], v[162:165], v[208:211], v[68:71]
	v_mfma_f32_16x16x32_bf16 v[64:67], v[170:173], v[208:211], v[64:67]
	v_mfma_f32_16x16x32_bf16 v[108:111], v[166:169], v[188:191], v[108:111]
	v_mfma_f32_16x16x32_bf16 v[104:107], v[180:183], v[188:191], v[104:107]
	v_mfma_f32_16x16x32_bf16 v[92:95], v[166:169], v[196:199], v[92:95]
	v_mfma_f32_16x16x32_bf16 v[88:91], v[180:183], v[196:199], v[88:91]
	v_mfma_f32_16x16x32_bf16 v[76:79], v[166:169], v[204:207], v[76:79]
	v_mfma_f32_16x16x32_bf16 v[72:75], v[180:183], v[204:207], v[72:75]
	s_setprio 2
	s_barrier
	v_mfma_f32_16x16x32_bf16 v[68:71], v[166:169], v[212:215], v[68:71]
	v_mfma_f32_16x16x32_bf16 v[64:67], v[180:183], v[212:215], v[64:67]
	s_setprio 0
	s_add_i32 s63, s0, s39
	v_lshl_add_u64 v[174:175], s[30:31], 0, v[130:131]
	s_mov_b32 m0, s63
	ds_read_b128 v[184:187], v145 offset:16384
	ds_read_b128 v[188:191], v145 offset:17408
	ds_read_b128 v[192:195], v145 offset:18432
	ds_read_b128 v[196:199], v145 offset:19456
	ds_read_b128 v[200:203], v145 offset:20480
	ds_read_b128 v[204:207], v145 offset:21504
	ds_read_b128 v[208:211], v145 offset:22528
	ds_read_b128 v[212:215], v145 offset:23552
	global_load_lds_dwordx4 v[174:175], off
	s_add_i32 m0, s63, 0x2000
	s_add_u32 s64, s30, 0x80000
	v_lshl_add_u64 v[216:217], s[30:31], 0, v[134:135]
	s_addc_u32 s65, s31, 0
	s_add_i32 s63, s55, s39
	global_load_lds_dwordx4 v[216:217], off
	v_lshl_add_u64 v[218:219], s[64:65], 0, v[130:131]
	s_mov_b32 m0, s63
	v_lshl_add_u64 v[220:221], s[34:35], 0, v[132:133]
	global_load_lds_dwordx4 v[218:219], off
	v_lshl_add_u64 v[218:219], s[64:65], 0, v[134:135]
	s_add_i32 m0, s63, 0x2000
	s_nop 0
	global_load_lds_dwordx4 v[218:219], off
	v_lshl_add_u64 v[218:219], s[34:35], 0, v[128:129]
	s_mov_b32 m0, s41
	s_nop 0
	global_load_lds_dwordx4 v[218:219], off
	s_mov_b32 m0, s46
	s_nop 0
	global_load_lds_dwordx4 v[220:221], off
	s_waitcnt vmcnt(8)
	s_waitcnt lgkmcnt(0)
	s_barrier
; #define PG8_STAGE(bufoff, gbase, voff) do { _Pragma("unroll") for (int _i = 0; _i < 2; ++_i) \
;         __builtin_amdgcn_global_load_lds((const unsigned*)((const char*)(gbase) + (voff)[_i]), (LAS unsigned*)(lds + (bufoff) + ldsw + _i * 8192), 16, 0, 0); } while (0)
; #define PG8_LDA(dst, b, h) do { _Pragma("unroll") for (int m = 0; m < 4; ++m) _Pragma("unroll") for (int k = 0; k < 2; ++k) dst[m][k] = *(const LAS bf16x8*)(lds + PG8_SA(b, h) + aoff + m * 2048 + k * 1024); } while (0)
; #define PG8_LDB(dst, b, h) do { _Pragma("unroll") for (int n = 0; n < 2; ++n) _Pragma("unroll") for (int k = 0; k < 2; ++k) dst[n][k] = *(const LAS bf16x8*)(lds + PG8_SB(b, h) + boff + n * 2048 + k * 1024); } while (0)
; #define PG8_MMA(ai, bj, At, Bt) do { __builtin_amdgcn_s_setprio(1); _Pragma("unroll") for (int m = 0; m < 4; ++m) _Pragma("unroll") for (int n = 0; n < 2; ++n) _Pragma("unroll") for (int k = 0; k < 2; ++k) \
;         acc[ai][bj][m][n] = __builtin_amdgcn_mfma_f32_16x16x32_bf16(Bt[n][k], At[m][k], acc[ai][bj][m][n], 0, 0, 0); __builtin_amdgcn_s_setprio(0); } while (0)
; #define PG8_WAIT_V(n) asm volatile("s_waitcnt vmcnt(" #n ")" ::: "memory")
; #define PG8_WAIT_L(n) asm volatile("s_waitcnt lgkmcnt(" #n ")" ::: "memory")
; #define PG8_BAR __builtin_amdgcn_s_barrier()
; #define PG8_SCHED __builtin_amdgcn_sched_barrier(0)
; template <class Epi, class Sched, bool ALIGN_EPI = true, bool SP2 = true>
; __device__ __forceinline__ void gemm_phase(LAS unsigned char* lds, const bf16_t* Ag, const bf16_t* Btg, const int K, const int lda, const int ldb, const Sched& S, const Epi& E) {
;     ...
;             PG8_WAIT_V(8); PG8_WAIT_L(0); PG8_BAR; PG8_MMA(1, 0, At, B0); PG8_MMA(1, 1, At, B1); PG8_BAR; PG8_SCHED;
;             PG8_LDB(B0, 1, 0); PG8_LDB(B1, 1, 1); PG8_SCHED; PG8_LDA(At, 1, 0); PG8_STAGE(PG8_SA(0, 1), a2 + hstepA, voffA);
;             PG8_WAIT_V(8); PG8_WAIT_L(0); PG8_BAR; PG8_MMA(0, 0, At, B0); PG8_MMA(0, 1, At, B1); PG8_BAR; PG8_SCHED;
	s_setprio 1
	s_waitcnt lgkmcnt(0)
	v_mfma_f32_16x16x32_bf16 v[60:63], v[146:149], v[184:187], v[60:63]
	v_mfma_f32_16x16x32_bf16 v[56:59], v[154:157], v[184:187], v[56:59]
	v_mfma_f32_16x16x32_bf16 v[52:55], v[146:149], v[192:195], v[52:55]
	v_mfma_f32_16x16x32_bf16 v[48:51], v[154:157], v[192:195], v[48:51]
	v_mfma_f32_16x16x32_bf16 v[36:39], v[146:149], v[200:203], v[36:39]
	v_mfma_f32_16x16x32_bf16 v[32:35], v[154:157], v[200:203], v[32:35]
	v_mfma_f32_16x16x32_bf16 v[20:23], v[146:149], v[208:211], v[20:23]
	v_mfma_f32_16x16x32_bf16 v[16:19], v[154:157], v[208:211], v[16:19]
	v_mfma_f32_16x16x32_bf16 v[60:63], v[150:153], v[188:191], v[60:63]
	v_mfma_f32_16x16x32_bf16 v[56:59], v[158:161], v[188:191], v[56:59]
	v_mfma_f32_16x16x32_bf16 v[52:55], v[150:153], v[196:199], v[52:55]
	v_mfma_f32_16x16x32_bf16 v[48:51], v[158:161], v[196:199], v[48:51]
	v_mfma_f32_16x16x32_bf16 v[36:39], v[150:153], v[204:207], v[36:39]
	v_mfma_f32_16x16x32_bf16 v[32:35], v[158:161], v[204:207], v[32:35]
	v_mfma_f32_16x16x32_bf16 v[20:23], v[150:153], v[212:215], v[20:23]
	v_mfma_f32_16x16x32_bf16 v[16:19], v[158:161], v[212:215], v[16:19]
	v_mfma_f32_16x16x32_bf16 v[44:47], v[162:165], v[184:187], v[44:47]
	v_mfma_f32_16x16x32_bf16 v[40:43], v[170:173], v[184:187], v[40:43]
	v_mfma_f32_16x16x32_bf16 v[28:31], v[162:165], v[192:195], v[28:31]
	v_mfma_f32_16x16x32_bf16 v[24:27], v[170:173], v[192:195], v[24:27]
	v_mfma_f32_16x16x32_bf16 v[12:15], v[162:165], v[200:203], v[12:15]
	v_mfma_f32_16x16x32_bf16 v[8:11], v[170:173], v[200:203], v[8:11]
	v_mfma_f32_16x16x32_bf16 v[4:7], v[162:165], v[208:211], v[4:7]
	v_mfma_f32_16x16x32_bf16 v[0:3], v[170:173], v[208:211], v[0:3]
	v_mfma_f32_16x16x32_bf16 v[44:47], v[166:169], v[188:191], v[44:47]
	v_mfma_f32_16x16x32_bf16 v[40:43], v[180:183], v[188:191], v[40:43]
	v_mfma_f32_16x16x32_bf16 v[28:31], v[166:169], v[196:199], v[28:31]
	v_mfma_f32_16x16x32_bf16 v[24:27], v[180:183], v[196:199], v[24:27]
	v_mfma_f32_16x16x32_bf16 v[12:15], v[166:169], v[204:207], v[12:15]
	v_mfma_f32_16x16x32_bf16 v[8:11], v[180:183], v[204:207], v[8:11]
	s_setprio 2
	s_barrier
	v_mfma_f32_16x16x32_bf16 v[4:7], v[166:169], v[212:215], v[4:7]
	v_mfma_f32_16x16x32_bf16 v[0:3], v[180:183], v[212:215], v[0:3]
	s_setprio 0
	s_add_i32 s63, 0, 0x18000
	s_add_i32 s64, 0, 0x1c000
	v_add_u32_e32 v158, s63, v142
	v_add_u32_e32 v180, s64, v142
	ds_read_b128 v[146:149], v158
	ds_read_b128 v[150:153], v158 offset:1024
	ds_read_b128 v[154:157], v158 offset:2048
	ds_read_b128 v[158:161], v158 offset:3072
	ds_read_b128 v[162:165], v180
	ds_read_b128 v[166:169], v180 offset:1024
	ds_read_b128 v[170:173], v180 offset:2048
	ds_read_b128 v[180:183], v180 offset:3072
	s_add_u32 s34, s34, 0x80000
	s_addc_u32 s35, s35, 0
	s_mov_b32 m0, s47
	v_lshl_add_u64 v[222:223], s[34:35], 0, v[128:129]
	ds_read_b128 v[184:187], v145 offset:32768
	ds_read_b128 v[188:191], v145 offset:33792
	ds_read_b128 v[192:195], v145 offset:34816
	ds_read_b128 v[196:199], v145 offset:35840
	ds_read_b128 v[200:203], v145 offset:36864
	ds_read_b128 v[204:207], v145 offset:37888
	ds_read_b128 v[208:211], v145 offset:38912
	ds_read_b128 v[212:215], v145 offset:39936
	global_load_lds_dwordx4 v[222:223], off
	v_lshl_add_u64 v[222:223], s[34:35], 0, v[132:133]
	s_mov_b32 m0, s50
	s_nop 0
	global_load_lds_dwordx4 v[222:223], off
	s_waitcnt vmcnt(8)
	s_waitcnt lgkmcnt(0)
	s_barrier
	s_setprio 1
	s_waitcnt lgkmcnt(0)
	v_mfma_f32_16x16x32_bf16 v[124:127], v[146:149], v[184:187], v[124:127]
	v_mfma_f32_16x16x32_bf16 v[120:123], v[154:157], v[184:187], v[120:123]
	v_mfma_f32_16x16x32_bf16 v[116:119], v[146:149], v[192:195], v[116:119]
	v_mfma_f32_16x16x32_bf16 v[112:115], v[154:157], v[192:195], v[112:115]
	v_mfma_f32_16x16x32_bf16 v[100:103], v[146:149], v[200:203], v[100:103]
	v_mfma_f32_16x16x32_bf16 v[96:99], v[154:157], v[200:203], v[96:99]
	v_mfma_f32_16x16x32_bf16 v[84:87], v[146:149], v[208:211], v[84:87]
	v_mfma_f32_16x16x32_bf16 v[80:83], v[154:157], v[208:211], v[80:83]
	v_mfma_f32_16x16x32_bf16 v[124:127], v[150:153], v[188:191], v[124:127]
	v_mfma_f32_16x16x32_bf16 v[120:123], v[158:161], v[188:191], v[120:123]
	v_mfma_f32_16x16x32_bf16 v[116:119], v[150:153], v[196:199], v[116:119]
	v_mfma_f32_16x16x32_bf16 v[112:115], v[158:161], v[196:199], v[112:115]
	v_mfma_f32_16x16x32_bf16 v[100:103], v[150:153], v[204:207], v[100:103]
	v_mfma_f32_16x16x32_bf16 v[96:99], v[158:161], v[204:207], v[96:99]
	v_mfma_f32_16x16x32_bf16 v[84:87], v[150:153], v[212:215], v[84:87]
	v_mfma_f32_16x16x32_bf16 v[80:83], v[158:161], v[212:215], v[80:83]
	v_mfma_f32_16x16x32_bf16 v[108:111], v[162:165], v[184:187], v[108:111]
	v_mfma_f32_16x16x32_bf16 v[104:107], v[170:173], v[184:187], v[104:107]
	v_mfma_f32_16x16x32_bf16 v[92:95], v[162:165], v[192:195], v[92:95]
	v_mfma_f32_16x16x32_bf16 v[88:91], v[170:173], v[192:195], v[88:91]
	v_mfma_f32_16x16x32_bf16 v[76:79], v[162:165], v[200:203], v[76:79]
	v_mfma_f32_16x16x32_bf16 v[72:75], v[170:173], v[200:203], v[72:75]
	v_mfma_f32_16x16x32_bf16 v[68:71], v[162:165], v[208:211], v[68:71]
	v_mfma_f32_16x16x32_bf16 v[64:67], v[170:173], v[208:211], v[64:67]
	v_mfma_f32_16x16x32_bf16 v[108:111], v[166:169], v[188:191], v[108:111]
	v_mfma_f32_16x16x32_bf16 v[104:107], v[180:183], v[188:191], v[104:107]
	v_mfma_f32_16x16x32_bf16 v[92:95], v[166:169], v[196:199], v[92:95]
	v_mfma_f32_16x16x32_bf16 v[88:91], v[180:183], v[196:199], v[88:91]
	v_mfma_f32_16x16x32_bf16 v[76:79], v[166:169], v[204:207], v[76:79]
	v_mfma_f32_16x16x32_bf16 v[72:75], v[180:183], v[204:207], v[72:75]
	s_setprio 2
	s_barrier
; #define PG8_STAGE(bufoff, gbase, voff) do { _Pragma("unroll") for (int _i = 0; _i < 2; ++_i) \
;         __builtin_amdgcn_global_load_lds((const unsigned*)((const char*)(gbase) + (voff)[_i]), (LAS unsigned*)(lds + (bufoff) + ldsw + _i * 8192), 16, 0, 0); } while (0)
; #define PG8_LDA(dst, b, h) do { _Pragma("unroll") for (int m = 0; m < 4; ++m) _Pragma("unroll") for (int k = 0; k < 2; ++k) dst[m][k] = *(const LAS bf16x8*)(lds + PG8_SA(b, h) + aoff + m * 2048 + k * 1024); } while (0)
; #define PG8_MMA(ai, bj, At, Bt) do { __builtin_amdgcn_s_setprio(1); _Pragma("unroll") for (int m = 0; m < 4; ++m) _Pragma("unroll") for (int n = 0; n < 2; ++n) _Pragma("unroll") for (int k = 0; k < 2; ++k) \
;         acc[ai][bj][m][n] = __builtin_amdgcn_mfma_f32_16x16x32_bf16(Bt[n][k], At[m][k], acc[ai][bj][m][n], 0, 0, 0); __builtin_amdgcn_s_setprio(0); } while (0)
; #define PG8_WAIT_V(n) asm volatile("s_waitcnt vmcnt(" #n ")" ::: "memory")
; #define PG8_WAIT_L(n) asm volatile("s_waitcnt lgkmcnt(" #n ")" ::: "memory")
; #define PG8_BAR __builtin_amdgcn_s_barrier()
; #define PG8_SCHED __builtin_amdgcn_sched_barrier(0)
; template <class Epi, class Sched, bool ALIGN_EPI = true, bool SP2 = true>
; __device__ __forceinline__ void gemm_phase(LAS unsigned char* lds, const bf16_t* Ag, const bf16_t* Btg, const int K, const int lda, const int ldb, const Sched& S, const Epi& E) {
;     ...
;             PG8_WAIT_V(8); PG8_WAIT_L(0); PG8_BAR; PG8_MMA(0, 0, At, B0); PG8_MMA(0, 1, At, B1); PG8_BAR; PG8_SCHED;
;             PG8_LDA(At, 1, 1); PG8_STAGE(PG8_SB(1, 0), b3, voffB); PG8_STAGE(PG8_SB(1, 1), b3 + hstepB, voffB); PG8_STAGE(PG8_SA(1, 0), a3, voffA);
;             PG8_WAIT_V(8); PG8_WAIT_L(0); PG8_BAR; PG8_MMA(1, 0, At, B0); PG8_MMA(1, 1, At, B1); PG8_BAR; PG8_SCHED;
	v_mfma_f32_16x16x32_bf16 v[68:71], v[166:169], v[212:215], v[68:71]
	v_mfma_f32_16x16x32_bf16 v[64:67], v[180:183], v[212:215], v[64:67]
	s_setprio 0
	s_add_i32 s34, s63, s39
	v_lshl_add_u64 v[174:175], v[174:175], 0, s[10:11]
	s_mov_b32 m0, s34
	ds_read_b128 v[184:187], v145 offset:49152
	ds_read_b128 v[188:191], v145 offset:50176
	ds_read_b128 v[192:195], v145 offset:51200
	ds_read_b128 v[196:199], v145 offset:52224
	ds_read_b128 v[200:203], v145 offset:53248
	ds_read_b128 v[204:207], v145 offset:54272
	ds_read_b128 v[208:211], v145 offset:55296
	ds_read_b128 v[212:215], v145 offset:56320
	global_load_lds_dwordx4 v[174:175], off
	s_add_i32 m0, s34, 0x2000
	s_add_u32 s30, s30, 0x80080
	v_lshl_add_u64 v[174:175], v[216:217], 0, s[10:11]
	s_addc_u32 s31, s31, 0
	s_add_i32 s34, s64, s39
	global_load_lds_dwordx4 v[174:175], off
	v_lshl_add_u64 v[174:175], s[30:31], 0, v[130:131]
	s_mov_b32 m0, s34
	s_nop 0
	global_load_lds_dwordx4 v[174:175], off
	v_lshl_add_u64 v[174:175], s[30:31], 0, v[134:135]
	s_add_i32 m0, s34, 0x2000
	s_nop 0
	global_load_lds_dwordx4 v[174:175], off
	v_lshl_add_u64 v[174:175], v[218:219], 0, s[10:11]
	s_mov_b32 m0, s51
	s_nop 0
	global_load_lds_dwordx4 v[174:175], off
	v_lshl_add_u64 v[174:175], v[220:221], 0, s[10:11]
	s_mov_b32 m0, s52
	s_nop 0
	global_load_lds_dwordx4 v[174:175], off
	s_waitcnt vmcnt(8)
	s_waitcnt lgkmcnt(0)
	s_barrier
	s_setprio 1
	s_waitcnt lgkmcnt(0)
	v_mfma_f32_16x16x32_bf16 v[60:63], v[146:149], v[184:187], v[60:63]
	v_mfma_f32_16x16x32_bf16 v[56:59], v[154:157], v[184:187], v[56:59]
	v_mfma_f32_16x16x32_bf16 v[52:55], v[146:149], v[192:195], v[52:55]
	v_mfma_f32_16x16x32_bf16 v[48:51], v[154:157], v[192:195], v[48:51]
	v_mfma_f32_16x16x32_bf16 v[36:39], v[146:149], v[200:203], v[36:39]
	v_mfma_f32_16x16x32_bf16 v[32:35], v[154:157], v[200:203], v[32:35]
	v_mfma_f32_16x16x32_bf16 v[20:23], v[146:149], v[208:211], v[20:23]
	v_mfma_f32_16x16x32_bf16 v[16:19], v[154:157], v[208:211], v[16:19]
	v_mfma_f32_16x16x32_bf16 v[60:63], v[150:153], v[188:191], v[60:63]
	v_mfma_f32_16x16x32_bf16 v[56:59], v[158:161], v[188:191], v[56:59]
	v_mfma_f32_16x16x32_bf16 v[52:55], v[150:153], v[196:199], v[52:55]
	v_mfma_f32_16x16x32_bf16 v[48:51], v[158:161], v[196:199], v[48:51]
	v_mfma_f32_16x16x32_bf16 v[36:39], v[150:153], v[204:207], v[36:39]
	v_mfma_f32_16x16x32_bf16 v[32:35], v[158:161], v[204:207], v[32:35]
	v_mfma_f32_16x16x32_bf16 v[20:23], v[150:153], v[212:215], v[20:23]
	v_mfma_f32_16x16x32_bf16 v[16:19], v[158:161], v[212:215], v[16:19]
	v_mfma_f32_16x16x32_bf16 v[44:47], v[162:165], v[184:187], v[44:47]
	v_mfma_f32_16x16x32_bf16 v[40:43], v[170:173], v[184:187], v[40:43]
	v_mfma_f32_16x16x32_bf16 v[28:31], v[162:165], v[192:195], v[28:31]
	v_mfma_f32_16x16x32_bf16 v[24:27], v[170:173], v[192:195], v[24:27]
	v_mfma_f32_16x16x32_bf16 v[12:15], v[162:165], v[200:203], v[12:15]
	v_mfma_f32_16x16x32_bf16 v[8:11], v[170:173], v[200:203], v[8:11]
	v_mfma_f32_16x16x32_bf16 v[4:7], v[162:165], v[208:211], v[4:7]
	v_mfma_f32_16x16x32_bf16 v[0:3], v[170:173], v[208:211], v[0:3]
	v_mfma_f32_16x16x32_bf16 v[44:47], v[166:169], v[188:191], v[44:47]
	v_mfma_f32_16x16x32_bf16 v[40:43], v[180:183], v[188:191], v[40:43]
	v_mfma_f32_16x16x32_bf16 v[28:31], v[166:169], v[196:199], v[28:31]
	v_mfma_f32_16x16x32_bf16 v[24:27], v[180:183], v[196:199], v[24:27]
	v_mfma_f32_16x16x32_bf16 v[12:15], v[166:169], v[204:207], v[12:15]
	v_mfma_f32_16x16x32_bf16 v[8:11], v[180:183], v[204:207], v[8:11]
	s_setprio 2
	s_barrier
	v_mfma_f32_16x16x32_bf16 v[4:7], v[166:169], v[212:215], v[4:7]
	v_mfma_f32_16x16x32_bf16 v[0:3], v[180:183], v[212:215], v[0:3]
	s_setprio 0
	s_add_i32 s62, s62, 2
	s_add_u32 s28, s28, 0x100
	s_addc_u32 s29, s29, 0
	s_add_u32 s60, s60, 0x100
	s_addc_u32 s61, s61, 0
	s_cmp_gt_u32 s62, 29
	s_cbranch_scc0 .LBB0_302
	s_and_b64 vcc, exec, s[12:13]
	s_cbranch_vccz .LBB0_305
	s_barrier

; #define PG8_STAGE(bufoff, gbase, voff) do { _Pragma("unroll") for (int _i = 0; _i < 2; ++_i) \
;         __builtin_amdgcn_global_load_lds((const unsigned*)((const char*)(gbase) + (voff)[_i]), (LAS unsigned*)(lds + (bufoff) + ldsw + _i * 8192), 16, 0, 0); } while (0)
; #define PG8_LDA(dst, b, h) do { _Pragma("unroll") for (int m = 0; m < 4; ++m) _Pragma("unroll") for (int k = 0; k < 2; ++k) dst[m][k] = *(const LAS bf16x8*)(lds + PG8_SA(b, h) + aoff + m * 2048 + k * 1024); } while (0)
; #define PG8_LDB(dst, b, h) do { _Pragma("unroll") for (int n = 0; n < 2; ++n) _Pragma("unroll") for (int k = 0; k < 2; ++k) dst[n][k] = *(const LAS bf16x8*)(lds + PG8_SB(b, h) + boff + n * 2048 + k * 1024); } while (0)
; #define PG8_MMA(ai, bj, At, Bt) do { __builtin_amdgcn_s_setprio(1); _Pragma("unroll") for (int m = 0; m < 4; ++m) _Pragma("unroll") for (int n = 0; n < 2; ++n) _Pragma("unroll") for (int k = 0; k < 2; ++k) \
;         acc[ai][bj][m][n] = __builtin_amdgcn_mfma_f32_16x16x32_bf16(Bt[n][k], At[m][k], acc[ai][bj][m][n], 0, 0, 0); __builtin_amdgcn_s_setprio(0); } while (0)
; #define PG8_WAIT_V(n) asm volatile("s_waitcnt vmcnt(" #n ")" ::: "memory")
; #define PG8_WAIT_L(n) asm volatile("s_waitcnt lgkmcnt(" #n ")" ::: "memory")
; #define PG8_BAR __builtin_amdgcn_s_barrier()
; template <class Epi, class Sched, bool ALIGN_EPI = true, bool SP2 = true>
; __device__ __forceinline__ void gemm_phase(LAS unsigned char* lds, const bf16_t* Ag, const bf16_t* Btg, const int K, const int lda, const int ldb, const Sched& S, const Epi& E) {
;     ...
;             const char* a1 = cA + (size_t)(t + 1) * kstep;
;             const char* a2 = last ? nA : cA + (size_t)(t + 2) * kstep; const char* b2 = last ? nB : cB + (size_t)(t + 2) * kstep;
;             const char* a3 = a2 + kstep; const char* b3 = b2 + kstep;
;             if constexpr (SP2) {
;             PG8_LDB(B0, 0, 0); PG8_LDB(B1, 0, 1); PG8_SCHED; PG8_LDA(At, 0, 0); PG8_STAGE(PG8_SA(1, 1), a1 + hstepA, voffA);
;             PG8_WAIT_V(8); PG8_WAIT_L(0); PG8_BAR; PG8_MMA(0, 0, At, B0); PG8_MMA(0, 1, At, B1); PG8_BAR; PG8_SCHED;
;             PG8_LDA(At, 0, 1); PG8_STAGE(PG8_SB(0, 0), b2, voffB); PG8_STAGE(PG8_SB(0, 1), b2 + hstepB, voffB); PG8_STAGE(PG8_SA(0, 0), a2, voffA);
;             PG8_WAIT_V(8); PG8_WAIT_L(0); PG8_BAR; PG8_MMA(1, 0, At, B0); PG8_MMA(1, 1, At, B1); PG8_BAR; PG8_SCHED;
.LBB0_387:
	ds_read_b128 v[80:83], v182
	ds_read_b128 v[84:87], v182 offset:1024
	ds_read_b128 v[136:139], v182 offset:2048
	ds_read_b128 v[140:143], v182 offset:3072
	ds_read_b128 v[164:167], v183
	ds_read_b128 v[168:171], v183 offset:1024
	ds_read_b128 v[172:175], v183 offset:2048
	ds_read_b128 v[186:189], v183 offset:3072
	s_add_u32 s6, s4, 0xfff80080
	s_addc_u32 s7, s5, -1
	s_cmp_eq_u32 s38, 28
	s_cselect_b32 s35, s1, s7
	s_cselect_b32 s34, s9, s6
	s_cselect_b32 s7, s15, s33
	s_cselect_b32 s6, s21, s23
	v_lshl_add_u64 v[222:223], s[4:5], 0, v[156:157]
	s_add_i32 m0, s54, 0xc000
	ds_read_b128 v[190:193], v184
	ds_read_b128 v[194:197], v184 offset:1024
	ds_read_b128 v[198:201], v184 offset:2048
	ds_read_b128 v[202:205], v184 offset:3072
	ds_read_b128 v[206:209], v184 offset:4096
	ds_read_b128 v[210:213], v184 offset:5120
	ds_read_b128 v[214:217], v184 offset:6144
	ds_read_b128 v[218:221], v184 offset:7168
	global_load_lds_dwordx4 v[222:223], off
	v_lshl_add_u64 v[222:223], s[4:5], 0, v[158:159]
	s_add_i32 m0, s54, 0xe000
	s_nop 0
	global_load_lds_dwordx4 v[222:223], off
	s_waitcnt vmcnt(8)
	s_waitcnt lgkmcnt(0)
	s_barrier
	s_setprio 1
	s_waitcnt lgkmcnt(0)
	v_mfma_f32_16x16x32_bf16 v[132:135], v[80:83], v[190:193], v[132:135]
	v_mfma_f32_16x16x32_bf16 v[128:131], v[136:139], v[190:193], v[128:131]
	v_mfma_f32_16x16x32_bf16 v[124:127], v[80:83], v[198:201], v[124:127]
	v_mfma_f32_16x16x32_bf16 v[120:123], v[136:139], v[198:201], v[120:123]
	v_mfma_f32_16x16x32_bf16 v[116:119], v[80:83], v[206:209], v[116:119]
	v_mfma_f32_16x16x32_bf16 v[112:115], v[136:139], v[206:209], v[112:115]
	v_mfma_f32_16x16x32_bf16 v[108:111], v[80:83], v[214:217], v[108:111]
	v_mfma_f32_16x16x32_bf16 v[104:107], v[136:139], v[214:217], v[104:107]
	v_mfma_f32_16x16x32_bf16 v[132:135], v[84:87], v[194:197], v[132:135]
	v_mfma_f32_16x16x32_bf16 v[128:131], v[140:143], v[194:197], v[128:131]
	v_mfma_f32_16x16x32_bf16 v[124:127], v[84:87], v[202:205], v[124:127]
	v_mfma_f32_16x16x32_bf16 v[120:123], v[140:143], v[202:205], v[120:123]
	v_mfma_f32_16x16x32_bf16 v[116:119], v[84:87], v[210:213], v[116:119]
	v_mfma_f32_16x16x32_bf16 v[112:115], v[140:143], v[210:213], v[112:115]
	v_mfma_f32_16x16x32_bf16 v[108:111], v[84:87], v[218:221], v[108:111]
	v_mfma_f32_16x16x32_bf16 v[104:107], v[140:143], v[218:221], v[104:107]
	v_mfma_f32_16x16x32_bf16 v[60:63], v[164:167], v[190:193], v[60:63]
	v_mfma_f32_16x16x32_bf16 v[56:59], v[172:175], v[190:193], v[56:59]
	v_mfma_f32_16x16x32_bf16 v[52:55], v[164:167], v[198:201], v[52:55]
	v_mfma_f32_16x16x32_bf16 v[48:51], v[172:175], v[198:201], v[48:51]
	v_mfma_f32_16x16x32_bf16 v[44:47], v[164:167], v[206:209], v[44:47]
	v_mfma_f32_16x16x32_bf16 v[40:43], v[172:175], v[206:209], v[40:43]
	v_mfma_f32_16x16x32_bf16 v[36:39], v[164:167], v[214:217], v[36:39]
	v_mfma_f32_16x16x32_bf16 v[32:35], v[172:175], v[214:217], v[32:35]
	v_mfma_f32_16x16x32_bf16 v[60:63], v[168:171], v[194:197], v[60:63]
	v_mfma_f32_16x16x32_bf16 v[56:59], v[186:189], v[194:197], v[56:59]
	v_mfma_f32_16x16x32_bf16 v[52:55], v[168:171], v[202:205], v[52:55]
	v_mfma_f32_16x16x32_bf16 v[48:51], v[186:189], v[202:205], v[48:51]
	v_mfma_f32_16x16x32_bf16 v[44:47], v[168:171], v[210:213], v[44:47]
	v_mfma_f32_16x16x32_bf16 v[40:43], v[186:189], v[210:213], v[40:43]
	s_setprio 2
	s_barrier
	v_mfma_f32_16x16x32_bf16 v[36:39], v[168:171], v[218:221], v[36:39]
	v_mfma_f32_16x16x32_bf16 v[32:35], v[186:189], v[218:221], v[32:35]
	s_setprio 0
	s_add_i32 s39, s84, s37
	v_lshl_add_u64 v[222:223], s[6:7], 0, v[146:147]
	s_mov_b32 m0, s39
	ds_read_b128 v[190:193], v184 offset:16384
	ds_read_b128 v[194:197], v184 offset:17408
	ds_read_b128 v[198:201], v184 offset:18432
	ds_read_b128 v[202:205], v184 offset:19456
	ds_read_b128 v[206:209], v184 offset:20480
	ds_read_b128 v[210:213], v184 offset:21504
	ds_read_b128 v[214:217], v184 offset:22528
	ds_read_b128 v[218:221], v184 offset:23552
	global_load_lds_dwordx4 v[222:223], off
	s_add_i32 m0, s39, 0x2000
	s_add_u32 s46, s6, 0x80000
	v_lshl_add_u64 v[224:225], s[6:7], 0, v[150:151]
	s_addc_u32 s47, s7, 0
	s_add_i32 s39, s85, s37
	global_load_lds_dwordx4 v[224:225], off
	v_lshl_add_u64 v[226:227], s[46:47], 0, v[146:147]
	s_mov_b32 m0, s39
	v_lshl_add_u64 v[228:229], s[34:35], 0, v[148:149]
	global_load_lds_dwordx4 v[226:227], off
	v_lshl_add_u64 v[226:227], s[46:47], 0, v[150:151]
	s_add_i32 m0, s39, 0x2000
	s_nop 0
	global_load_lds_dwordx4 v[226:227], off
	v_lshl_add_u64 v[226:227], s[34:35], 0, v[144:145]
	s_mov_b32 m0, s54
	s_nop 0
	global_load_lds_dwordx4 v[226:227], off
	s_mov_b32 m0, s55
	s_nop 0
	global_load_lds_dwordx4 v[228:229], off
	s_waitcnt vmcnt(8)
	s_waitcnt lgkmcnt(0)
	s_barrier
; #define PG8_STAGE(bufoff, gbase, voff) do { _Pragma("unroll") for (int _i = 0; _i < 2; ++_i) \
;         __builtin_amdgcn_global_load_lds((const unsigned*)((const char*)(gbase) + (voff)[_i]), (LAS unsigned*)(lds + (bufoff) + ldsw + _i * 8192), 16, 0, 0); } while (0)
; #define PG8_LDA(dst, b, h) do { _Pragma("unroll") for (int m = 0; m < 4; ++m) _Pragma("unroll") for (int k = 0; k < 2; ++k) dst[m][k] = *(const LAS bf16x8*)(lds + PG8_SA(b, h) + aoff + m * 2048 + k * 1024); } while (0)
; #define PG8_LDB(dst, b, h) do { _Pragma("unroll") for (int n = 0; n < 2; ++n) _Pragma("unroll") for (int k = 0; k < 2; ++k) dst[n][k] = *(const LAS bf16x8*)(lds + PG8_SB(b, h) + boff + n * 2048 + k * 1024); } while (0)
; #define PG8_MMA(ai, bj, At, Bt) do { __builtin_amdgcn_s_setprio(1); _Pragma("unroll") for (int m = 0; m < 4; ++m) _Pragma("unroll") for (int n = 0; n < 2; ++n) _Pragma("unroll") for (int k = 0; k < 2; ++k) \
;         acc[ai][bj][m][n] = __builtin_amdgcn_mfma_f32_16x16x32_bf16(Bt[n][k], At[m][k], acc[ai][bj][m][n], 0, 0, 0); __builtin_amdgcn_s_setprio(0); } while (0)
; #define PG8_WAIT_V(n) asm volatile("s_waitcnt vmcnt(" #n ")" ::: "memory")
; #define PG8_WAIT_L(n) asm volatile("s_waitcnt lgkmcnt(" #n ")" ::: "memory")
; #define PG8_BAR __builtin_amdgcn_s_barrier()
; #define PG8_SCHED __builtin_amdgcn_sched_barrier(0)
; template <class Epi, class Sched, bool ALIGN_EPI = true, bool SP2 = true>
; __device__ __forceinline__ void gemm_phase(LAS unsigned char* lds, const bf16_t* Ag, const bf16_t* Btg, const int K, const int lda, const int ldb, const Sched& S, const Epi& E) {
;     ...
;             PG8_WAIT_V(8); PG8_WAIT_L(0); PG8_BAR; PG8_MMA(1, 0, At, B0); PG8_MMA(1, 1, At, B1); PG8_BAR; PG8_SCHED;
;             PG8_LDB(B0, 1, 0); PG8_LDB(B1, 1, 1); PG8_SCHED; PG8_LDA(At, 1, 0); PG8_STAGE(PG8_SA(0, 1), a2 + hstepA, voffA);
;             PG8_WAIT_V(8); PG8_WAIT_L(0); PG8_BAR; PG8_MMA(0, 0, At, B0); PG8_MMA(0, 1, At, B1); PG8_BAR; PG8_SCHED;
	s_setprio 1
	s_waitcnt lgkmcnt(0)
	v_mfma_f32_16x16x32_bf16 v[100:103], v[80:83], v[190:193], v[100:103]
	v_mfma_f32_16x16x32_bf16 v[96:99], v[136:139], v[190:193], v[96:99]
	v_mfma_f32_16x16x32_bf16 v[92:95], v[80:83], v[198:201], v[92:95]
	v_mfma_f32_16x16x32_bf16 v[88:91], v[136:139], v[198:201], v[88:91]
	v_mfma_f32_16x16x32_bf16 v[76:79], v[80:83], v[206:209], v[76:79]
	v_mfma_f32_16x16x32_bf16 v[72:75], v[136:139], v[206:209], v[72:75]
	v_mfma_f32_16x16x32_bf16 v[68:71], v[80:83], v[214:217], v[68:71]
	v_mfma_f32_16x16x32_bf16 v[64:67], v[136:139], v[214:217], v[64:67]
	v_mfma_f32_16x16x32_bf16 v[100:103], v[84:87], v[194:197], v[100:103]
	v_mfma_f32_16x16x32_bf16 v[96:99], v[140:143], v[194:197], v[96:99]
	v_mfma_f32_16x16x32_bf16 v[92:95], v[84:87], v[202:205], v[92:95]
	v_mfma_f32_16x16x32_bf16 v[88:91], v[140:143], v[202:205], v[88:91]
	v_mfma_f32_16x16x32_bf16 v[76:79], v[84:87], v[210:213], v[76:79]
	v_mfma_f32_16x16x32_bf16 v[72:75], v[140:143], v[210:213], v[72:75]
	v_mfma_f32_16x16x32_bf16 v[68:71], v[84:87], v[218:221], v[68:71]
	v_mfma_f32_16x16x32_bf16 v[64:67], v[140:143], v[218:221], v[64:67]
	v_mfma_f32_16x16x32_bf16 v[28:31], v[164:167], v[190:193], v[28:31]
	v_mfma_f32_16x16x32_bf16 v[24:27], v[172:175], v[190:193], v[24:27]
	v_mfma_f32_16x16x32_bf16 v[20:23], v[164:167], v[198:201], v[20:23]
	v_mfma_f32_16x16x32_bf16 v[16:19], v[172:175], v[198:201], v[16:19]
	v_mfma_f32_16x16x32_bf16 v[12:15], v[164:167], v[206:209], v[12:15]
	v_mfma_f32_16x16x32_bf16 v[8:11], v[172:175], v[206:209], v[8:11]
	v_mfma_f32_16x16x32_bf16 v[4:7], v[164:167], v[214:217], v[4:7]
	v_mfma_f32_16x16x32_bf16 v[0:3], v[172:175], v[214:217], v[0:3]
	v_mfma_f32_16x16x32_bf16 v[28:31], v[168:171], v[194:197], v[28:31]
	v_mfma_f32_16x16x32_bf16 v[24:27], v[186:189], v[194:197], v[24:27]
	v_mfma_f32_16x16x32_bf16 v[20:23], v[168:171], v[202:205], v[20:23]
	v_mfma_f32_16x16x32_bf16 v[16:19], v[186:189], v[202:205], v[16:19]
	v_mfma_f32_16x16x32_bf16 v[12:15], v[168:171], v[210:213], v[12:15]
	v_mfma_f32_16x16x32_bf16 v[8:11], v[186:189], v[210:213], v[8:11]
	s_setprio 2
	s_barrier
	v_mfma_f32_16x16x32_bf16 v[4:7], v[168:171], v[218:221], v[4:7]
	v_mfma_f32_16x16x32_bf16 v[0:3], v[186:189], v[218:221], v[0:3]
	s_setprio 0
	s_add_i32 s39, 0, 0x18000
	s_add_i32 s40, 0, 0x1c000
	v_add_u32_e32 v140, s39, v180
	v_add_u32_e32 v152, s40, v180
	ds_read_b128 v[80:83], v140
	ds_read_b128 v[84:87], v140 offset:1024
	ds_read_b128 v[136:139], v140 offset:2048
	ds_read_b128 v[140:143], v140 offset:3072
	ds_read_b128 v[164:167], v152
	ds_read_b128 v[168:171], v152 offset:1024
	ds_read_b128 v[172:175], v152 offset:2048
	ds_read_b128 v[186:189], v152 offset:3072
	s_add_u32 s34, s34, 0x80000
	s_addc_u32 s35, s35, 0
	s_mov_b32 m0, s58
	v_lshl_add_u64 v[230:231], s[34:35], 0, v[144:145]
	ds_read_b128 v[190:193], v184 offset:32768
	ds_read_b128 v[194:197], v184 offset:33792
	ds_read_b128 v[198:201], v184 offset:34816
	ds_read_b128 v[202:205], v184 offset:35840
	ds_read_b128 v[206:209], v184 offset:36864
	ds_read_b128 v[210:213], v184 offset:37888
	ds_read_b128 v[214:217], v184 offset:38912
	ds_read_b128 v[218:221], v184 offset:39936
	global_load_lds_dwordx4 v[230:231], off
	v_lshl_add_u64 v[230:231], s[34:35], 0, v[148:149]
	s_mov_b32 m0, s59
	s_nop 0
	global_load_lds_dwordx4 v[230:231], off
	s_waitcnt vmcnt(8)
	s_waitcnt lgkmcnt(0)
	s_barrier
	s_setprio 1
	s_waitcnt lgkmcnt(0)
	v_mfma_f32_16x16x32_bf16 v[132:135], v[80:83], v[190:193], v[132:135]
	v_mfma_f32_16x16x32_bf16 v[128:131], v[136:139], v[190:193], v[128:131]
	v_mfma_f32_16x16x32_bf16 v[124:127], v[80:83], v[198:201], v[124:127]
	v_mfma_f32_16x16x32_bf16 v[120:123], v[136:139], v[198:201], v[120:123]
	v_mfma_f32_16x16x32_bf16 v[116:119], v[80:83], v[206:209], v[116:119]
	v_mfma_f32_16x16x32_bf16 v[112:115], v[136:139], v[206:209], v[112:115]
	v_mfma_f32_16x16x32_bf16 v[108:111], v[80:83], v[214:217], v[108:111]
	v_mfma_f32_16x16x32_bf16 v[104:107], v[136:139], v[214:217], v[104:107]
	v_mfma_f32_16x16x32_bf16 v[132:135], v[84:87], v[194:197], v[132:135]
	v_mfma_f32_16x16x32_bf16 v[128:131], v[140:143], v[194:197], v[128:131]
	v_mfma_f32_16x16x32_bf16 v[124:127], v[84:87], v[202:205], v[124:127]
	v_mfma_f32_16x16x32_bf16 v[120:123], v[140:143], v[202:205], v[120:123]
	v_mfma_f32_16x16x32_bf16 v[116:119], v[84:87], v[210:213], v[116:119]
	v_mfma_f32_16x16x32_bf16 v[112:115], v[140:143], v[210:213], v[112:115]
	v_mfma_f32_16x16x32_bf16 v[108:111], v[84:87], v[218:221], v[108:111]
	v_mfma_f32_16x16x32_bf16 v[104:107], v[140:143], v[218:221], v[104:107]
	v_mfma_f32_16x16x32_bf16 v[60:63], v[164:167], v[190:193], v[60:63]
	v_mfma_f32_16x16x32_bf16 v[56:59], v[172:175], v[190:193], v[56:59]
	v_mfma_f32_16x16x32_bf16 v[52:55], v[164:167], v[198:201], v[52:55]
	v_mfma_f32_16x16x32_bf16 v[48:51], v[172:175], v[198:201], v[48:51]
	v_mfma_f32_16x16x32_bf16 v[44:47], v[164:167], v[206:209], v[44:47]
	v_mfma_f32_16x16x32_bf16 v[40:43], v[172:175], v[206:209], v[40:43]
	v_mfma_f32_16x16x32_bf16 v[36:39], v[164:167], v[214:217], v[36:39]
	v_mfma_f32_16x16x32_bf16 v[32:35], v[172:175], v[214:217], v[32:35]
	v_mfma_f32_16x16x32_bf16 v[60:63], v[168:171], v[194:197], v[60:63]
	v_mfma_f32_16x16x32_bf16 v[56:59], v[186:189], v[194:197], v[56:59]
	v_mfma_f32_16x16x32_bf16 v[52:55], v[168:171], v[202:205], v[52:55]
	v_mfma_f32_16x16x32_bf16 v[48:51], v[186:189], v[202:205], v[48:51]
	v_mfma_f32_16x16x32_bf16 v[44:47], v[168:171], v[210:213], v[44:47]
	v_mfma_f32_16x16x32_bf16 v[40:43], v[186:189], v[210:213], v[40:43]
	s_setprio 2
	s_barrier
; #define PG8_STAGE(bufoff, gbase, voff) do { _Pragma("unroll") for (int _i = 0; _i < 2; ++_i) \
;         __builtin_amdgcn_global_load_lds((const unsigned*)((const char*)(gbase) + (voff)[_i]), (LAS unsigned*)(lds + (bufoff) + ldsw + _i * 8192), 16, 0, 0); } while (0)
; #define PG8_LDA(dst, b, h) do { _Pragma("unroll") for (int m = 0; m < 4; ++m) _Pragma("unroll") for (int k = 0; k < 2; ++k) dst[m][k] = *(const LAS bf16x8*)(lds + PG8_SA(b, h) + aoff + m * 2048 + k * 1024); } while (0)
; #define PG8_MMA(ai, bj, At, Bt) do { __builtin_amdgcn_s_setprio(1); _Pragma("unroll") for (int m = 0; m < 4; ++m) _Pragma("unroll") for (int n = 0; n < 2; ++n) _Pragma("unroll") for (int k = 0; k < 2; ++k) \
;         acc[ai][bj][m][n] = __builtin_amdgcn_mfma_f32_16x16x32_bf16(Bt[n][k], At[m][k], acc[ai][bj][m][n], 0, 0, 0); __builtin_amdgcn_s_setprio(0); } while (0)
; #define PG8_WAIT_V(n) asm volatile("s_waitcnt vmcnt(" #n ")" ::: "memory")
; #define PG8_WAIT_L(n) asm volatile("s_waitcnt lgkmcnt(" #n ")" ::: "memory")
; #define PG8_BAR __builtin_amdgcn_s_barrier()
; #define PG8_SCHED __builtin_amdgcn_sched_barrier(0)
; template <class Epi, class Sched, bool ALIGN_EPI = true, bool SP2 = true>
; __device__ __forceinline__ void gemm_phase(LAS unsigned char* lds, const bf16_t* Ag, const bf16_t* Btg, const int K, const int lda, const int ldb, const Sched& S, const Epi& E) {
;     ...
;             PG8_WAIT_V(8); PG8_WAIT_L(0); PG8_BAR; PG8_MMA(0, 0, At, B0); PG8_MMA(0, 1, At, B1); PG8_BAR; PG8_SCHED;
;             PG8_LDA(At, 1, 1); PG8_STAGE(PG8_SB(1, 0), b3, voffB); PG8_STAGE(PG8_SB(1, 1), b3 + hstepB, voffB); PG8_STAGE(PG8_SA(1, 0), a3, voffA);
;             PG8_WAIT_V(8); PG8_WAIT_L(0); PG8_BAR; PG8_MMA(1, 0, At, B0); PG8_MMA(1, 1, At, B1); PG8_BAR; PG8_SCHED;
	v_mfma_f32_16x16x32_bf16 v[36:39], v[168:171], v[218:221], v[36:39]
	v_mfma_f32_16x16x32_bf16 v[32:35], v[186:189], v[218:221], v[32:35]
	s_setprio 0
	s_add_i32 s34, s39, s37
	v_lshl_add_u64 v[222:223], v[222:223], 0, s[16:17]
	s_mov_b32 m0, s34
	ds_read_b128 v[190:193], v184 offset:49152
	ds_read_b128 v[194:197], v184 offset:50176
	ds_read_b128 v[198:201], v184 offset:51200
	ds_read_b128 v[202:205], v184 offset:52224
	ds_read_b128 v[206:209], v184 offset:53248
	ds_read_b128 v[210:213], v184 offset:54272
	ds_read_b128 v[214:217], v184 offset:55296
	ds_read_b128 v[218:221], v184 offset:56320
	global_load_lds_dwordx4 v[222:223], off
	s_add_i32 m0, s34, 0x2000
	s_add_u32 s6, s6, 0x80080
	v_lshl_add_u64 v[222:223], v[224:225], 0, s[16:17]
	s_addc_u32 s7, s7, 0
	s_add_i32 s34, s40, s37
	global_load_lds_dwordx4 v[222:223], off
	v_lshl_add_u64 v[222:223], s[6:7], 0, v[146:147]
	s_mov_b32 m0, s34
	s_nop 0
	global_load_lds_dwordx4 v[222:223], off
	v_lshl_add_u64 v[222:223], s[6:7], 0, v[150:151]
	s_add_i32 m0, s34, 0x2000
	s_nop 0
	global_load_lds_dwordx4 v[222:223], off
	v_lshl_add_u64 v[222:223], v[226:227], 0, s[16:17]
	s_mov_b32 m0, s61
	s_nop 0
	global_load_lds_dwordx4 v[222:223], off
	v_lshl_add_u64 v[222:223], v[228:229], 0, s[16:17]
	s_mov_b32 m0, s70
	s_nop 0
	global_load_lds_dwordx4 v[222:223], off
	s_waitcnt vmcnt(8)
	s_waitcnt lgkmcnt(0)
	s_barrier
	s_setprio 1
	s_waitcnt lgkmcnt(0)
	v_mfma_f32_16x16x32_bf16 v[100:103], v[80:83], v[190:193], v[100:103]
	v_mfma_f32_16x16x32_bf16 v[96:99], v[136:139], v[190:193], v[96:99]
	v_mfma_f32_16x16x32_bf16 v[92:95], v[80:83], v[198:201], v[92:95]
	v_mfma_f32_16x16x32_bf16 v[88:91], v[136:139], v[198:201], v[88:91]
	v_mfma_f32_16x16x32_bf16 v[76:79], v[80:83], v[206:209], v[76:79]
	v_mfma_f32_16x16x32_bf16 v[72:75], v[136:139], v[206:209], v[72:75]
	v_mfma_f32_16x16x32_bf16 v[68:71], v[80:83], v[214:217], v[68:71]
	v_mfma_f32_16x16x32_bf16 v[64:67], v[136:139], v[214:217], v[64:67]
	v_mfma_f32_16x16x32_bf16 v[100:103], v[84:87], v[194:197], v[100:103]
	v_mfma_f32_16x16x32_bf16 v[96:99], v[140:143], v[194:197], v[96:99]
	v_mfma_f32_16x16x32_bf16 v[92:95], v[84:87], v[202:205], v[92:95]
	v_mfma_f32_16x16x32_bf16 v[88:91], v[140:143], v[202:205], v[88:91]
	v_mfma_f32_16x16x32_bf16 v[76:79], v[84:87], v[210:213], v[76:79]
	v_mfma_f32_16x16x32_bf16 v[72:75], v[140:143], v[210:213], v[72:75]
	v_mfma_f32_16x16x32_bf16 v[68:71], v[84:87], v[218:221], v[68:71]
	v_mfma_f32_16x16x32_bf16 v[64:67], v[140:143], v[218:221], v[64:67]
	v_mfma_f32_16x16x32_bf16 v[28:31], v[164:167], v[190:193], v[28:31]
	v_mfma_f32_16x16x32_bf16 v[24:27], v[172:175], v[190:193], v[24:27]
	v_mfma_f32_16x16x32_bf16 v[20:23], v[164:167], v[198:201], v[20:23]
	v_mfma_f32_16x16x32_bf16 v[16:19], v[172:175], v[198:201], v[16:19]
	v_mfma_f32_16x16x32_bf16 v[12:15], v[164:167], v[206:209], v[12:15]
	v_mfma_f32_16x16x32_bf16 v[8:11], v[172:175], v[206:209], v[8:11]
	v_mfma_f32_16x16x32_bf16 v[4:7], v[164:167], v[214:217], v[4:7]
	v_mfma_f32_16x16x32_bf16 v[0:3], v[172:175], v[214:217], v[0:3]
	v_mfma_f32_16x16x32_bf16 v[28:31], v[168:171], v[194:197], v[28:31]
	v_mfma_f32_16x16x32_bf16 v[24:27], v[186:189], v[194:197], v[24:27]
	v_mfma_f32_16x16x32_bf16 v[20:23], v[168:171], v[202:205], v[20:23]
	v_mfma_f32_16x16x32_bf16 v[16:19], v[186:189], v[202:205], v[16:19]
	v_mfma_f32_16x16x32_bf16 v[12:15], v[168:171], v[210:213], v[12:15]
	v_mfma_f32_16x16x32_bf16 v[8:11], v[186:189], v[210:213], v[8:11]
	s_setprio 2
	s_barrier
	v_mfma_f32_16x16x32_bf16 v[4:7], v[168:171], v[218:221], v[4:7]
	v_mfma_f32_16x16x32_bf16 v[0:3], v[186:189], v[218:221], v[0:3]
	s_setprio 0
	s_add_i32 s38, s38, 2
	s_add_u32 s4, s4, 0x100
	s_addc_u32 s5, s5, 0
	s_add_u32 s23, s23, 0x100
	s_addc_u32 s33, s33, 0
	s_cmp_gt_u32 s38, 29
	s_cbranch_scc0 .LBB0_387
	s_and_b64 vcc, exec, s[18:19]
	s_cbranch_vccz .LBB0_390
	s_barrier

; #define PG8_STAGE(bufoff, gbase, voff) do { _Pragma("unroll") for (int _i = 0; _i < 2; ++_i) \
;         __builtin_amdgcn_global_load_lds((const unsigned*)((const char*)(gbase) + (voff)[_i]), (LAS unsigned*)(lds + (bufoff) + ldsw + _i * 8192), 16, 0, 0); } while (0)
; #define PG8_LDA(dst, b, h) do { _Pragma("unroll") for (int m = 0; m < 4; ++m) _Pragma("unroll") for (int k = 0; k < 2; ++k) dst[m][k] = *(const LAS bf16x8*)(lds + PG8_SA(b, h) + aoff + m * 2048 + k * 1024); } while (0)
; #define PG8_LDB(dst, b, h) do { _Pragma("unroll") for (int n = 0; n < 2; ++n) _Pragma("unroll") for (int k = 0; k < 2; ++k) dst[n][k] = *(const LAS bf16x8*)(lds + PG8_SB(b, h) + boff + n * 2048 + k * 1024); } while (0)
; #define PG8_MMA(ai, bj, At, Bt) do { __builtin_amdgcn_s_setprio(1); _Pragma("unroll") for (int m = 0; m < 4; ++m) _Pragma("unroll") for (int n = 0; n < 2; ++n) _Pragma("unroll") for (int k = 0; k < 2; ++k) \
;         acc[ai][bj][m][n] = __builtin_amdgcn_mfma_f32_16x16x32_bf16(Bt[n][k], At[m][k], acc[ai][bj][m][n], 0, 0, 0); __builtin_amdgcn_s_setprio(0); } while (0)
; #define PG8_WAIT_V(n) asm volatile("s_waitcnt vmcnt(" #n ")" ::: "memory")
; #define PG8_WAIT_L(n) asm volatile("s_waitcnt lgkmcnt(" #n ")" ::: "memory")
; #define PG8_BAR __builtin_amdgcn_s_barrier()
; template <class Epi, class Sched, bool ALIGN_EPI = true, bool SP2 = true>
; __device__ __forceinline__ void gemm_phase(LAS unsigned char* lds, const bf16_t* Ag, const bf16_t* Btg, const int K, const int lda, const int ldb, const Sched& S, const Epi& E) {
;     ...
;             const char* a1 = cA + (size_t)(t + 1) * kstep;
;             const char* a2 = last ? nA : cA + (size_t)(t + 2) * kstep; const char* b2 = last ? nB : cB + (size_t)(t + 2) * kstep;
;             const char* a3 = a2 + kstep; const char* b3 = b2 + kstep;
;             if constexpr (SP2) {
;             PG8_LDB(B0, 0, 0); PG8_LDB(B1, 0, 1); PG8_SCHED; PG8_LDA(At, 0, 0); PG8_STAGE(PG8_SA(1, 1), a1 + hstepA, voffA);
;             PG8_WAIT_V(8); PG8_WAIT_L(0); PG8_BAR; PG8_MMA(0, 0, At, B0); PG8_MMA(0, 1, At, B1); PG8_BAR; PG8_SCHED;
;             PG8_LDA(At, 0, 1); PG8_STAGE(PG8_SB(0, 0), b2, voffB); PG8_STAGE(PG8_SB(0, 1), b2 + hstepB, voffB); PG8_STAGE(PG8_SA(0, 0), a2, voffA);
;             PG8_WAIT_V(8); PG8_WAIT_L(0); PG8_BAR; PG8_MMA(1, 0, At, B0); PG8_MMA(1, 1, At, B1); PG8_BAR; PG8_SCHED;
.LBB0_787:
	ds_read_b128 v[108:111], v170
	ds_read_b128 v[112:115], v170 offset:1024
	ds_read_b128 v[154:157], v170 offset:2048
	ds_read_b128 v[158:161], v170 offset:3072
	ds_read_b128 v[162:165], v171
	ds_read_b128 v[180:183], v171 offset:1024
	ds_read_b128 v[184:187], v171 offset:2048
	ds_read_b128 v[188:191], v171 offset:3072
	s_add_u32 s26, s24, 0xfff80080
	s_addc_u32 s27, s25, -1
	s_cmp_eq_u32 s53, 28
	s_cselect_b32 s29, s11, s27
	s_cselect_b32 s28, s13, s26
	s_cselect_b32 s27, s33, s52
	s_cselect_b32 s26, s50, s51
	v_lshl_add_u64 v[174:175], s[24:25], 0, v[146:147]
	s_add_i32 m0, s37, 0xc000
	ds_read_b128 v[192:195], v172
	ds_read_b128 v[196:199], v172 offset:1024
	ds_read_b128 v[200:203], v172 offset:2048
	ds_read_b128 v[204:207], v172 offset:3072
	ds_read_b128 v[208:211], v172 offset:4096
	ds_read_b128 v[212:215], v172 offset:5120
	ds_read_b128 v[216:219], v172 offset:6144
	ds_read_b128 v[220:223], v172 offset:7168
	global_load_lds_dwordx4 v[174:175], off
	v_lshl_add_u64 v[174:175], s[24:25], 0, v[148:149]
	s_add_i32 m0, s37, 0xe000
	s_nop 0
	global_load_lds_dwordx4 v[174:175], off
	s_waitcnt vmcnt(8)
	s_waitcnt lgkmcnt(0)
	s_barrier
	s_setprio 1
	s_waitcnt lgkmcnt(0)
	v_mfma_f32_16x16x32_bf16 v[132:135], v[108:111], v[192:195], v[132:135]
	v_mfma_f32_16x16x32_bf16 v[128:131], v[154:157], v[192:195], v[128:131]
	v_mfma_f32_16x16x32_bf16 v[124:127], v[108:111], v[200:203], v[124:127]
	v_mfma_f32_16x16x32_bf16 v[120:123], v[154:157], v[200:203], v[120:123]
	v_mfma_f32_16x16x32_bf16 v[116:119], v[108:111], v[208:211], v[116:119]
	v_mfma_f32_16x16x32_bf16 v[104:107], v[154:157], v[208:211], v[104:107]
	v_mfma_f32_16x16x32_bf16 v[100:103], v[108:111], v[216:219], v[100:103]
	v_mfma_f32_16x16x32_bf16 v[96:99], v[154:157], v[216:219], v[96:99]
	v_mfma_f32_16x16x32_bf16 v[132:135], v[112:115], v[196:199], v[132:135]
	v_mfma_f32_16x16x32_bf16 v[128:131], v[158:161], v[196:199], v[128:131]
	v_mfma_f32_16x16x32_bf16 v[124:127], v[112:115], v[204:207], v[124:127]
	v_mfma_f32_16x16x32_bf16 v[120:123], v[158:161], v[204:207], v[120:123]
	v_mfma_f32_16x16x32_bf16 v[116:119], v[112:115], v[212:215], v[116:119]
	v_mfma_f32_16x16x32_bf16 v[104:107], v[158:161], v[212:215], v[104:107]
	v_mfma_f32_16x16x32_bf16 v[100:103], v[112:115], v[220:223], v[100:103]
	v_mfma_f32_16x16x32_bf16 v[96:99], v[158:161], v[220:223], v[96:99]
	v_mfma_f32_16x16x32_bf16 v[60:63], v[162:165], v[192:195], v[60:63]
	v_mfma_f32_16x16x32_bf16 v[56:59], v[184:187], v[192:195], v[56:59]
	v_mfma_f32_16x16x32_bf16 v[52:55], v[162:165], v[200:203], v[52:55]
	v_mfma_f32_16x16x32_bf16 v[48:51], v[184:187], v[200:203], v[48:51]
	v_mfma_f32_16x16x32_bf16 v[44:47], v[162:165], v[208:211], v[44:47]
	v_mfma_f32_16x16x32_bf16 v[40:43], v[184:187], v[208:211], v[40:43]
	v_mfma_f32_16x16x32_bf16 v[36:39], v[162:165], v[216:219], v[36:39]
	v_mfma_f32_16x16x32_bf16 v[32:35], v[184:187], v[216:219], v[32:35]
	v_mfma_f32_16x16x32_bf16 v[60:63], v[180:183], v[196:199], v[60:63]
	v_mfma_f32_16x16x32_bf16 v[56:59], v[188:191], v[196:199], v[56:59]
	v_mfma_f32_16x16x32_bf16 v[52:55], v[180:183], v[204:207], v[52:55]
	v_mfma_f32_16x16x32_bf16 v[48:51], v[188:191], v[204:207], v[48:51]
	v_mfma_f32_16x16x32_bf16 v[44:47], v[180:183], v[212:215], v[44:47]
	v_mfma_f32_16x16x32_bf16 v[40:43], v[188:191], v[212:215], v[40:43]
	s_setprio 2
	s_barrier
	v_mfma_f32_16x16x32_bf16 v[36:39], v[180:183], v[220:223], v[36:39]
	v_mfma_f32_16x16x32_bf16 v[32:35], v[188:191], v[220:223], v[32:35]
	s_setprio 0
	s_add_i32 s54, s46, s35
	v_lshl_add_u64 v[174:175], s[26:27], 0, v[138:139]
	s_mov_b32 m0, s54
	ds_read_b128 v[192:195], v172 offset:16384
	ds_read_b128 v[196:199], v172 offset:17408
	ds_read_b128 v[200:203], v172 offset:18432
	ds_read_b128 v[204:207], v172 offset:19456
	ds_read_b128 v[208:211], v172 offset:20480
	ds_read_b128 v[212:215], v172 offset:21504
	ds_read_b128 v[216:219], v172 offset:22528
	ds_read_b128 v[220:223], v172 offset:23552
	global_load_lds_dwordx4 v[174:175], off
	s_add_i32 m0, s54, 0x2000
	s_add_u32 s54, s26, 0x80000
	v_lshl_add_u64 v[224:225], s[26:27], 0, v[142:143]
	s_addc_u32 s55, s27, 0
	s_add_i32 s58, s47, s35
	global_load_lds_dwordx4 v[224:225], off
	v_lshl_add_u64 v[226:227], s[54:55], 0, v[138:139]
	s_mov_b32 m0, s58
	v_lshl_add_u64 v[228:229], s[28:29], 0, v[140:141]
	global_load_lds_dwordx4 v[226:227], off
	v_lshl_add_u64 v[226:227], s[54:55], 0, v[142:143]
	s_add_i32 m0, s58, 0x2000
	s_nop 0
	global_load_lds_dwordx4 v[226:227], off
	v_lshl_add_u64 v[226:227], s[28:29], 0, v[136:137]
	s_mov_b32 m0, s37
	s_nop 0
	global_load_lds_dwordx4 v[226:227], off
	s_mov_b32 m0, s38
	s_nop 0
	global_load_lds_dwordx4 v[228:229], off
	s_waitcnt vmcnt(8)
	s_waitcnt lgkmcnt(0)
	s_barrier
; #define PG8_STAGE(bufoff, gbase, voff) do { _Pragma("unroll") for (int _i = 0; _i < 2; ++_i) \
;         __builtin_amdgcn_global_load_lds((const unsigned*)((const char*)(gbase) + (voff)[_i]), (LAS unsigned*)(lds + (bufoff) + ldsw + _i * 8192), 16, 0, 0); } while (0)
; #define PG8_LDA(dst, b, h) do { _Pragma("unroll") for (int m = 0; m < 4; ++m) _Pragma("unroll") for (int k = 0; k < 2; ++k) dst[m][k] = *(const LAS bf16x8*)(lds + PG8_SA(b, h) + aoff + m * 2048 + k * 1024); } while (0)
; #define PG8_LDB(dst, b, h) do { _Pragma("unroll") for (int n = 0; n < 2; ++n) _Pragma("unroll") for (int k = 0; k < 2; ++k) dst[n][k] = *(const LAS bf16x8*)(lds + PG8_SB(b, h) + boff + n * 2048 + k * 1024); } while (0)
; #define PG8_MMA(ai, bj, At, Bt) do { __builtin_amdgcn_s_setprio(1); _Pragma("unroll") for (int m = 0; m < 4; ++m) _Pragma("unroll") for (int n = 0; n < 2; ++n) _Pragma("unroll") for (int k = 0; k < 2; ++k) \
;         acc[ai][bj][m][n] = __builtin_amdgcn_mfma_f32_16x16x32_bf16(Bt[n][k], At[m][k], acc[ai][bj][m][n], 0, 0, 0); __builtin_amdgcn_s_setprio(0); } while (0)
; #define PG8_WAIT_V(n) asm volatile("s_waitcnt vmcnt(" #n ")" ::: "memory")
; #define PG8_WAIT_L(n) asm volatile("s_waitcnt lgkmcnt(" #n ")" ::: "memory")
; #define PG8_BAR __builtin_amdgcn_s_barrier()
; #define PG8_SCHED __builtin_amdgcn_sched_barrier(0)
; template <class Epi, class Sched, bool ALIGN_EPI = true, bool SP2 = true>
; __device__ __forceinline__ void gemm_phase(LAS unsigned char* lds, const bf16_t* Ag, const bf16_t* Btg, const int K, const int lda, const int ldb, const Sched& S, const Epi& E) {
;     ...
;             PG8_WAIT_V(8); PG8_WAIT_L(0); PG8_BAR; PG8_MMA(1, 0, At, B0); PG8_MMA(1, 1, At, B1); PG8_BAR; PG8_SCHED;
;             PG8_LDB(B0, 1, 0); PG8_LDB(B1, 1, 1); PG8_SCHED; PG8_LDA(At, 1, 0); PG8_STAGE(PG8_SA(0, 1), a2 + hstepA, voffA);
;             PG8_WAIT_V(8); PG8_WAIT_L(0); PG8_BAR; PG8_MMA(0, 0, At, B0); PG8_MMA(0, 1, At, B1); PG8_BAR; PG8_SCHED;
	s_setprio 1
	s_waitcnt lgkmcnt(0)
	v_mfma_f32_16x16x32_bf16 v[92:95], v[108:111], v[192:195], v[92:95]
	v_mfma_f32_16x16x32_bf16 v[88:91], v[154:157], v[192:195], v[88:91]
	v_mfma_f32_16x16x32_bf16 v[84:87], v[108:111], v[200:203], v[84:87]
	v_mfma_f32_16x16x32_bf16 v[80:83], v[154:157], v[200:203], v[80:83]
	v_mfma_f32_16x16x32_bf16 v[76:79], v[108:111], v[208:211], v[76:79]
	v_mfma_f32_16x16x32_bf16 v[72:75], v[154:157], v[208:211], v[72:75]
	v_mfma_f32_16x16x32_bf16 v[68:71], v[108:111], v[216:219], v[68:71]
	v_mfma_f32_16x16x32_bf16 v[64:67], v[154:157], v[216:219], v[64:67]
	v_mfma_f32_16x16x32_bf16 v[92:95], v[112:115], v[196:199], v[92:95]
	v_mfma_f32_16x16x32_bf16 v[88:91], v[158:161], v[196:199], v[88:91]
	v_mfma_f32_16x16x32_bf16 v[84:87], v[112:115], v[204:207], v[84:87]
	v_mfma_f32_16x16x32_bf16 v[80:83], v[158:161], v[204:207], v[80:83]
	v_mfma_f32_16x16x32_bf16 v[76:79], v[112:115], v[212:215], v[76:79]
	v_mfma_f32_16x16x32_bf16 v[72:75], v[158:161], v[212:215], v[72:75]
	v_mfma_f32_16x16x32_bf16 v[68:71], v[112:115], v[220:223], v[68:71]
	v_mfma_f32_16x16x32_bf16 v[64:67], v[158:161], v[220:223], v[64:67]
	v_mfma_f32_16x16x32_bf16 v[28:31], v[162:165], v[192:195], v[28:31]
	v_mfma_f32_16x16x32_bf16 v[24:27], v[184:187], v[192:195], v[24:27]
	v_mfma_f32_16x16x32_bf16 v[20:23], v[162:165], v[200:203], v[20:23]
	v_mfma_f32_16x16x32_bf16 v[16:19], v[184:187], v[200:203], v[16:19]
	v_mfma_f32_16x16x32_bf16 v[12:15], v[162:165], v[208:211], v[12:15]
	v_mfma_f32_16x16x32_bf16 v[8:11], v[184:187], v[208:211], v[8:11]
	v_mfma_f32_16x16x32_bf16 v[4:7], v[162:165], v[216:219], v[4:7]
	v_mfma_f32_16x16x32_bf16 v[0:3], v[184:187], v[216:219], v[0:3]
	v_mfma_f32_16x16x32_bf16 v[28:31], v[180:183], v[196:199], v[28:31]
	v_mfma_f32_16x16x32_bf16 v[24:27], v[188:191], v[196:199], v[24:27]
	v_mfma_f32_16x16x32_bf16 v[20:23], v[180:183], v[204:207], v[20:23]
	v_mfma_f32_16x16x32_bf16 v[16:19], v[188:191], v[204:207], v[16:19]
	v_mfma_f32_16x16x32_bf16 v[12:15], v[180:183], v[212:215], v[12:15]
	v_mfma_f32_16x16x32_bf16 v[8:11], v[188:191], v[212:215], v[8:11]
	s_setprio 2
	s_barrier
	v_mfma_f32_16x16x32_bf16 v[4:7], v[180:183], v[220:223], v[4:7]
	v_mfma_f32_16x16x32_bf16 v[0:3], v[188:191], v[220:223], v[0:3]
	s_setprio 0
	s_add_i32 s54, 0, 0x18000
	s_add_i32 s55, 0, 0x1c000
	v_add_u32_e32 v158, s54, v168
	v_add_u32_e32 v173, s55, v168
	ds_read_b128 v[108:111], v158
	ds_read_b128 v[112:115], v158 offset:1024
	ds_read_b128 v[154:157], v158 offset:2048
	ds_read_b128 v[158:161], v158 offset:3072
	ds_read_b128 v[162:165], v173
	ds_read_b128 v[180:183], v173 offset:1024
	ds_read_b128 v[184:187], v173 offset:2048
	ds_read_b128 v[188:191], v173 offset:3072
	s_add_u32 s28, s28, 0x80000
	s_addc_u32 s29, s29, 0
	s_mov_b32 m0, s39
	v_lshl_add_u64 v[230:231], s[28:29], 0, v[136:137]
	ds_read_b128 v[192:195], v172 offset:32768
	ds_read_b128 v[196:199], v172 offset:33792
	ds_read_b128 v[200:203], v172 offset:34816
	ds_read_b128 v[204:207], v172 offset:35840
	ds_read_b128 v[208:211], v172 offset:36864
	ds_read_b128 v[212:215], v172 offset:37888
	ds_read_b128 v[216:219], v172 offset:38912
	ds_read_b128 v[220:223], v172 offset:39936
	global_load_lds_dwordx4 v[230:231], off
	v_lshl_add_u64 v[230:231], s[28:29], 0, v[140:141]
	s_mov_b32 m0, s40
	s_nop 0
	global_load_lds_dwordx4 v[230:231], off
	s_waitcnt vmcnt(8)
	s_waitcnt lgkmcnt(0)
	s_barrier
	s_setprio 1
	s_waitcnt lgkmcnt(0)
	v_mfma_f32_16x16x32_bf16 v[132:135], v[108:111], v[192:195], v[132:135]
	v_mfma_f32_16x16x32_bf16 v[128:131], v[154:157], v[192:195], v[128:131]
	v_mfma_f32_16x16x32_bf16 v[124:127], v[108:111], v[200:203], v[124:127]
	v_mfma_f32_16x16x32_bf16 v[120:123], v[154:157], v[200:203], v[120:123]
	v_mfma_f32_16x16x32_bf16 v[116:119], v[108:111], v[208:211], v[116:119]
	v_mfma_f32_16x16x32_bf16 v[104:107], v[154:157], v[208:211], v[104:107]
	v_mfma_f32_16x16x32_bf16 v[100:103], v[108:111], v[216:219], v[100:103]
	v_mfma_f32_16x16x32_bf16 v[96:99], v[154:157], v[216:219], v[96:99]
	v_mfma_f32_16x16x32_bf16 v[132:135], v[112:115], v[196:199], v[132:135]
	v_mfma_f32_16x16x32_bf16 v[128:131], v[158:161], v[196:199], v[128:131]
	v_mfma_f32_16x16x32_bf16 v[124:127], v[112:115], v[204:207], v[124:127]
	v_mfma_f32_16x16x32_bf16 v[120:123], v[158:161], v[204:207], v[120:123]
	v_mfma_f32_16x16x32_bf16 v[116:119], v[112:115], v[212:215], v[116:119]
	v_mfma_f32_16x16x32_bf16 v[104:107], v[158:161], v[212:215], v[104:107]
	v_mfma_f32_16x16x32_bf16 v[100:103], v[112:115], v[220:223], v[100:103]
	v_mfma_f32_16x16x32_bf16 v[96:99], v[158:161], v[220:223], v[96:99]
	v_mfma_f32_16x16x32_bf16 v[60:63], v[162:165], v[192:195], v[60:63]
	v_mfma_f32_16x16x32_bf16 v[56:59], v[184:187], v[192:195], v[56:59]
	v_mfma_f32_16x16x32_bf16 v[52:55], v[162:165], v[200:203], v[52:55]
	v_mfma_f32_16x16x32_bf16 v[48:51], v[184:187], v[200:203], v[48:51]
	v_mfma_f32_16x16x32_bf16 v[44:47], v[162:165], v[208:211], v[44:47]
	v_mfma_f32_16x16x32_bf16 v[40:43], v[184:187], v[208:211], v[40:43]
	v_mfma_f32_16x16x32_bf16 v[36:39], v[162:165], v[216:219], v[36:39]
	v_mfma_f32_16x16x32_bf16 v[32:35], v[184:187], v[216:219], v[32:35]
	v_mfma_f32_16x16x32_bf16 v[60:63], v[180:183], v[196:199], v[60:63]
	v_mfma_f32_16x16x32_bf16 v[56:59], v[188:191], v[196:199], v[56:59]
	v_mfma_f32_16x16x32_bf16 v[52:55], v[180:183], v[204:207], v[52:55]
	v_mfma_f32_16x16x32_bf16 v[48:51], v[188:191], v[204:207], v[48:51]
	v_mfma_f32_16x16x32_bf16 v[44:47], v[180:183], v[212:215], v[44:47]
	v_mfma_f32_16x16x32_bf16 v[40:43], v[188:191], v[212:215], v[40:43]
	s_setprio 2
	s_barrier
; #define PG8_STAGE(bufoff, gbase, voff) do { _Pragma("unroll") for (int _i = 0; _i < 2; ++_i) \
;         __builtin_amdgcn_global_load_lds((const unsigned*)((const char*)(gbase) + (voff)[_i]), (LAS unsigned*)(lds + (bufoff) + ldsw + _i * 8192), 16, 0, 0); } while (0)
; #define PG8_LDA(dst, b, h) do { _Pragma("unroll") for (int m = 0; m < 4; ++m) _Pragma("unroll") for (int k = 0; k < 2; ++k) dst[m][k] = *(const LAS bf16x8*)(lds + PG8_SA(b, h) + aoff + m * 2048 + k * 1024); } while (0)
; #define PG8_LDB(dst, b, h) do { _Pragma("unroll") for (int n = 0; n < 2; ++n) _Pragma("unroll") for (int k = 0; k < 2; ++k) dst[n][k] = *(const LAS bf16x8*)(lds + PG8_SB(b, h) + boff + n * 2048 + k * 1024); } while (0)
; template <class Epi, class Sched, bool ALIGN_EPI = true, bool SP2 = true>
; __device__ __forceinline__ void gemm_phase(LAS unsigned char* lds, const bf16_t* Ag, const bf16_t* Btg, const int K, const int lda, const int ldb, const Sched& S, const Epi& E) {
;     ...
;         for (int t = 0; t < nt; t += 2) {
;             const bool last = (t == nt - 2);
;             const char* a1 = cA + (size_t)(t + 1) * kstep;
;             const char* a2 = last ? nA : cA + (size_t)(t + 2) * kstep; const char* b2 = last ? nB : cB + (size_t)(t + 2) * kstep;
;             const char* a3 = a2 + kstep; const char* b3 = b2 + kstep;
;             if constexpr (SP2) {
;             PG8_LDB(B0, 0, 0); PG8_LDB(B1, 0, 1); PG8_SCHED; PG8_LDA(At, 0, 0); PG8_STAGE(PG8_SA(1, 1), a1 + hstepA, voffA);
;             PG8_WAIT_V(8); PG8_WAIT_L(0); PG8_BAR; PG8_MMA(0, 0, At, B0); PG8_MMA(0, 1, At, B1); PG8_BAR; PG8_SCHED;
;             PG8_LDA(At, 0, 1); PG8_STAGE(PG8_SB(0, 0), b2, voffB); PG8_STAGE(PG8_SB(0, 1), b2 + hstepB, voffB); PG8_STAGE(PG8_SA(0, 0), a2, voffA);
;             PG8_WAIT_V(8); PG8_WAIT_L(0); PG8_BAR; PG8_MMA(1, 0, At, B0); PG8_MMA(1, 1, At, B1); PG8_BAR; PG8_SCHED;
;             PG8_LDB(B0, 1, 0); PG8_LDB(B1, 1, 1); PG8_SCHED; PG8_LDA(At, 1, 0); PG8_STAGE(PG8_SA(0, 1), a2 + hstepA, voffA);
;             PG8_WAIT_V(8); PG8_WAIT_L(0); PG8_BAR; PG8_MMA(0, 0, At, B0); PG8_MMA(0, 1, At, B1); PG8_BAR; PG8_SCHED;
;             PG8_LDA(At, 1, 1); PG8_STAGE(PG8_SB(1, 0), b3, voffB); PG8_STAGE(PG8_SB(1, 1), b3 + hstepB, voffB); PG8_STAGE(PG8_SA(1, 0), a3, voffA);
;             PG8_WAIT_V(8); PG8_WAIT_L(0); PG8_BAR; PG8_MMA(1, 0, At, B0); PG8_MMA(1, 1, At, B1); PG8_BAR; PG8_SCHED;
	v_mfma_f32_16x16x32_bf16 v[36:39], v[180:183], v[220:223], v[36:39]
	v_mfma_f32_16x16x32_bf16 v[32:35], v[188:191], v[220:223], v[32:35]
	s_setprio 0
	s_add_i32 s28, s54, s35
	v_lshl_add_u64 v[174:175], v[174:175], 0, s[6:7]
	s_mov_b32 m0, s28
	ds_read_b128 v[192:195], v172 offset:49152
	ds_read_b128 v[196:199], v172 offset:50176
	ds_read_b128 v[200:203], v172 offset:51200
	ds_read_b128 v[204:207], v172 offset:52224
	ds_read_b128 v[208:211], v172 offset:53248
	ds_read_b128 v[212:215], v172 offset:54272
	ds_read_b128 v[216:219], v172 offset:55296
	ds_read_b128 v[220:223], v172 offset:56320
	global_load_lds_dwordx4 v[174:175], off
	s_add_i32 m0, s28, 0x2000
	s_add_u32 s26, s26, 0x80080
	v_lshl_add_u64 v[174:175], v[224:225], 0, s[6:7]
	s_addc_u32 s27, s27, 0
	s_add_i32 s28, s55, s35
	global_load_lds_dwordx4 v[174:175], off
	v_lshl_add_u64 v[174:175], s[26:27], 0, v[138:139]
	s_mov_b32 m0, s28
	s_nop 0
	global_load_lds_dwordx4 v[174:175], off
	v_lshl_add_u64 v[174:175], s[26:27], 0, v[142:143]
	s_add_i32 m0, s28, 0x2000
	s_nop 0
	global_load_lds_dwordx4 v[174:175], off
	v_lshl_add_u64 v[174:175], v[226:227], 0, s[6:7]
	s_mov_b32 m0, s42
	s_nop 0
	global_load_lds_dwordx4 v[174:175], off
	v_lshl_add_u64 v[174:175], v[228:229], 0, s[6:7]
	s_mov_b32 m0, s43
	s_nop 0
	global_load_lds_dwordx4 v[174:175], off
	s_waitcnt vmcnt(8)
	s_waitcnt lgkmcnt(0)
	s_barrier
	s_setprio 1
	s_waitcnt lgkmcnt(0)
	v_mfma_f32_16x16x32_bf16 v[92:95], v[108:111], v[192:195], v[92:95]
	v_mfma_f32_16x16x32_bf16 v[88:91], v[154:157], v[192:195], v[88:91]
	v_mfma_f32_16x16x32_bf16 v[84:87], v[108:111], v[200:203], v[84:87]
	v_mfma_f32_16x16x32_bf16 v[80:83], v[154:157], v[200:203], v[80:83]
	v_mfma_f32_16x16x32_bf16 v[76:79], v[108:111], v[208:211], v[76:79]
	v_mfma_f32_16x16x32_bf16 v[72:75], v[154:157], v[208:211], v[72:75]
	v_mfma_f32_16x16x32_bf16 v[68:71], v[108:111], v[216:219], v[68:71]
	v_mfma_f32_16x16x32_bf16 v[64:67], v[154:157], v[216:219], v[64:67]
	v_mfma_f32_16x16x32_bf16 v[92:95], v[112:115], v[196:199], v[92:95]
	v_mfma_f32_16x16x32_bf16 v[88:91], v[158:161], v[196:199], v[88:91]
	v_mfma_f32_16x16x32_bf16 v[84:87], v[112:115], v[204:207], v[84:87]
	v_mfma_f32_16x16x32_bf16 v[80:83], v[158:161], v[204:207], v[80:83]
	v_mfma_f32_16x16x32_bf16 v[76:79], v[112:115], v[212:215], v[76:79]
	v_mfma_f32_16x16x32_bf16 v[72:75], v[158:161], v[212:215], v[72:75]
	v_mfma_f32_16x16x32_bf16 v[68:71], v[112:115], v[220:223], v[68:71]
	v_mfma_f32_16x16x32_bf16 v[64:67], v[158:161], v[220:223], v[64:67]
	v_mfma_f32_16x16x32_bf16 v[28:31], v[162:165], v[192:195], v[28:31]
	v_mfma_f32_16x16x32_bf16 v[24:27], v[184:187], v[192:195], v[24:27]
	v_mfma_f32_16x16x32_bf16 v[20:23], v[162:165], v[200:203], v[20:23]
	v_mfma_f32_16x16x32_bf16 v[16:19], v[184:187], v[200:203], v[16:19]
	v_mfma_f32_16x16x32_bf16 v[12:15], v[162:165], v[208:211], v[12:15]
	v_mfma_f32_16x16x32_bf16 v[8:11], v[184:187], v[208:211], v[8:11]
	v_mfma_f32_16x16x32_bf16 v[4:7], v[162:165], v[216:219], v[4:7]
	v_mfma_f32_16x16x32_bf16 v[0:3], v[184:187], v[216:219], v[0:3]
	v_mfma_f32_16x16x32_bf16 v[28:31], v[180:183], v[196:199], v[28:31]
	v_mfma_f32_16x16x32_bf16 v[24:27], v[188:191], v[196:199], v[24:27]
	v_mfma_f32_16x16x32_bf16 v[20:23], v[180:183], v[204:207], v[20:23]
	v_mfma_f32_16x16x32_bf16 v[16:19], v[188:191], v[204:207], v[16:19]
	v_mfma_f32_16x16x32_bf16 v[12:15], v[180:183], v[212:215], v[12:15]
	v_mfma_f32_16x16x32_bf16 v[8:11], v[188:191], v[212:215], v[8:11]
	s_setprio 2
	s_barrier
	v_mfma_f32_16x16x32_bf16 v[4:7], v[180:183], v[220:223], v[4:7]
	v_mfma_f32_16x16x32_bf16 v[0:3], v[188:191], v[220:223], v[0:3]
	s_setprio 0
	s_add_i32 s53, s53, 2
	s_add_u32 s24, s24, 0x100
	s_addc_u32 s25, s25, 0
	s_add_u32 s51, s51, 0x100
	s_addc_u32 s52, s52, 0
	s_cmp_gt_u32 s53, 29
	s_cbranch_scc0 .LBB0_787
	s_and_b64 vcc, exec, s[8:9]
	s_cbranch_vccz .LBB0_790
	s_barrier

; #define PG8_STAGE(bufoff, gbase, voff) do { _Pragma("unroll") for (int _i = 0; _i < 2; ++_i) \
;         __builtin_amdgcn_global_load_lds((const unsigned*)((const char*)(gbase) + (voff)[_i]), (LAS unsigned*)(lds + (bufoff) + ldsw + _i * 8192), 16, 0, 0); } while (0)
; #define PG8_LDA(dst, b, h) do { _Pragma("unroll") for (int m = 0; m < 4; ++m) _Pragma("unroll") for (int k = 0; k < 2; ++k) dst[m][k] = *(const LAS bf16x8*)(lds + PG8_SA(b, h) + aoff + m * 2048 + k * 1024); } while (0)
; #define PG8_LDB(dst, b, h) do { _Pragma("unroll") for (int n = 0; n < 2; ++n) _Pragma("unroll") for (int k = 0; k < 2; ++k) dst[n][k] = *(const LAS bf16x8*)(lds + PG8_SB(b, h) + boff + n * 2048 + k * 1024); } while (0)
; #define PG8_MMA(ai, bj, At, Bt) do { __builtin_amdgcn_s_setprio(1); _Pragma("unroll") for (int m = 0; m < 4; ++m) _Pragma("unroll") for (int n = 0; n < 2; ++n) _Pragma("unroll") for (int k = 0; k < 2; ++k) \
;         acc[ai][bj][m][n] = __builtin_amdgcn_mfma_f32_16x16x32_bf16(Bt[n][k], At[m][k], acc[ai][bj][m][n], 0, 0, 0); __builtin_amdgcn_s_setprio(0); } while (0)
; #define PG8_WAIT_V(n) asm volatile("s_waitcnt vmcnt(" #n ")" ::: "memory")
; #define PG8_WAIT_L(n) asm volatile("s_waitcnt lgkmcnt(" #n ")" ::: "memory")
; #define PG8_BAR __builtin_amdgcn_s_barrier()
; #define PG8_SCHED __builtin_amdgcn_sched_barrier(0)
; template <class Epi, class Sched, bool ALIGN_EPI = true, bool SP2 = true>
; __device__ __forceinline__ void gemm_phase(LAS unsigned char* lds, const bf16_t* Ag, const bf16_t* Btg, const int K, const int lda, const int ldb, const Sched& S, const Epi& E) {
;     ...
;         for (int t = 0; t < nt; t += 2) {
;             const bool last = (t == nt - 2);
;             const char* a1 = cA + (size_t)(t + 1) * kstep;
;             const char* a2 = last ? nA : cA + (size_t)(t + 2) * kstep; const char* b2 = last ? nB : cB + (size_t)(t + 2) * kstep;
;             const char* a3 = a2 + kstep; const char* b3 = b2 + kstep;
;             if constexpr (SP2) {
;             PG8_LDB(B0, 0, 0); PG8_LDB(B1, 0, 1); PG8_SCHED; PG8_LDA(At, 0, 0); PG8_STAGE(PG8_SA(1, 1), a1 + hstepA, voffA);
;             PG8_WAIT_V(8); PG8_WAIT_L(0); PG8_BAR; PG8_MMA(0, 0, At, B0); PG8_MMA(0, 1, At, B1); PG8_BAR; PG8_SCHED;
;             PG8_LDA(At, 0, 1); PG8_STAGE(PG8_SB(0, 0), b2, voffB); PG8_STAGE(PG8_SB(0, 1), b2 + hstepB, voffB); PG8_STAGE(PG8_SA(0, 0), a2, voffA);
.LBB0_866:
	ds_read_b128 v[146:149], v159
	ds_read_b128 v[162:165], v159 offset:1024
	ds_read_b128 v[168:171], v159 offset:2048
	ds_read_b128 v[172:175], v159 offset:3072
	ds_read_b128 v[180:183], v160
	ds_read_b128 v[184:187], v160 offset:1024
	ds_read_b128 v[188:191], v160 offset:2048
	ds_read_b128 v[192:195], v160 offset:3072
	s_add_u32 s28, s26, 0xfff80080
	s_addc_u32 s29, s27, -1
	s_cmp_eq_u32 s53, 12
	s_cselect_b32 s31, s13, s29
	s_cselect_b32 s30, s15, s28
	s_cselect_b32 s29, s47, s52
	s_cselect_b32 s28, s50, s51
	v_lshl_add_u64 v[228:229], s[26:27], 0, v[138:139]
	s_add_i32 m0, s35, 0xc000
	ds_read_b128 v[196:199], v161
	ds_read_b128 v[200:203], v161 offset:1024
	ds_read_b128 v[204:207], v161 offset:2048
	ds_read_b128 v[208:211], v161 offset:3072
	ds_read_b128 v[212:215], v161 offset:4096
	ds_read_b128 v[216:219], v161 offset:5120
	ds_read_b128 v[220:223], v161 offset:6144
	ds_read_b128 v[224:227], v161 offset:7168
	global_load_lds_dwordx4 v[228:229], off
	v_lshl_add_u64 v[228:229], s[26:27], 0, v[140:141]
	s_add_i32 m0, s35, 0xe000
	s_nop 0
	global_load_lds_dwordx4 v[228:229], off
	s_waitcnt vmcnt(8)
	s_waitcnt lgkmcnt(0)
	s_barrier
	s_setprio 1
	s_waitcnt lgkmcnt(0)
	v_mfma_f32_16x16x32_bf16 v[124:127], v[146:149], v[196:199], v[124:127]
	v_mfma_f32_16x16x32_bf16 v[120:123], v[168:171], v[196:199], v[120:123]
	v_mfma_f32_16x16x32_bf16 v[108:111], v[146:149], v[204:207], v[108:111]
	v_mfma_f32_16x16x32_bf16 v[104:107], v[168:171], v[204:207], v[104:107]
	v_mfma_f32_16x16x32_bf16 v[92:95], v[146:149], v[212:215], v[92:95]
	v_mfma_f32_16x16x32_bf16 v[88:91], v[168:171], v[212:215], v[88:91]
	v_mfma_f32_16x16x32_bf16 v[76:79], v[146:149], v[220:223], v[76:79]
	v_mfma_f32_16x16x32_bf16 v[72:75], v[168:171], v[220:223], v[72:75]
	v_mfma_f32_16x16x32_bf16 v[124:127], v[162:165], v[200:203], v[124:127]
	v_mfma_f32_16x16x32_bf16 v[120:123], v[172:175], v[200:203], v[120:123]
	v_mfma_f32_16x16x32_bf16 v[108:111], v[162:165], v[208:211], v[108:111]
	v_mfma_f32_16x16x32_bf16 v[104:107], v[172:175], v[208:211], v[104:107]
	v_mfma_f32_16x16x32_bf16 v[92:95], v[162:165], v[216:219], v[92:95]
	v_mfma_f32_16x16x32_bf16 v[88:91], v[172:175], v[216:219], v[88:91]
	v_mfma_f32_16x16x32_bf16 v[76:79], v[162:165], v[224:227], v[76:79]
	v_mfma_f32_16x16x32_bf16 v[72:75], v[172:175], v[224:227], v[72:75]
	v_mfma_f32_16x16x32_bf16 v[116:119], v[180:183], v[196:199], v[116:119]
	v_mfma_f32_16x16x32_bf16 v[112:115], v[188:191], v[196:199], v[112:115]
	v_mfma_f32_16x16x32_bf16 v[100:103], v[180:183], v[204:207], v[100:103]
	v_mfma_f32_16x16x32_bf16 v[96:99], v[188:191], v[204:207], v[96:99]
	v_mfma_f32_16x16x32_bf16 v[84:87], v[180:183], v[212:215], v[84:87]
	v_mfma_f32_16x16x32_bf16 v[80:83], v[188:191], v[212:215], v[80:83]
	v_mfma_f32_16x16x32_bf16 v[68:71], v[180:183], v[220:223], v[68:71]
	v_mfma_f32_16x16x32_bf16 v[64:67], v[188:191], v[220:223], v[64:67]
	v_mfma_f32_16x16x32_bf16 v[116:119], v[184:187], v[200:203], v[116:119]
	v_mfma_f32_16x16x32_bf16 v[112:115], v[192:195], v[200:203], v[112:115]
	v_mfma_f32_16x16x32_bf16 v[100:103], v[184:187], v[208:211], v[100:103]
	v_mfma_f32_16x16x32_bf16 v[96:99], v[192:195], v[208:211], v[96:99]
	v_mfma_f32_16x16x32_bf16 v[84:87], v[184:187], v[216:219], v[84:87]
	v_mfma_f32_16x16x32_bf16 v[80:83], v[192:195], v[216:219], v[80:83]
	s_setprio 2
	s_barrier
	v_mfma_f32_16x16x32_bf16 v[68:71], v[184:187], v[224:227], v[68:71]
	v_mfma_f32_16x16x32_bf16 v[64:67], v[192:195], v[224:227], v[64:67]
	s_setprio 0
	s_add_i32 s54, s45, s34
	v_lshl_add_u64 v[228:229], s[28:29], 0, v[130:131]
	s_mov_b32 m0, s54
	ds_read_b128 v[196:199], v161 offset:16384
	ds_read_b128 v[200:203], v161 offset:17408
	ds_read_b128 v[204:207], v161 offset:18432
	ds_read_b128 v[208:211], v161 offset:19456
	ds_read_b128 v[212:215], v161 offset:20480
	ds_read_b128 v[216:219], v161 offset:21504
	ds_read_b128 v[220:223], v161 offset:22528
	ds_read_b128 v[224:227], v161 offset:23552
	global_load_lds_dwordx4 v[228:229], off
	s_add_i32 m0, s54, 0x2000
	s_add_u32 s54, s28, 0x80000
	v_lshl_add_u64 v[230:231], s[28:29], 0, v[134:135]
	s_addc_u32 s55, s29, 0
	s_add_i32 s58, s46, s34
	global_load_lds_dwordx4 v[230:231], off
	v_lshl_add_u64 v[232:233], s[54:55], 0, v[130:131]
	s_mov_b32 m0, s58
	v_lshl_add_u64 v[234:235], s[30:31], 0, v[132:133]
	global_load_lds_dwordx4 v[232:233], off
	v_lshl_add_u64 v[232:233], s[54:55], 0, v[134:135]
	s_add_i32 m0, s58, 0x2000
	s_nop 0
	global_load_lds_dwordx4 v[232:233], off
	v_lshl_add_u64 v[232:233], s[30:31], 0, v[128:129]
	s_mov_b32 m0, s35
	s_nop 0
	global_load_lds_dwordx4 v[232:233], off
	s_mov_b32 m0, s37
	s_nop 0
	global_load_lds_dwordx4 v[234:235], off
	s_waitcnt vmcnt(8)
	s_waitcnt lgkmcnt(0)
	s_barrier
; #define PG8_STAGE(bufoff, gbase, voff) do { _Pragma("unroll") for (int _i = 0; _i < 2; ++_i) \
;         __builtin_amdgcn_global_load_lds((const unsigned*)((const char*)(gbase) + (voff)[_i]), (LAS unsigned*)(lds + (bufoff) + ldsw + _i * 8192), 16, 0, 0); } while (0)
; #define PG8_LDA(dst, b, h) do { _Pragma("unroll") for (int m = 0; m < 4; ++m) _Pragma("unroll") for (int k = 0; k < 2; ++k) dst[m][k] = *(const LAS bf16x8*)(lds + PG8_SA(b, h) + aoff + m * 2048 + k * 1024); } while (0)
; #define PG8_LDB(dst, b, h) do { _Pragma("unroll") for (int n = 0; n < 2; ++n) _Pragma("unroll") for (int k = 0; k < 2; ++k) dst[n][k] = *(const LAS bf16x8*)(lds + PG8_SB(b, h) + boff + n * 2048 + k * 1024); } while (0)
; #define PG8_MMA(ai, bj, At, Bt) do { __builtin_amdgcn_s_setprio(1); _Pragma("unroll") for (int m = 0; m < 4; ++m) _Pragma("unroll") for (int n = 0; n < 2; ++n) _Pragma("unroll") for (int k = 0; k < 2; ++k) \
;         acc[ai][bj][m][n] = __builtin_amdgcn_mfma_f32_16x16x32_bf16(Bt[n][k], At[m][k], acc[ai][bj][m][n], 0, 0, 0); __builtin_amdgcn_s_setprio(0); } while (0)
; #define PG8_WAIT_V(n) asm volatile("s_waitcnt vmcnt(" #n ")" ::: "memory")
; #define PG8_WAIT_L(n) asm volatile("s_waitcnt lgkmcnt(" #n ")" ::: "memory")
; #define PG8_BAR __builtin_amdgcn_s_barrier()
; #define PG8_SCHED __builtin_amdgcn_sched_barrier(0)
; template <class Epi, class Sched, bool ALIGN_EPI = true, bool SP2 = true>
; __device__ __forceinline__ void gemm_phase(LAS unsigned char* lds, const bf16_t* Ag, const bf16_t* Btg, const int K, const int lda, const int ldb, const Sched& S, const Epi& E) {
;     ...
;             PG8_WAIT_V(8); PG8_WAIT_L(0); PG8_BAR; PG8_MMA(1, 0, At, B0); PG8_MMA(1, 1, At, B1); PG8_BAR; PG8_SCHED;
;             PG8_LDB(B0, 1, 0); PG8_LDB(B1, 1, 1); PG8_SCHED; PG8_LDA(At, 1, 0); PG8_STAGE(PG8_SA(0, 1), a2 + hstepA, voffA);
;             PG8_WAIT_V(8); PG8_WAIT_L(0); PG8_BAR; PG8_MMA(0, 0, At, B0); PG8_MMA(0, 1, At, B1); PG8_BAR; PG8_SCHED;
	s_setprio 1
	s_waitcnt lgkmcnt(0)
	v_mfma_f32_16x16x32_bf16 v[60:63], v[146:149], v[196:199], v[60:63]
	v_mfma_f32_16x16x32_bf16 v[56:59], v[168:171], v[196:199], v[56:59]
	v_mfma_f32_16x16x32_bf16 v[44:47], v[146:149], v[204:207], v[44:47]
	v_mfma_f32_16x16x32_bf16 v[40:43], v[168:171], v[204:207], v[40:43]
	v_mfma_f32_16x16x32_bf16 v[28:31], v[146:149], v[212:215], v[28:31]
	v_mfma_f32_16x16x32_bf16 v[24:27], v[168:171], v[212:215], v[24:27]
	v_mfma_f32_16x16x32_bf16 v[12:15], v[146:149], v[220:223], v[12:15]
	v_mfma_f32_16x16x32_bf16 v[8:11], v[168:171], v[220:223], v[8:11]
	v_mfma_f32_16x16x32_bf16 v[60:63], v[162:165], v[200:203], v[60:63]
	v_mfma_f32_16x16x32_bf16 v[56:59], v[172:175], v[200:203], v[56:59]
	v_mfma_f32_16x16x32_bf16 v[44:47], v[162:165], v[208:211], v[44:47]
	v_mfma_f32_16x16x32_bf16 v[40:43], v[172:175], v[208:211], v[40:43]
	v_mfma_f32_16x16x32_bf16 v[28:31], v[162:165], v[216:219], v[28:31]
	v_mfma_f32_16x16x32_bf16 v[24:27], v[172:175], v[216:219], v[24:27]
	v_mfma_f32_16x16x32_bf16 v[12:15], v[162:165], v[224:227], v[12:15]
	v_mfma_f32_16x16x32_bf16 v[8:11], v[172:175], v[224:227], v[8:11]
	v_mfma_f32_16x16x32_bf16 v[52:55], v[180:183], v[196:199], v[52:55]
	v_mfma_f32_16x16x32_bf16 v[48:51], v[188:191], v[196:199], v[48:51]
	v_mfma_f32_16x16x32_bf16 v[36:39], v[180:183], v[204:207], v[36:39]
	v_mfma_f32_16x16x32_bf16 v[32:35], v[188:191], v[204:207], v[32:35]
	v_mfma_f32_16x16x32_bf16 v[20:23], v[180:183], v[212:215], v[20:23]
	v_mfma_f32_16x16x32_bf16 v[16:19], v[188:191], v[212:215], v[16:19]
	v_mfma_f32_16x16x32_bf16 v[4:7], v[180:183], v[220:223], v[4:7]
	v_mfma_f32_16x16x32_bf16 v[0:3], v[188:191], v[220:223], v[0:3]
	v_mfma_f32_16x16x32_bf16 v[52:55], v[184:187], v[200:203], v[52:55]
	v_mfma_f32_16x16x32_bf16 v[48:51], v[192:195], v[200:203], v[48:51]
	v_mfma_f32_16x16x32_bf16 v[36:39], v[184:187], v[208:211], v[36:39]
	v_mfma_f32_16x16x32_bf16 v[32:35], v[192:195], v[208:211], v[32:35]
	v_mfma_f32_16x16x32_bf16 v[20:23], v[184:187], v[216:219], v[20:23]
	v_mfma_f32_16x16x32_bf16 v[16:19], v[192:195], v[216:219], v[16:19]
	s_setprio 2
	s_barrier
	v_mfma_f32_16x16x32_bf16 v[4:7], v[184:187], v[224:227], v[4:7]
	v_mfma_f32_16x16x32_bf16 v[0:3], v[192:195], v[224:227], v[0:3]
	s_setprio 0
	s_add_i32 s54, 0, 0x18000
	s_add_i32 s55, 0, 0x1c000
	v_add_u32_e32 v172, s54, v157
	v_add_u32_e32 v192, s55, v157
	ds_read_b128 v[146:149], v172
	ds_read_b128 v[162:165], v172 offset:1024
	ds_read_b128 v[168:171], v172 offset:2048
	ds_read_b128 v[172:175], v172 offset:3072
	ds_read_b128 v[180:183], v192
	ds_read_b128 v[184:187], v192 offset:1024
	ds_read_b128 v[188:191], v192 offset:2048
	ds_read_b128 v[192:195], v192 offset:3072
	s_add_u32 s30, s30, 0x80000
	s_addc_u32 s31, s31, 0
	s_mov_b32 m0, s38
	v_lshl_add_u64 v[236:237], s[30:31], 0, v[128:129]
	ds_read_b128 v[196:199], v161 offset:32768
	ds_read_b128 v[200:203], v161 offset:33792
	ds_read_b128 v[204:207], v161 offset:34816
	ds_read_b128 v[208:211], v161 offset:35840
	ds_read_b128 v[212:215], v161 offset:36864
	ds_read_b128 v[216:219], v161 offset:37888
	ds_read_b128 v[220:223], v161 offset:38912
	ds_read_b128 v[224:227], v161 offset:39936
	global_load_lds_dwordx4 v[236:237], off
	v_lshl_add_u64 v[236:237], s[30:31], 0, v[132:133]
	s_mov_b32 m0, s39
	s_nop 0
	global_load_lds_dwordx4 v[236:237], off
	s_waitcnt vmcnt(8)
	s_waitcnt lgkmcnt(0)
	s_barrier
	s_setprio 1
	s_waitcnt lgkmcnt(0)
	v_mfma_f32_16x16x32_bf16 v[124:127], v[146:149], v[196:199], v[124:127]
	v_mfma_f32_16x16x32_bf16 v[120:123], v[168:171], v[196:199], v[120:123]
	v_mfma_f32_16x16x32_bf16 v[108:111], v[146:149], v[204:207], v[108:111]
	v_mfma_f32_16x16x32_bf16 v[104:107], v[168:171], v[204:207], v[104:107]
	v_mfma_f32_16x16x32_bf16 v[92:95], v[146:149], v[212:215], v[92:95]
	v_mfma_f32_16x16x32_bf16 v[88:91], v[168:171], v[212:215], v[88:91]
	v_mfma_f32_16x16x32_bf16 v[76:79], v[146:149], v[220:223], v[76:79]
	v_mfma_f32_16x16x32_bf16 v[72:75], v[168:171], v[220:223], v[72:75]
	v_mfma_f32_16x16x32_bf16 v[124:127], v[162:165], v[200:203], v[124:127]
	v_mfma_f32_16x16x32_bf16 v[120:123], v[172:175], v[200:203], v[120:123]
	v_mfma_f32_16x16x32_bf16 v[108:111], v[162:165], v[208:211], v[108:111]
	v_mfma_f32_16x16x32_bf16 v[104:107], v[172:175], v[208:211], v[104:107]
	v_mfma_f32_16x16x32_bf16 v[92:95], v[162:165], v[216:219], v[92:95]
	v_mfma_f32_16x16x32_bf16 v[88:91], v[172:175], v[216:219], v[88:91]
	v_mfma_f32_16x16x32_bf16 v[76:79], v[162:165], v[224:227], v[76:79]
	v_mfma_f32_16x16x32_bf16 v[72:75], v[172:175], v[224:227], v[72:75]
	v_mfma_f32_16x16x32_bf16 v[116:119], v[180:183], v[196:199], v[116:119]
	v_mfma_f32_16x16x32_bf16 v[112:115], v[188:191], v[196:199], v[112:115]
	v_mfma_f32_16x16x32_bf16 v[100:103], v[180:183], v[204:207], v[100:103]
	v_mfma_f32_16x16x32_bf16 v[96:99], v[188:191], v[204:207], v[96:99]
	v_mfma_f32_16x16x32_bf16 v[84:87], v[180:183], v[212:215], v[84:87]
	v_mfma_f32_16x16x32_bf16 v[80:83], v[188:191], v[212:215], v[80:83]
	v_mfma_f32_16x16x32_bf16 v[68:71], v[180:183], v[220:223], v[68:71]
	v_mfma_f32_16x16x32_bf16 v[64:67], v[188:191], v[220:223], v[64:67]
	v_mfma_f32_16x16x32_bf16 v[116:119], v[184:187], v[200:203], v[116:119]
	v_mfma_f32_16x16x32_bf16 v[112:115], v[192:195], v[200:203], v[112:115]
	v_mfma_f32_16x16x32_bf16 v[100:103], v[184:187], v[208:211], v[100:103]
	v_mfma_f32_16x16x32_bf16 v[96:99], v[192:195], v[208:211], v[96:99]
	v_mfma_f32_16x16x32_bf16 v[84:87], v[184:187], v[216:219], v[84:87]
	v_mfma_f32_16x16x32_bf16 v[80:83], v[192:195], v[216:219], v[80:83]
	s_setprio 2
	s_barrier
; #define PG8_STAGE(bufoff, gbase, voff) do { _Pragma("unroll") for (int _i = 0; _i < 2; ++_i) \
;         __builtin_amdgcn_global_load_lds((const unsigned*)((const char*)(gbase) + (voff)[_i]), (LAS unsigned*)(lds + (bufoff) + ldsw + _i * 8192), 16, 0, 0); } while (0)
; #define PG8_LDA(dst, b, h) do { _Pragma("unroll") for (int m = 0; m < 4; ++m) _Pragma("unroll") for (int k = 0; k < 2; ++k) dst[m][k] = *(const LAS bf16x8*)(lds + PG8_SA(b, h) + aoff + m * 2048 + k * 1024); } while (0)
; #define PG8_LDB(dst, b, h) do { _Pragma("unroll") for (int n = 0; n < 2; ++n) _Pragma("unroll") for (int k = 0; k < 2; ++k) dst[n][k] = *(const LAS bf16x8*)(lds + PG8_SB(b, h) + boff + n * 2048 + k * 1024); } while (0)
; template <class Epi, class Sched, bool ALIGN_EPI = true, bool SP2 = true>
; __device__ __forceinline__ void gemm_phase(LAS unsigned char* lds, const bf16_t* Ag, const bf16_t* Btg, const int K, const int lda, const int ldb, const Sched& S, const Epi& E) {
;     ...
;         for (int t = 0; t < nt; t += 2) {
;             const bool last = (t == nt - 2);
;             const char* a1 = cA + (size_t)(t + 1) * kstep;
;             const char* a2 = last ? nA : cA + (size_t)(t + 2) * kstep; const char* b2 = last ? nB : cB + (size_t)(t + 2) * kstep;
;             const char* a3 = a2 + kstep; const char* b3 = b2 + kstep;
;             if constexpr (SP2) {
;             PG8_LDB(B0, 0, 0); PG8_LDB(B1, 0, 1); PG8_SCHED; PG8_LDA(At, 0, 0); PG8_STAGE(PG8_SA(1, 1), a1 + hstepA, voffA);
;             PG8_WAIT_V(8); PG8_WAIT_L(0); PG8_BAR; PG8_MMA(0, 0, At, B0); PG8_MMA(0, 1, At, B1); PG8_BAR; PG8_SCHED;
;             PG8_LDA(At, 0, 1); PG8_STAGE(PG8_SB(0, 0), b2, voffB); PG8_STAGE(PG8_SB(0, 1), b2 + hstepB, voffB); PG8_STAGE(PG8_SA(0, 0), a2, voffA);
;             PG8_WAIT_V(8); PG8_WAIT_L(0); PG8_BAR; PG8_MMA(1, 0, At, B0); PG8_MMA(1, 1, At, B1); PG8_BAR; PG8_SCHED;
;             PG8_LDB(B0, 1, 0); PG8_LDB(B1, 1, 1); PG8_SCHED; PG8_LDA(At, 1, 0); PG8_STAGE(PG8_SA(0, 1), a2 + hstepA, voffA);
;             PG8_WAIT_V(8); PG8_WAIT_L(0); PG8_BAR; PG8_MMA(0, 0, At, B0); PG8_MMA(0, 1, At, B1); PG8_BAR; PG8_SCHED;
;             PG8_LDA(At, 1, 1); PG8_STAGE(PG8_SB(1, 0), b3, voffB); PG8_STAGE(PG8_SB(1, 1), b3 + hstepB, voffB); PG8_STAGE(PG8_SA(1, 0), a3, voffA);
;             PG8_WAIT_V(8); PG8_WAIT_L(0); PG8_BAR; PG8_MMA(1, 0, At, B0); PG8_MMA(1, 1, At, B1); PG8_BAR; PG8_SCHED;
	v_mfma_f32_16x16x32_bf16 v[68:71], v[184:187], v[224:227], v[68:71]
	v_mfma_f32_16x16x32_bf16 v[64:67], v[192:195], v[224:227], v[64:67]
	s_setprio 0
	s_add_i32 s30, s54, s34
	v_lshl_add_u64 v[228:229], v[228:229], 0, s[8:9]
	s_mov_b32 m0, s30
	ds_read_b128 v[196:199], v161 offset:49152
	ds_read_b128 v[200:203], v161 offset:50176
	ds_read_b128 v[204:207], v161 offset:51200
	ds_read_b128 v[208:211], v161 offset:52224
	ds_read_b128 v[212:215], v161 offset:53248
	ds_read_b128 v[216:219], v161 offset:54272
	ds_read_b128 v[220:223], v161 offset:55296
	ds_read_b128 v[224:227], v161 offset:56320
	global_load_lds_dwordx4 v[228:229], off
	s_add_i32 m0, s30, 0x2000
	s_add_u32 s28, s28, 0x80080
	v_lshl_add_u64 v[228:229], v[230:231], 0, s[8:9]
	s_addc_u32 s29, s29, 0
	s_add_i32 s30, s55, s34
	global_load_lds_dwordx4 v[228:229], off
	v_lshl_add_u64 v[228:229], s[28:29], 0, v[130:131]
	s_mov_b32 m0, s30
	s_nop 0
	global_load_lds_dwordx4 v[228:229], off
	v_lshl_add_u64 v[228:229], s[28:29], 0, v[134:135]
	s_add_i32 m0, s30, 0x2000
	s_nop 0
	global_load_lds_dwordx4 v[228:229], off
	v_lshl_add_u64 v[228:229], v[232:233], 0, s[8:9]
	s_mov_b32 m0, s41
	s_nop 0
	global_load_lds_dwordx4 v[228:229], off
	v_lshl_add_u64 v[228:229], v[234:235], 0, s[8:9]
	s_mov_b32 m0, s42
	s_nop 0
	global_load_lds_dwordx4 v[228:229], off
	s_waitcnt vmcnt(8)
	s_waitcnt lgkmcnt(0)
	s_barrier
	s_setprio 1
	s_waitcnt lgkmcnt(0)
	v_mfma_f32_16x16x32_bf16 v[60:63], v[146:149], v[196:199], v[60:63]
	v_mfma_f32_16x16x32_bf16 v[56:59], v[168:171], v[196:199], v[56:59]
	v_mfma_f32_16x16x32_bf16 v[44:47], v[146:149], v[204:207], v[44:47]
	v_mfma_f32_16x16x32_bf16 v[40:43], v[168:171], v[204:207], v[40:43]
	v_mfma_f32_16x16x32_bf16 v[28:31], v[146:149], v[212:215], v[28:31]
	v_mfma_f32_16x16x32_bf16 v[24:27], v[168:171], v[212:215], v[24:27]
	v_mfma_f32_16x16x32_bf16 v[12:15], v[146:149], v[220:223], v[12:15]
	v_mfma_f32_16x16x32_bf16 v[8:11], v[168:171], v[220:223], v[8:11]
	v_mfma_f32_16x16x32_bf16 v[60:63], v[162:165], v[200:203], v[60:63]
	v_mfma_f32_16x16x32_bf16 v[56:59], v[172:175], v[200:203], v[56:59]
	v_mfma_f32_16x16x32_bf16 v[44:47], v[162:165], v[208:211], v[44:47]
	v_mfma_f32_16x16x32_bf16 v[40:43], v[172:175], v[208:211], v[40:43]
	v_mfma_f32_16x16x32_bf16 v[28:31], v[162:165], v[216:219], v[28:31]
	v_mfma_f32_16x16x32_bf16 v[24:27], v[172:175], v[216:219], v[24:27]
	v_mfma_f32_16x16x32_bf16 v[12:15], v[162:165], v[224:227], v[12:15]
	v_mfma_f32_16x16x32_bf16 v[8:11], v[172:175], v[224:227], v[8:11]
	v_mfma_f32_16x16x32_bf16 v[52:55], v[180:183], v[196:199], v[52:55]
	v_mfma_f32_16x16x32_bf16 v[48:51], v[188:191], v[196:199], v[48:51]
	v_mfma_f32_16x16x32_bf16 v[36:39], v[180:183], v[204:207], v[36:39]
	v_mfma_f32_16x16x32_bf16 v[32:35], v[188:191], v[204:207], v[32:35]
	v_mfma_f32_16x16x32_bf16 v[20:23], v[180:183], v[212:215], v[20:23]
	v_mfma_f32_16x16x32_bf16 v[16:19], v[188:191], v[212:215], v[16:19]
	v_mfma_f32_16x16x32_bf16 v[4:7], v[180:183], v[220:223], v[4:7]
	v_mfma_f32_16x16x32_bf16 v[0:3], v[188:191], v[220:223], v[0:3]
	v_mfma_f32_16x16x32_bf16 v[52:55], v[184:187], v[200:203], v[52:55]
	v_mfma_f32_16x16x32_bf16 v[48:51], v[192:195], v[200:203], v[48:51]
	v_mfma_f32_16x16x32_bf16 v[36:39], v[184:187], v[208:211], v[36:39]
	v_mfma_f32_16x16x32_bf16 v[32:35], v[192:195], v[208:211], v[32:35]
	v_mfma_f32_16x16x32_bf16 v[20:23], v[184:187], v[216:219], v[20:23]
	v_mfma_f32_16x16x32_bf16 v[16:19], v[192:195], v[216:219], v[16:19]
	s_setprio 2
	s_barrier
	v_mfma_f32_16x16x32_bf16 v[4:7], v[184:187], v[224:227], v[4:7]
	v_mfma_f32_16x16x32_bf16 v[0:3], v[192:195], v[224:227], v[0:3]
	s_setprio 0
	s_add_i32 s53, s53, 2
	s_add_u32 s26, s26, 0x100
	s_addc_u32 s27, s27, 0
	s_add_u32 s51, s51, 0x100
	s_addc_u32 s52, s52, 0
	s_cmp_gt_u32 s53, 13
	s_cbranch_scc0 .LBB0_866
	s_and_b64 vcc, exec, s[10:11]
	s_cbranch_vccz .LBB0_869
	s_barrier

; #define PG8_STAGE(bufoff, gbase, voff) do { _Pragma("unroll") for (int _i = 0; _i < 2; ++_i) \
;         __builtin_amdgcn_global_load_lds((const unsigned*)((const char*)(gbase) + (voff)[_i]), (LAS unsigned*)(lds + (bufoff) + ldsw + _i * 8192), 16, 0, 0); } while (0)
; #define PG8_LDA(dst, b, h) do { _Pragma("unroll") for (int m = 0; m < 4; ++m) _Pragma("unroll") for (int k = 0; k < 2; ++k) dst[m][k] = *(const LAS bf16x8*)(lds + PG8_SA(b, h) + aoff + m * 2048 + k * 1024); } while (0)
; #define PG8_LDB(dst, b, h) do { _Pragma("unroll") for (int n = 0; n < 2; ++n) _Pragma("unroll") for (int k = 0; k < 2; ++k) dst[n][k] = *(const LAS bf16x8*)(lds + PG8_SB(b, h) + boff + n * 2048 + k * 1024); } while (0)
; #define PG8_MMA(ai, bj, At, Bt) do { __builtin_amdgcn_s_setprio(1); _Pragma("unroll") for (int m = 0; m < 4; ++m) _Pragma("unroll") for (int n = 0; n < 2; ++n) _Pragma("unroll") for (int k = 0; k < 2; ++k) \
;         acc[ai][bj][m][n] = __builtin_amdgcn_mfma_f32_16x16x32_bf16(Bt[n][k], At[m][k], acc[ai][bj][m][n], 0, 0, 0); __builtin_amdgcn_s_setprio(0); } while (0)
; #define PG8_WAIT_V(n) asm volatile("s_waitcnt vmcnt(" #n ")" ::: "memory")
; #define PG8_WAIT_L(n) asm volatile("s_waitcnt lgkmcnt(" #n ")" ::: "memory")
; #define PG8_BAR __builtin_amdgcn_s_barrier()
; #define PG8_SCHED __builtin_amdgcn_sched_barrier(0)
; template <class Epi, class Sched, bool ALIGN_EPI = true, bool SP2 = true>
; __device__ __forceinline__ void gemm_phase(LAS unsigned char* lds, const bf16_t* Ag, const bf16_t* Btg, const int K, const int lda, const int ldb, const Sched& S, const Epi& E) {
;     ...
;         for (int t = 0; t < nt; t += 2) {
;             const bool last = (t == nt - 2);
;             const char* a1 = cA + (size_t)(t + 1) * kstep;
;             const char* a2 = last ? nA : cA + (size_t)(t + 2) * kstep; const char* b2 = last ? nB : cB + (size_t)(t + 2) * kstep;
;             const char* a3 = a2 + kstep; const char* b3 = b2 + kstep;
;             if constexpr (SP2) {
;             PG8_LDB(B0, 0, 0); PG8_LDB(B1, 0, 1); PG8_SCHED; PG8_LDA(At, 0, 0); PG8_STAGE(PG8_SA(1, 1), a1 + hstepA, voffA);
;             PG8_WAIT_V(8); PG8_WAIT_L(0); PG8_BAR; PG8_MMA(0, 0, At, B0); PG8_MMA(0, 1, At, B1); PG8_BAR; PG8_SCHED;
;             PG8_LDA(At, 0, 1); PG8_STAGE(PG8_SB(0, 0), b2, voffB); PG8_STAGE(PG8_SB(0, 1), b2 + hstepB, voffB); PG8_STAGE(PG8_SA(0, 0), a2, voffA);
.LBB0_890:
	ds_read_b128 v[146:149], v156
	ds_read_b128 v[150:153], v156 offset:1024
	ds_read_b128 v[160:163], v156 offset:2048
	ds_read_b128 v[168:171], v156 offset:3072
	ds_read_b128 v[172:175], v157
	ds_read_b128 v[180:183], v157 offset:1024
	ds_read_b128 v[184:187], v157 offset:2048
	ds_read_b128 v[188:191], v157 offset:3072
	s_add_u32 s28, s26, 0xfff80080
	s_addc_u32 s29, s27, -1
	s_cmp_eq_u32 s59, 12
	s_cselect_b32 s31, s13, s29
	s_cselect_b32 s30, s15, s28
	s_cselect_b32 s29, s33, s58
	s_cselect_b32 s28, s54, s55
	v_lshl_add_u64 v[164:165], s[26:27], 0, v[138:139]
	s_add_i32 m0, s41, 0xc000
	ds_read_b128 v[192:195], v158
	ds_read_b128 v[196:199], v158 offset:1024
	ds_read_b128 v[200:203], v158 offset:2048
	ds_read_b128 v[204:207], v158 offset:3072
	ds_read_b128 v[208:211], v158 offset:4096
	ds_read_b128 v[212:215], v158 offset:5120
	ds_read_b128 v[216:219], v158 offset:6144
	ds_read_b128 v[220:223], v158 offset:7168
	global_load_lds_dwordx4 v[164:165], off
	v_lshl_add_u64 v[164:165], s[26:27], 0, v[140:141]
	s_add_i32 m0, s41, 0xe000
	s_nop 0
	global_load_lds_dwordx4 v[164:165], off
	s_waitcnt vmcnt(8)
	s_waitcnt lgkmcnt(0)
	s_barrier
	s_setprio 1
	s_waitcnt lgkmcnt(0)
	v_mfma_f32_16x16x32_bf16 v[124:127], v[146:149], v[192:195], v[124:127]
	v_mfma_f32_16x16x32_bf16 v[120:123], v[160:163], v[192:195], v[120:123]
	v_mfma_f32_16x16x32_bf16 v[108:111], v[146:149], v[200:203], v[108:111]
	v_mfma_f32_16x16x32_bf16 v[104:107], v[160:163], v[200:203], v[104:107]
	v_mfma_f32_16x16x32_bf16 v[92:95], v[146:149], v[208:211], v[92:95]
	v_mfma_f32_16x16x32_bf16 v[88:91], v[160:163], v[208:211], v[88:91]
	v_mfma_f32_16x16x32_bf16 v[76:79], v[146:149], v[216:219], v[76:79]
	v_mfma_f32_16x16x32_bf16 v[72:75], v[160:163], v[216:219], v[72:75]
	v_mfma_f32_16x16x32_bf16 v[124:127], v[150:153], v[196:199], v[124:127]
	v_mfma_f32_16x16x32_bf16 v[120:123], v[168:171], v[196:199], v[120:123]
	v_mfma_f32_16x16x32_bf16 v[108:111], v[150:153], v[204:207], v[108:111]
	v_mfma_f32_16x16x32_bf16 v[104:107], v[168:171], v[204:207], v[104:107]
	v_mfma_f32_16x16x32_bf16 v[92:95], v[150:153], v[212:215], v[92:95]
	v_mfma_f32_16x16x32_bf16 v[88:91], v[168:171], v[212:215], v[88:91]
	v_mfma_f32_16x16x32_bf16 v[76:79], v[150:153], v[220:223], v[76:79]
	v_mfma_f32_16x16x32_bf16 v[72:75], v[168:171], v[220:223], v[72:75]
	v_mfma_f32_16x16x32_bf16 v[116:119], v[172:175], v[192:195], v[116:119]
	v_mfma_f32_16x16x32_bf16 v[112:115], v[184:187], v[192:195], v[112:115]
	v_mfma_f32_16x16x32_bf16 v[100:103], v[172:175], v[200:203], v[100:103]
	v_mfma_f32_16x16x32_bf16 v[96:99], v[184:187], v[200:203], v[96:99]
	v_mfma_f32_16x16x32_bf16 v[84:87], v[172:175], v[208:211], v[84:87]
	v_mfma_f32_16x16x32_bf16 v[80:83], v[184:187], v[208:211], v[80:83]
	v_mfma_f32_16x16x32_bf16 v[68:71], v[172:175], v[216:219], v[68:71]
	v_mfma_f32_16x16x32_bf16 v[64:67], v[184:187], v[216:219], v[64:67]
	v_mfma_f32_16x16x32_bf16 v[116:119], v[180:183], v[196:199], v[116:119]
	v_mfma_f32_16x16x32_bf16 v[112:115], v[188:191], v[196:199], v[112:115]
	v_mfma_f32_16x16x32_bf16 v[100:103], v[180:183], v[204:207], v[100:103]
	v_mfma_f32_16x16x32_bf16 v[96:99], v[188:191], v[204:207], v[96:99]
	v_mfma_f32_16x16x32_bf16 v[84:87], v[180:183], v[212:215], v[84:87]
	v_mfma_f32_16x16x32_bf16 v[80:83], v[188:191], v[212:215], v[80:83]
	s_setprio 2
	s_barrier
	v_mfma_f32_16x16x32_bf16 v[68:71], v[180:183], v[220:223], v[68:71]
	v_mfma_f32_16x16x32_bf16 v[64:67], v[188:191], v[220:223], v[64:67]
	s_setprio 0
	s_add_i32 s60, s52, s40
	v_lshl_add_u64 v[164:165], s[28:29], 0, v[130:131]
	s_mov_b32 m0, s60
	ds_read_b128 v[192:195], v158 offset:16384
	ds_read_b128 v[196:199], v158 offset:17408
	ds_read_b128 v[200:203], v158 offset:18432
	ds_read_b128 v[204:207], v158 offset:19456
	ds_read_b128 v[208:211], v158 offset:20480
	ds_read_b128 v[212:215], v158 offset:21504
	ds_read_b128 v[216:219], v158 offset:22528
	ds_read_b128 v[220:223], v158 offset:23552
	global_load_lds_dwordx4 v[164:165], off
	s_add_i32 m0, s60, 0x2000
	s_add_u32 s60, s28, 0x80000
	v_lshl_add_u64 v[224:225], s[28:29], 0, v[134:135]
	s_addc_u32 s61, s29, 0
	s_add_i32 s64, s53, s40
	global_load_lds_dwordx4 v[224:225], off
	v_lshl_add_u64 v[226:227], s[60:61], 0, v[130:131]
	s_mov_b32 m0, s64
	v_lshl_add_u64 v[228:229], s[30:31], 0, v[132:133]
	global_load_lds_dwordx4 v[226:227], off
	v_lshl_add_u64 v[226:227], s[60:61], 0, v[134:135]
	s_add_i32 m0, s64, 0x2000
	s_nop 0
	global_load_lds_dwordx4 v[226:227], off
	v_lshl_add_u64 v[226:227], s[30:31], 0, v[128:129]
	s_mov_b32 m0, s41
	s_nop 0
	global_load_lds_dwordx4 v[226:227], off
	s_mov_b32 m0, s42
	s_nop 0
	global_load_lds_dwordx4 v[228:229], off
	s_waitcnt vmcnt(8)
	s_waitcnt lgkmcnt(0)
	s_barrier
; #define PG8_STAGE(bufoff, gbase, voff) do { _Pragma("unroll") for (int _i = 0; _i < 2; ++_i) \
;         __builtin_amdgcn_global_load_lds((const unsigned*)((const char*)(gbase) + (voff)[_i]), (LAS unsigned*)(lds + (bufoff) + ldsw + _i * 8192), 16, 0, 0); } while (0)
; #define PG8_LDA(dst, b, h) do { _Pragma("unroll") for (int m = 0; m < 4; ++m) _Pragma("unroll") for (int k = 0; k < 2; ++k) dst[m][k] = *(const LAS bf16x8*)(lds + PG8_SA(b, h) + aoff + m * 2048 + k * 1024); } while (0)
; #define PG8_LDB(dst, b, h) do { _Pragma("unroll") for (int n = 0; n < 2; ++n) _Pragma("unroll") for (int k = 0; k < 2; ++k) dst[n][k] = *(const LAS bf16x8*)(lds + PG8_SB(b, h) + boff + n * 2048 + k * 1024); } while (0)
; #define PG8_MMA(ai, bj, At, Bt) do { __builtin_amdgcn_s_setprio(1); _Pragma("unroll") for (int m = 0; m < 4; ++m) _Pragma("unroll") for (int n = 0; n < 2; ++n) _Pragma("unroll") for (int k = 0; k < 2; ++k) \
;         acc[ai][bj][m][n] = __builtin_amdgcn_mfma_f32_16x16x32_bf16(Bt[n][k], At[m][k], acc[ai][bj][m][n], 0, 0, 0); __builtin_amdgcn_s_setprio(0); } while (0)
; #define PG8_WAIT_V(n) asm volatile("s_waitcnt vmcnt(" #n ")" ::: "memory")
; #define PG8_WAIT_L(n) asm volatile("s_waitcnt lgkmcnt(" #n ")" ::: "memory")
; #define PG8_BAR __builtin_amdgcn_s_barrier()
; #define PG8_SCHED __builtin_amdgcn_sched_barrier(0)
; template <class Epi, class Sched, bool ALIGN_EPI = true, bool SP2 = true>
; __device__ __forceinline__ void gemm_phase(LAS unsigned char* lds, const bf16_t* Ag, const bf16_t* Btg, const int K, const int lda, const int ldb, const Sched& S, const Epi& E) {
;     ...
;             PG8_WAIT_V(8); PG8_WAIT_L(0); PG8_BAR; PG8_MMA(1, 0, At, B0); PG8_MMA(1, 1, At, B1); PG8_BAR; PG8_SCHED;
;             PG8_LDB(B0, 1, 0); PG8_LDB(B1, 1, 1); PG8_SCHED; PG8_LDA(At, 1, 0); PG8_STAGE(PG8_SA(0, 1), a2 + hstepA, voffA);
;             PG8_WAIT_V(8); PG8_WAIT_L(0); PG8_BAR; PG8_MMA(0, 0, At, B0); PG8_MMA(0, 1, At, B1); PG8_BAR; PG8_SCHED;
	s_setprio 1
	s_waitcnt lgkmcnt(0)
	v_mfma_f32_16x16x32_bf16 v[60:63], v[146:149], v[192:195], v[60:63]
	v_mfma_f32_16x16x32_bf16 v[56:59], v[160:163], v[192:195], v[56:59]
	v_mfma_f32_16x16x32_bf16 v[44:47], v[146:149], v[200:203], v[44:47]
	v_mfma_f32_16x16x32_bf16 v[40:43], v[160:163], v[200:203], v[40:43]
	v_mfma_f32_16x16x32_bf16 v[28:31], v[146:149], v[208:211], v[28:31]
	v_mfma_f32_16x16x32_bf16 v[24:27], v[160:163], v[208:211], v[24:27]
	v_mfma_f32_16x16x32_bf16 v[12:15], v[146:149], v[216:219], v[12:15]
	v_mfma_f32_16x16x32_bf16 v[8:11], v[160:163], v[216:219], v[8:11]
	v_mfma_f32_16x16x32_bf16 v[60:63], v[150:153], v[196:199], v[60:63]
	v_mfma_f32_16x16x32_bf16 v[56:59], v[168:171], v[196:199], v[56:59]
	v_mfma_f32_16x16x32_bf16 v[44:47], v[150:153], v[204:207], v[44:47]
	v_mfma_f32_16x16x32_bf16 v[40:43], v[168:171], v[204:207], v[40:43]
	v_mfma_f32_16x16x32_bf16 v[28:31], v[150:153], v[212:215], v[28:31]
	v_mfma_f32_16x16x32_bf16 v[24:27], v[168:171], v[212:215], v[24:27]
	v_mfma_f32_16x16x32_bf16 v[12:15], v[150:153], v[220:223], v[12:15]
	v_mfma_f32_16x16x32_bf16 v[8:11], v[168:171], v[220:223], v[8:11]
	v_mfma_f32_16x16x32_bf16 v[52:55], v[172:175], v[192:195], v[52:55]
	v_mfma_f32_16x16x32_bf16 v[48:51], v[184:187], v[192:195], v[48:51]
	v_mfma_f32_16x16x32_bf16 v[36:39], v[172:175], v[200:203], v[36:39]
	v_mfma_f32_16x16x32_bf16 v[32:35], v[184:187], v[200:203], v[32:35]
	v_mfma_f32_16x16x32_bf16 v[20:23], v[172:175], v[208:211], v[20:23]
	v_mfma_f32_16x16x32_bf16 v[16:19], v[184:187], v[208:211], v[16:19]
	v_mfma_f32_16x16x32_bf16 v[4:7], v[172:175], v[216:219], v[4:7]
	v_mfma_f32_16x16x32_bf16 v[0:3], v[184:187], v[216:219], v[0:3]
	v_mfma_f32_16x16x32_bf16 v[52:55], v[180:183], v[196:199], v[52:55]
	v_mfma_f32_16x16x32_bf16 v[48:51], v[188:191], v[196:199], v[48:51]
	v_mfma_f32_16x16x32_bf16 v[36:39], v[180:183], v[204:207], v[36:39]
	v_mfma_f32_16x16x32_bf16 v[32:35], v[188:191], v[204:207], v[32:35]
	v_mfma_f32_16x16x32_bf16 v[20:23], v[180:183], v[212:215], v[20:23]
	v_mfma_f32_16x16x32_bf16 v[16:19], v[188:191], v[212:215], v[16:19]
	s_setprio 2
	s_barrier
	v_mfma_f32_16x16x32_bf16 v[4:7], v[180:183], v[220:223], v[4:7]
	v_mfma_f32_16x16x32_bf16 v[0:3], v[188:191], v[220:223], v[0:3]
	s_setprio 0
	s_add_i32 s60, 0, 0x18000
	v_add_u32_e32 v159, s60, v154
	s_add_i32 s61, 0, 0x1c000
	ds_read_b128 v[146:149], v159
	ds_read_b128 v[150:153], v159 offset:1024
	ds_read_b128 v[160:163], v159 offset:2048
	ds_read_b128 v[168:171], v159 offset:3072
	v_add_u32_e32 v159, s61, v154
	ds_read_b128 v[172:175], v159
	ds_read_b128 v[180:183], v159 offset:1024
	ds_read_b128 v[184:187], v159 offset:2048
	ds_read_b128 v[188:191], v159 offset:3072
	s_add_u32 s30, s30, 0x80000
	s_addc_u32 s31, s31, 0
	s_mov_b32 m0, s43
	v_lshl_add_u64 v[230:231], s[30:31], 0, v[128:129]
	ds_read_b128 v[192:195], v158 offset:32768
	ds_read_b128 v[196:199], v158 offset:33792
	ds_read_b128 v[200:203], v158 offset:34816
	ds_read_b128 v[204:207], v158 offset:35840
	ds_read_b128 v[208:211], v158 offset:36864
	ds_read_b128 v[212:215], v158 offset:37888
	ds_read_b128 v[216:219], v158 offset:38912
	ds_read_b128 v[220:223], v158 offset:39936
	global_load_lds_dwordx4 v[230:231], off
	v_lshl_add_u64 v[230:231], s[30:31], 0, v[132:133]
	s_mov_b32 m0, s44
	s_nop 0
	global_load_lds_dwordx4 v[230:231], off
	s_waitcnt vmcnt(8)
	s_waitcnt lgkmcnt(0)
	s_barrier
	s_setprio 1
	s_waitcnt lgkmcnt(0)
	v_mfma_f32_16x16x32_bf16 v[124:127], v[146:149], v[192:195], v[124:127]
	v_mfma_f32_16x16x32_bf16 v[120:123], v[160:163], v[192:195], v[120:123]
	v_mfma_f32_16x16x32_bf16 v[108:111], v[146:149], v[200:203], v[108:111]
	v_mfma_f32_16x16x32_bf16 v[104:107], v[160:163], v[200:203], v[104:107]
	v_mfma_f32_16x16x32_bf16 v[92:95], v[146:149], v[208:211], v[92:95]
	v_mfma_f32_16x16x32_bf16 v[88:91], v[160:163], v[208:211], v[88:91]
	v_mfma_f32_16x16x32_bf16 v[76:79], v[146:149], v[216:219], v[76:79]
	v_mfma_f32_16x16x32_bf16 v[72:75], v[160:163], v[216:219], v[72:75]
	v_mfma_f32_16x16x32_bf16 v[124:127], v[150:153], v[196:199], v[124:127]
	v_mfma_f32_16x16x32_bf16 v[120:123], v[168:171], v[196:199], v[120:123]
	v_mfma_f32_16x16x32_bf16 v[108:111], v[150:153], v[204:207], v[108:111]
	v_mfma_f32_16x16x32_bf16 v[104:107], v[168:171], v[204:207], v[104:107]
	v_mfma_f32_16x16x32_bf16 v[92:95], v[150:153], v[212:215], v[92:95]
	v_mfma_f32_16x16x32_bf16 v[88:91], v[168:171], v[212:215], v[88:91]
	v_mfma_f32_16x16x32_bf16 v[76:79], v[150:153], v[220:223], v[76:79]
	v_mfma_f32_16x16x32_bf16 v[72:75], v[168:171], v[220:223], v[72:75]
	v_mfma_f32_16x16x32_bf16 v[116:119], v[172:175], v[192:195], v[116:119]
	v_mfma_f32_16x16x32_bf16 v[112:115], v[184:187], v[192:195], v[112:115]
	v_mfma_f32_16x16x32_bf16 v[100:103], v[172:175], v[200:203], v[100:103]
	v_mfma_f32_16x16x32_bf16 v[96:99], v[184:187], v[200:203], v[96:99]
	v_mfma_f32_16x16x32_bf16 v[84:87], v[172:175], v[208:211], v[84:87]
	v_mfma_f32_16x16x32_bf16 v[80:83], v[184:187], v[208:211], v[80:83]
	v_mfma_f32_16x16x32_bf16 v[68:71], v[172:175], v[216:219], v[68:71]
	v_mfma_f32_16x16x32_bf16 v[64:67], v[184:187], v[216:219], v[64:67]
	v_mfma_f32_16x16x32_bf16 v[116:119], v[180:183], v[196:199], v[116:119]
	v_mfma_f32_16x16x32_bf16 v[112:115], v[188:191], v[196:199], v[112:115]
	v_mfma_f32_16x16x32_bf16 v[100:103], v[180:183], v[204:207], v[100:103]
	v_mfma_f32_16x16x32_bf16 v[96:99], v[188:191], v[204:207], v[96:99]
	v_mfma_f32_16x16x32_bf16 v[84:87], v[180:183], v[212:215], v[84:87]
	v_mfma_f32_16x16x32_bf16 v[80:83], v[188:191], v[212:215], v[80:83]
	s_setprio 2
	s_barrier
; #define PG8_STAGE(bufoff, gbase, voff) do { _Pragma("unroll") for (int _i = 0; _i < 2; ++_i) \
;         __builtin_amdgcn_global_load_lds((const unsigned*)((const char*)(gbase) + (voff)[_i]), (LAS unsigned*)(lds + (bufoff) + ldsw + _i * 8192), 16, 0, 0); } while (0)
; #define PG8_LDA(dst, b, h) do { _Pragma("unroll") for (int m = 0; m < 4; ++m) _Pragma("unroll") for (int k = 0; k < 2; ++k) dst[m][k] = *(const LAS bf16x8*)(lds + PG8_SA(b, h) + aoff + m * 2048 + k * 1024); } while (0)
; #define PG8_LDB(dst, b, h) do { _Pragma("unroll") for (int n = 0; n < 2; ++n) _Pragma("unroll") for (int k = 0; k < 2; ++k) dst[n][k] = *(const LAS bf16x8*)(lds + PG8_SB(b, h) + boff + n * 2048 + k * 1024); } while (0)
; template <class Epi, class Sched, bool ALIGN_EPI = true, bool SP2 = true>
; __device__ __forceinline__ void gemm_phase(LAS unsigned char* lds, const bf16_t* Ag, const bf16_t* Btg, const int K, const int lda, const int ldb, const Sched& S, const Epi& E) {
;     ...
;         for (int t = 0; t < nt; t += 2) {
;             const bool last = (t == nt - 2);
;             const char* a1 = cA + (size_t)(t + 1) * kstep;
;             const char* a2 = last ? nA : cA + (size_t)(t + 2) * kstep; const char* b2 = last ? nB : cB + (size_t)(t + 2) * kstep;
;             const char* a3 = a2 + kstep; const char* b3 = b2 + kstep;
;             if constexpr (SP2) {
;             PG8_LDB(B0, 0, 0); PG8_LDB(B1, 0, 1); PG8_SCHED; PG8_LDA(At, 0, 0); PG8_STAGE(PG8_SA(1, 1), a1 + hstepA, voffA);
;             PG8_WAIT_V(8); PG8_WAIT_L(0); PG8_BAR; PG8_MMA(0, 0, At, B0); PG8_MMA(0, 1, At, B1); PG8_BAR; PG8_SCHED;
;             PG8_LDA(At, 0, 1); PG8_STAGE(PG8_SB(0, 0), b2, voffB); PG8_STAGE(PG8_SB(0, 1), b2 + hstepB, voffB); PG8_STAGE(PG8_SA(0, 0), a2, voffA);
;             PG8_WAIT_V(8); PG8_WAIT_L(0); PG8_BAR; PG8_MMA(1, 0, At, B0); PG8_MMA(1, 1, At, B1); PG8_BAR; PG8_SCHED;
;             PG8_LDB(B0, 1, 0); PG8_LDB(B1, 1, 1); PG8_SCHED; PG8_LDA(At, 1, 0); PG8_STAGE(PG8_SA(0, 1), a2 + hstepA, voffA);
;             PG8_WAIT_V(8); PG8_WAIT_L(0); PG8_BAR; PG8_MMA(0, 0, At, B0); PG8_MMA(0, 1, At, B1); PG8_BAR; PG8_SCHED;
;             PG8_LDA(At, 1, 1); PG8_STAGE(PG8_SB(1, 0), b3, voffB); PG8_STAGE(PG8_SB(1, 1), b3 + hstepB, voffB); PG8_STAGE(PG8_SA(1, 0), a3, voffA);
;             PG8_WAIT_V(8); PG8_WAIT_L(0); PG8_BAR; PG8_MMA(1, 0, At, B0); PG8_MMA(1, 1, At, B1); PG8_BAR; PG8_SCHED;
	v_mfma_f32_16x16x32_bf16 v[68:71], v[180:183], v[220:223], v[68:71]
	v_mfma_f32_16x16x32_bf16 v[64:67], v[188:191], v[220:223], v[64:67]
	s_setprio 0
	s_add_i32 s30, s60, s40
	v_lshl_add_u64 v[164:165], v[164:165], 0, s[6:7]
	s_mov_b32 m0, s30
	ds_read_b128 v[192:195], v158 offset:49152
	ds_read_b128 v[196:199], v158 offset:50176
	ds_read_b128 v[200:203], v158 offset:51200
	ds_read_b128 v[204:207], v158 offset:52224
	ds_read_b128 v[208:211], v158 offset:53248
	ds_read_b128 v[212:215], v158 offset:54272
	ds_read_b128 v[216:219], v158 offset:55296
	ds_read_b128 v[220:223], v158 offset:56320
	global_load_lds_dwordx4 v[164:165], off
	s_add_i32 m0, s30, 0x2000
	s_add_u32 s28, s28, 0x80080
	v_lshl_add_u64 v[164:165], v[224:225], 0, s[6:7]
	s_addc_u32 s29, s29, 0
	s_add_i32 s30, s61, s40
	global_load_lds_dwordx4 v[164:165], off
	v_lshl_add_u64 v[164:165], s[28:29], 0, v[130:131]
	s_mov_b32 m0, s30
	s_nop 0
	global_load_lds_dwordx4 v[164:165], off
	v_lshl_add_u64 v[164:165], s[28:29], 0, v[134:135]
	s_add_i32 m0, s30, 0x2000
	s_nop 0
	global_load_lds_dwordx4 v[164:165], off
	v_lshl_add_u64 v[164:165], v[226:227], 0, s[6:7]
	s_mov_b32 m0, s46
	s_nop 0
	global_load_lds_dwordx4 v[164:165], off
	v_lshl_add_u64 v[164:165], v[228:229], 0, s[6:7]
	s_mov_b32 m0, s47
	s_nop 0
	global_load_lds_dwordx4 v[164:165], off
	s_waitcnt vmcnt(8)
	s_waitcnt lgkmcnt(0)
	s_barrier
	s_setprio 1
	s_waitcnt lgkmcnt(0)
	v_mfma_f32_16x16x32_bf16 v[60:63], v[146:149], v[192:195], v[60:63]
	v_mfma_f32_16x16x32_bf16 v[56:59], v[160:163], v[192:195], v[56:59]
	v_mfma_f32_16x16x32_bf16 v[44:47], v[146:149], v[200:203], v[44:47]
	v_mfma_f32_16x16x32_bf16 v[40:43], v[160:163], v[200:203], v[40:43]
	v_mfma_f32_16x16x32_bf16 v[28:31], v[146:149], v[208:211], v[28:31]
	v_mfma_f32_16x16x32_bf16 v[24:27], v[160:163], v[208:211], v[24:27]
	v_mfma_f32_16x16x32_bf16 v[12:15], v[146:149], v[216:219], v[12:15]
	v_mfma_f32_16x16x32_bf16 v[8:11], v[160:163], v[216:219], v[8:11]
	v_mfma_f32_16x16x32_bf16 v[60:63], v[150:153], v[196:199], v[60:63]
	v_mfma_f32_16x16x32_bf16 v[56:59], v[168:171], v[196:199], v[56:59]
	v_mfma_f32_16x16x32_bf16 v[44:47], v[150:153], v[204:207], v[44:47]
	v_mfma_f32_16x16x32_bf16 v[40:43], v[168:171], v[204:207], v[40:43]
	v_mfma_f32_16x16x32_bf16 v[28:31], v[150:153], v[212:215], v[28:31]
	v_mfma_f32_16x16x32_bf16 v[24:27], v[168:171], v[212:215], v[24:27]
	v_mfma_f32_16x16x32_bf16 v[12:15], v[150:153], v[220:223], v[12:15]
	v_mfma_f32_16x16x32_bf16 v[8:11], v[168:171], v[220:223], v[8:11]
	v_mfma_f32_16x16x32_bf16 v[52:55], v[172:175], v[192:195], v[52:55]
	v_mfma_f32_16x16x32_bf16 v[48:51], v[184:187], v[192:195], v[48:51]
	v_mfma_f32_16x16x32_bf16 v[36:39], v[172:175], v[200:203], v[36:39]
	v_mfma_f32_16x16x32_bf16 v[32:35], v[184:187], v[200:203], v[32:35]
	v_mfma_f32_16x16x32_bf16 v[20:23], v[172:175], v[208:211], v[20:23]
	v_mfma_f32_16x16x32_bf16 v[16:19], v[184:187], v[208:211], v[16:19]
	v_mfma_f32_16x16x32_bf16 v[4:7], v[172:175], v[216:219], v[4:7]
	v_mfma_f32_16x16x32_bf16 v[0:3], v[184:187], v[216:219], v[0:3]
	v_mfma_f32_16x16x32_bf16 v[52:55], v[180:183], v[196:199], v[52:55]
	v_mfma_f32_16x16x32_bf16 v[48:51], v[188:191], v[196:199], v[48:51]
	v_mfma_f32_16x16x32_bf16 v[36:39], v[180:183], v[204:207], v[36:39]
	v_mfma_f32_16x16x32_bf16 v[32:35], v[188:191], v[204:207], v[32:35]
	v_mfma_f32_16x16x32_bf16 v[20:23], v[180:183], v[212:215], v[20:23]
	v_mfma_f32_16x16x32_bf16 v[16:19], v[188:191], v[212:215], v[16:19]
	s_setprio 2
	s_barrier
	v_mfma_f32_16x16x32_bf16 v[4:7], v[180:183], v[220:223], v[4:7]
	v_mfma_f32_16x16x32_bf16 v[0:3], v[188:191], v[220:223], v[0:3]
	s_setprio 0
	s_add_i32 s59, s59, 2
	s_add_u32 s26, s26, 0x100
	s_addc_u32 s27, s27, 0
	s_add_u32 s55, s55, 0x100
	s_addc_u32 s58, s58, 0
	s_cmp_gt_u32 s59, 13
	s_cbranch_scc0 .LBB0_890
	s_and_b64 vcc, exec, s[8:9]
	s_cbranch_vccz .LBB0_893
	s_barrier

; #define PG8_STAGE(bufoff, gbase, voff) do { _Pragma("unroll") for (int _i = 0; _i < 2; ++_i) \
;         __builtin_amdgcn_global_load_lds((const unsigned*)((const char*)(gbase) + (voff)[_i]), (LAS unsigned*)(lds + (bufoff) + ldsw + _i * 8192), 16, 0, 0); } while (0)
; #define PG8_LDA(dst, b, h) do { _Pragma("unroll") for (int m = 0; m < 4; ++m) _Pragma("unroll") for (int k = 0; k < 2; ++k) dst[m][k] = *(const LAS bf16x8*)(lds + PG8_SA(b, h) + aoff + m * 2048 + k * 1024); } while (0)
; #define PG8_LDB(dst, b, h) do { _Pragma("unroll") for (int n = 0; n < 2; ++n) _Pragma("unroll") for (int k = 0; k < 2; ++k) dst[n][k] = *(const LAS bf16x8*)(lds + PG8_SB(b, h) + boff + n * 2048 + k * 1024); } while (0)
; #define PG8_MMA(ai, bj, At, Bt) do { __builtin_amdgcn_s_setprio(1); _Pragma("unroll") for (int m = 0; m < 4; ++m) _Pragma("unroll") for (int n = 0; n < 2; ++n) _Pragma("unroll") for (int k = 0; k < 2; ++k) \
;         acc[ai][bj][m][n] = __builtin_amdgcn_mfma_f32_16x16x32_bf16(Bt[n][k], At[m][k], acc[ai][bj][m][n], 0, 0, 0); __builtin_amdgcn_s_setprio(0); } while (0)
; #define PG8_WAIT_V(n) asm volatile("s_waitcnt vmcnt(" #n ")" ::: "memory")
; #define PG8_WAIT_L(n) asm volatile("s_waitcnt lgkmcnt(" #n ")" ::: "memory")
; #define PG8_BAR __builtin_amdgcn_s_barrier()
; #define PG8_SCHED __builtin_amdgcn_sched_barrier(0)
; template <class Epi, class Sched, bool ALIGN_EPI = true, bool SP2 = true>
; __device__ __forceinline__ void gemm_phase(LAS unsigned char* lds, const bf16_t* Ag, const bf16_t* Btg, const int K, const int lda, const int ldb, const Sched& S, const Epi& E) {
;     ...
;         for (int t = 0; t < nt; t += 2) {
;             const bool last = (t == nt - 2);
;             const char* a1 = cA + (size_t)(t + 1) * kstep;
;             const char* a2 = last ? nA : cA + (size_t)(t + 2) * kstep; const char* b2 = last ? nB : cB + (size_t)(t + 2) * kstep;
;             const char* a3 = a2 + kstep; const char* b3 = b2 + kstep;
;             if constexpr (SP2) {
;             PG8_LDB(B0, 0, 0); PG8_LDB(B1, 0, 1); PG8_SCHED; PG8_LDA(At, 0, 0); PG8_STAGE(PG8_SA(1, 1), a1 + hstepA, voffA);
;             PG8_WAIT_V(8); PG8_WAIT_L(0); PG8_BAR; PG8_MMA(0, 0, At, B0); PG8_MMA(0, 1, At, B1); PG8_BAR; PG8_SCHED;
;             PG8_LDA(At, 0, 1); PG8_STAGE(PG8_SB(0, 0), b2, voffB); PG8_STAGE(PG8_SB(0, 1), b2 + hstepB, voffB); PG8_STAGE(PG8_SA(0, 0), a2, voffA);
.LBB0_969:
	ds_read_b128 v[152:155], v149
	ds_read_b128 v[156:159], v149 offset:1024
	ds_read_b128 v[160:163], v149 offset:2048
	ds_read_b128 v[168:171], v149 offset:3072
	ds_read_b128 v[172:175], v150
	ds_read_b128 v[180:183], v150 offset:1024
	ds_read_b128 v[184:187], v150 offset:2048
	ds_read_b128 v[188:191], v150 offset:3072
	s_add_u32 s26, s24, 0xfff80080
	s_addc_u32 s27, s25, -1
	s_cmp_eq_u32 s54, 28
	s_cselect_b32 s29, s33, s27
	s_cselect_b32 s28, s47, s26
	s_cselect_b32 s27, s50, s53
	s_cselect_b32 s26, s51, s52
	v_lshl_add_u64 v[146:147], s[24:25], 0, v[138:139]
	s_add_i32 m0, s34, 0xc000
	ds_read_b128 v[192:195], v151
	ds_read_b128 v[196:199], v151 offset:1024
	ds_read_b128 v[200:203], v151 offset:2048
	ds_read_b128 v[204:207], v151 offset:3072
	ds_read_b128 v[208:211], v151 offset:4096
	ds_read_b128 v[212:215], v151 offset:5120
	ds_read_b128 v[216:219], v151 offset:6144
	ds_read_b128 v[220:223], v151 offset:7168
	global_load_lds_dwordx4 v[146:147], off
	v_lshl_add_u64 v[146:147], s[24:25], 0, v[140:141]
	s_add_i32 m0, s34, 0xe000
	s_nop 0
	global_load_lds_dwordx4 v[146:147], off
	s_waitcnt vmcnt(8)
	s_waitcnt lgkmcnt(0)
	s_barrier
	s_setprio 1
	s_waitcnt lgkmcnt(0)
	v_mfma_f32_16x16x32_bf16 v[124:127], v[152:155], v[192:195], v[124:127]
	v_mfma_f32_16x16x32_bf16 v[120:123], v[160:163], v[192:195], v[120:123]
	v_mfma_f32_16x16x32_bf16 v[116:119], v[152:155], v[200:203], v[116:119]
	v_mfma_f32_16x16x32_bf16 v[108:111], v[160:163], v[200:203], v[108:111]
	v_mfma_f32_16x16x32_bf16 v[92:95], v[152:155], v[208:211], v[92:95]
	v_mfma_f32_16x16x32_bf16 v[88:91], v[160:163], v[208:211], v[88:91]
	v_mfma_f32_16x16x32_bf16 v[76:79], v[152:155], v[216:219], v[76:79]
	v_mfma_f32_16x16x32_bf16 v[72:75], v[160:163], v[216:219], v[72:75]
	v_mfma_f32_16x16x32_bf16 v[124:127], v[156:159], v[196:199], v[124:127]
	v_mfma_f32_16x16x32_bf16 v[120:123], v[168:171], v[196:199], v[120:123]
	v_mfma_f32_16x16x32_bf16 v[116:119], v[156:159], v[204:207], v[116:119]
	v_mfma_f32_16x16x32_bf16 v[108:111], v[168:171], v[204:207], v[108:111]
	v_mfma_f32_16x16x32_bf16 v[92:95], v[156:159], v[212:215], v[92:95]
	v_mfma_f32_16x16x32_bf16 v[88:91], v[168:171], v[212:215], v[88:91]
	v_mfma_f32_16x16x32_bf16 v[76:79], v[156:159], v[220:223], v[76:79]
	v_mfma_f32_16x16x32_bf16 v[72:75], v[168:171], v[220:223], v[72:75]
	v_mfma_f32_16x16x32_bf16 v[112:115], v[172:175], v[192:195], v[112:115]
	v_mfma_f32_16x16x32_bf16 v[104:107], v[184:187], v[192:195], v[104:107]
	v_mfma_f32_16x16x32_bf16 v[100:103], v[172:175], v[200:203], v[100:103]
	v_mfma_f32_16x16x32_bf16 v[96:99], v[184:187], v[200:203], v[96:99]
	v_mfma_f32_16x16x32_bf16 v[84:87], v[172:175], v[208:211], v[84:87]
	v_mfma_f32_16x16x32_bf16 v[80:83], v[184:187], v[208:211], v[80:83]
	v_mfma_f32_16x16x32_bf16 v[68:71], v[172:175], v[216:219], v[68:71]
	v_mfma_f32_16x16x32_bf16 v[64:67], v[184:187], v[216:219], v[64:67]
	v_mfma_f32_16x16x32_bf16 v[112:115], v[180:183], v[196:199], v[112:115]
	v_mfma_f32_16x16x32_bf16 v[104:107], v[188:191], v[196:199], v[104:107]
	v_mfma_f32_16x16x32_bf16 v[100:103], v[180:183], v[204:207], v[100:103]
	v_mfma_f32_16x16x32_bf16 v[96:99], v[188:191], v[204:207], v[96:99]
	v_mfma_f32_16x16x32_bf16 v[84:87], v[180:183], v[212:215], v[84:87]
	v_mfma_f32_16x16x32_bf16 v[80:83], v[188:191], v[212:215], v[80:83]
	s_setprio 2
	s_barrier
	v_mfma_f32_16x16x32_bf16 v[68:71], v[180:183], v[220:223], v[68:71]
	v_mfma_f32_16x16x32_bf16 v[64:67], v[188:191], v[220:223], v[64:67]
	s_setprio 0
	s_add_i32 s55, s44, s31
	v_lshl_add_u64 v[146:147], s[26:27], 0, v[130:131]
	s_mov_b32 m0, s55
	ds_read_b128 v[192:195], v151 offset:16384
	ds_read_b128 v[196:199], v151 offset:17408
	ds_read_b128 v[200:203], v151 offset:18432
	ds_read_b128 v[204:207], v151 offset:19456
	ds_read_b128 v[208:211], v151 offset:20480
	ds_read_b128 v[212:215], v151 offset:21504
	ds_read_b128 v[216:219], v151 offset:22528
	ds_read_b128 v[220:223], v151 offset:23552
	global_load_lds_dwordx4 v[146:147], off
	s_add_i32 m0, s55, 0x2000
	s_add_u32 s58, s26, 0x80000
	v_lshl_add_u64 v[164:165], s[26:27], 0, v[134:135]
	s_addc_u32 s59, s27, 0
	s_add_i32 s55, s45, s31
	global_load_lds_dwordx4 v[164:165], off
	v_lshl_add_u64 v[224:225], s[58:59], 0, v[130:131]
	s_mov_b32 m0, s55
	v_lshl_add_u64 v[226:227], s[28:29], 0, v[132:133]
	global_load_lds_dwordx4 v[224:225], off
	v_lshl_add_u64 v[224:225], s[58:59], 0, v[134:135]
	s_add_i32 m0, s55, 0x2000
	s_nop 0
	global_load_lds_dwordx4 v[224:225], off
	v_lshl_add_u64 v[224:225], s[28:29], 0, v[128:129]
	s_mov_b32 m0, s34
	s_nop 0
	global_load_lds_dwordx4 v[224:225], off
	s_mov_b32 m0, s35
	s_nop 0
	global_load_lds_dwordx4 v[226:227], off
	s_waitcnt vmcnt(8)
	s_waitcnt lgkmcnt(0)
	s_barrier
; #define PG8_STAGE(bufoff, gbase, voff) do { _Pragma("unroll") for (int _i = 0; _i < 2; ++_i) \
;         __builtin_amdgcn_global_load_lds((const unsigned*)((const char*)(gbase) + (voff)[_i]), (LAS unsigned*)(lds + (bufoff) + ldsw + _i * 8192), 16, 0, 0); } while (0)
; #define PG8_LDA(dst, b, h) do { _Pragma("unroll") for (int m = 0; m < 4; ++m) _Pragma("unroll") for (int k = 0; k < 2; ++k) dst[m][k] = *(const LAS bf16x8*)(lds + PG8_SA(b, h) + aoff + m * 2048 + k * 1024); } while (0)
; #define PG8_LDB(dst, b, h) do { _Pragma("unroll") for (int n = 0; n < 2; ++n) _Pragma("unroll") for (int k = 0; k < 2; ++k) dst[n][k] = *(const LAS bf16x8*)(lds + PG8_SB(b, h) + boff + n * 2048 + k * 1024); } while (0)
; #define PG8_MMA(ai, bj, At, Bt) do { __builtin_amdgcn_s_setprio(1); _Pragma("unroll") for (int m = 0; m < 4; ++m) _Pragma("unroll") for (int n = 0; n < 2; ++n) _Pragma("unroll") for (int k = 0; k < 2; ++k) \
;         acc[ai][bj][m][n] = __builtin_amdgcn_mfma_f32_16x16x32_bf16(Bt[n][k], At[m][k], acc[ai][bj][m][n], 0, 0, 0); __builtin_amdgcn_s_setprio(0); } while (0)
; #define PG8_WAIT_V(n) asm volatile("s_waitcnt vmcnt(" #n ")" ::: "memory")
; #define PG8_WAIT_L(n) asm volatile("s_waitcnt lgkmcnt(" #n ")" ::: "memory")
; #define PG8_BAR __builtin_amdgcn_s_barrier()
; #define PG8_SCHED __builtin_amdgcn_sched_barrier(0)
; template <class Epi, class Sched, bool ALIGN_EPI = true, bool SP2 = true>
; __device__ __forceinline__ void gemm_phase(LAS unsigned char* lds, const bf16_t* Ag, const bf16_t* Btg, const int K, const int lda, const int ldb, const Sched& S, const Epi& E) {
;     ...
;             PG8_WAIT_V(8); PG8_WAIT_L(0); PG8_BAR; PG8_MMA(1, 0, At, B0); PG8_MMA(1, 1, At, B1); PG8_BAR; PG8_SCHED;
;             PG8_LDB(B0, 1, 0); PG8_LDB(B1, 1, 1); PG8_SCHED; PG8_LDA(At, 1, 0); PG8_STAGE(PG8_SA(0, 1), a2 + hstepA, voffA);
;             PG8_WAIT_V(8); PG8_WAIT_L(0); PG8_BAR; PG8_MMA(0, 0, At, B0); PG8_MMA(0, 1, At, B1); PG8_BAR; PG8_SCHED;
	s_setprio 1
	s_waitcnt lgkmcnt(0)
	v_mfma_f32_16x16x32_bf16 v[60:63], v[152:155], v[192:195], v[60:63]
	v_mfma_f32_16x16x32_bf16 v[56:59], v[160:163], v[192:195], v[56:59]
	v_mfma_f32_16x16x32_bf16 v[44:47], v[152:155], v[200:203], v[44:47]
	v_mfma_f32_16x16x32_bf16 v[40:43], v[160:163], v[200:203], v[40:43]
	v_mfma_f32_16x16x32_bf16 v[28:31], v[152:155], v[208:211], v[28:31]
	v_mfma_f32_16x16x32_bf16 v[24:27], v[160:163], v[208:211], v[24:27]
	v_mfma_f32_16x16x32_bf16 v[12:15], v[152:155], v[216:219], v[12:15]
	v_mfma_f32_16x16x32_bf16 v[8:11], v[160:163], v[216:219], v[8:11]
	v_mfma_f32_16x16x32_bf16 v[60:63], v[156:159], v[196:199], v[60:63]
	v_mfma_f32_16x16x32_bf16 v[56:59], v[168:171], v[196:199], v[56:59]
	v_mfma_f32_16x16x32_bf16 v[44:47], v[156:159], v[204:207], v[44:47]
	v_mfma_f32_16x16x32_bf16 v[40:43], v[168:171], v[204:207], v[40:43]
	v_mfma_f32_16x16x32_bf16 v[28:31], v[156:159], v[212:215], v[28:31]
	v_mfma_f32_16x16x32_bf16 v[24:27], v[168:171], v[212:215], v[24:27]
	v_mfma_f32_16x16x32_bf16 v[12:15], v[156:159], v[220:223], v[12:15]
	v_mfma_f32_16x16x32_bf16 v[8:11], v[168:171], v[220:223], v[8:11]
	v_mfma_f32_16x16x32_bf16 v[52:55], v[172:175], v[192:195], v[52:55]
	v_mfma_f32_16x16x32_bf16 v[48:51], v[184:187], v[192:195], v[48:51]
	v_mfma_f32_16x16x32_bf16 v[36:39], v[172:175], v[200:203], v[36:39]
	v_mfma_f32_16x16x32_bf16 v[32:35], v[184:187], v[200:203], v[32:35]
	v_mfma_f32_16x16x32_bf16 v[20:23], v[172:175], v[208:211], v[20:23]
	v_mfma_f32_16x16x32_bf16 v[16:19], v[184:187], v[208:211], v[16:19]
	v_mfma_f32_16x16x32_bf16 v[4:7], v[172:175], v[216:219], v[4:7]
	v_mfma_f32_16x16x32_bf16 v[0:3], v[184:187], v[216:219], v[0:3]
	v_mfma_f32_16x16x32_bf16 v[52:55], v[180:183], v[196:199], v[52:55]
	v_mfma_f32_16x16x32_bf16 v[48:51], v[188:191], v[196:199], v[48:51]
	v_mfma_f32_16x16x32_bf16 v[36:39], v[180:183], v[204:207], v[36:39]
	v_mfma_f32_16x16x32_bf16 v[32:35], v[188:191], v[204:207], v[32:35]
	v_mfma_f32_16x16x32_bf16 v[20:23], v[180:183], v[212:215], v[20:23]
	v_mfma_f32_16x16x32_bf16 v[16:19], v[188:191], v[212:215], v[16:19]
	s_setprio 2
	s_barrier
	v_mfma_f32_16x16x32_bf16 v[4:7], v[180:183], v[220:223], v[4:7]
	v_mfma_f32_16x16x32_bf16 v[0:3], v[188:191], v[220:223], v[0:3]
	s_setprio 0
	s_add_i32 s55, 0, 0x18000
	s_add_i32 s58, 0, 0x1c000
	v_add_u32_e32 v168, s55, v148
	v_add_u32_e32 v188, s58, v148
	ds_read_b128 v[152:155], v168
	ds_read_b128 v[156:159], v168 offset:1024
	ds_read_b128 v[160:163], v168 offset:2048
	ds_read_b128 v[168:171], v168 offset:3072
	ds_read_b128 v[172:175], v188
	ds_read_b128 v[180:183], v188 offset:1024
	ds_read_b128 v[184:187], v188 offset:2048
	ds_read_b128 v[188:191], v188 offset:3072
	s_add_u32 s28, s28, 0x80000
	s_addc_u32 s29, s29, 0
	s_mov_b32 m0, s37
	v_lshl_add_u64 v[228:229], s[28:29], 0, v[128:129]
	ds_read_b128 v[192:195], v151 offset:32768
	ds_read_b128 v[196:199], v151 offset:33792
	ds_read_b128 v[200:203], v151 offset:34816
	ds_read_b128 v[204:207], v151 offset:35840
	ds_read_b128 v[208:211], v151 offset:36864
	ds_read_b128 v[212:215], v151 offset:37888
	ds_read_b128 v[216:219], v151 offset:38912
	ds_read_b128 v[220:223], v151 offset:39936
	global_load_lds_dwordx4 v[228:229], off
	v_lshl_add_u64 v[228:229], s[28:29], 0, v[132:133]
	s_mov_b32 m0, s38
	s_nop 0
	global_load_lds_dwordx4 v[228:229], off
	s_waitcnt vmcnt(8)
	s_waitcnt lgkmcnt(0)
	s_barrier
	s_setprio 1
	s_waitcnt lgkmcnt(0)
	v_mfma_f32_16x16x32_bf16 v[124:127], v[152:155], v[192:195], v[124:127]
	v_mfma_f32_16x16x32_bf16 v[120:123], v[160:163], v[192:195], v[120:123]
	v_mfma_f32_16x16x32_bf16 v[116:119], v[152:155], v[200:203], v[116:119]
	v_mfma_f32_16x16x32_bf16 v[108:111], v[160:163], v[200:203], v[108:111]
	v_mfma_f32_16x16x32_bf16 v[92:95], v[152:155], v[208:211], v[92:95]
	v_mfma_f32_16x16x32_bf16 v[88:91], v[160:163], v[208:211], v[88:91]
	v_mfma_f32_16x16x32_bf16 v[76:79], v[152:155], v[216:219], v[76:79]
	v_mfma_f32_16x16x32_bf16 v[72:75], v[160:163], v[216:219], v[72:75]
	v_mfma_f32_16x16x32_bf16 v[124:127], v[156:159], v[196:199], v[124:127]
	v_mfma_f32_16x16x32_bf16 v[120:123], v[168:171], v[196:199], v[120:123]
	v_mfma_f32_16x16x32_bf16 v[116:119], v[156:159], v[204:207], v[116:119]
	v_mfma_f32_16x16x32_bf16 v[108:111], v[168:171], v[204:207], v[108:111]
	v_mfma_f32_16x16x32_bf16 v[92:95], v[156:159], v[212:215], v[92:95]
	v_mfma_f32_16x16x32_bf16 v[88:91], v[168:171], v[212:215], v[88:91]
	v_mfma_f32_16x16x32_bf16 v[76:79], v[156:159], v[220:223], v[76:79]
	v_mfma_f32_16x16x32_bf16 v[72:75], v[168:171], v[220:223], v[72:75]
	v_mfma_f32_16x16x32_bf16 v[112:115], v[172:175], v[192:195], v[112:115]
	v_mfma_f32_16x16x32_bf16 v[104:107], v[184:187], v[192:195], v[104:107]
	v_mfma_f32_16x16x32_bf16 v[100:103], v[172:175], v[200:203], v[100:103]
	v_mfma_f32_16x16x32_bf16 v[96:99], v[184:187], v[200:203], v[96:99]
	v_mfma_f32_16x16x32_bf16 v[84:87], v[172:175], v[208:211], v[84:87]
	v_mfma_f32_16x16x32_bf16 v[80:83], v[184:187], v[208:211], v[80:83]
	v_mfma_f32_16x16x32_bf16 v[68:71], v[172:175], v[216:219], v[68:71]
	v_mfma_f32_16x16x32_bf16 v[64:67], v[184:187], v[216:219], v[64:67]
	v_mfma_f32_16x16x32_bf16 v[112:115], v[180:183], v[196:199], v[112:115]
	v_mfma_f32_16x16x32_bf16 v[104:107], v[188:191], v[196:199], v[104:107]
	v_mfma_f32_16x16x32_bf16 v[100:103], v[180:183], v[204:207], v[100:103]
	v_mfma_f32_16x16x32_bf16 v[96:99], v[188:191], v[204:207], v[96:99]
	v_mfma_f32_16x16x32_bf16 v[84:87], v[180:183], v[212:215], v[84:87]
	v_mfma_f32_16x16x32_bf16 v[80:83], v[188:191], v[212:215], v[80:83]
	s_setprio 2
	s_barrier
; #define PG8_STAGE(bufoff, gbase, voff) do { _Pragma("unroll") for (int _i = 0; _i < 2; ++_i) \
;         __builtin_amdgcn_global_load_lds((const unsigned*)((const char*)(gbase) + (voff)[_i]), (LAS unsigned*)(lds + (bufoff) + ldsw + _i * 8192), 16, 0, 0); } while (0)
; #define PG8_LDA(dst, b, h) do { _Pragma("unroll") for (int m = 0; m < 4; ++m) _Pragma("unroll") for (int k = 0; k < 2; ++k) dst[m][k] = *(const LAS bf16x8*)(lds + PG8_SA(b, h) + aoff + m * 2048 + k * 1024); } while (0)
; #define PG8_LDB(dst, b, h) do { _Pragma("unroll") for (int n = 0; n < 2; ++n) _Pragma("unroll") for (int k = 0; k < 2; ++k) dst[n][k] = *(const LAS bf16x8*)(lds + PG8_SB(b, h) + boff + n * 2048 + k * 1024); } while (0)
; template <class Epi, class Sched, bool ALIGN_EPI = true, bool SP2 = true>
; __device__ __forceinline__ void gemm_phase(LAS unsigned char* lds, const bf16_t* Ag, const bf16_t* Btg, const int K, const int lda, const int ldb, const Sched& S, const Epi& E) {
;     ...
;         for (int t = 0; t < nt; t += 2) {
;             const bool last = (t == nt - 2);
;             const char* a1 = cA + (size_t)(t + 1) * kstep;
;             const char* a2 = last ? nA : cA + (size_t)(t + 2) * kstep; const char* b2 = last ? nB : cB + (size_t)(t + 2) * kstep;
;             const char* a3 = a2 + kstep; const char* b3 = b2 + kstep;
;             if constexpr (SP2) {
;             PG8_LDB(B0, 0, 0); PG8_LDB(B1, 0, 1); PG8_SCHED; PG8_LDA(At, 0, 0); PG8_STAGE(PG8_SA(1, 1), a1 + hstepA, voffA);
;             PG8_WAIT_V(8); PG8_WAIT_L(0); PG8_BAR; PG8_MMA(0, 0, At, B0); PG8_MMA(0, 1, At, B1); PG8_BAR; PG8_SCHED;
;             PG8_LDA(At, 0, 1); PG8_STAGE(PG8_SB(0, 0), b2, voffB); PG8_STAGE(PG8_SB(0, 1), b2 + hstepB, voffB); PG8_STAGE(PG8_SA(0, 0), a2, voffA);
;             PG8_WAIT_V(8); PG8_WAIT_L(0); PG8_BAR; PG8_MMA(1, 0, At, B0); PG8_MMA(1, 1, At, B1); PG8_BAR; PG8_SCHED;
;             PG8_LDB(B0, 1, 0); PG8_LDB(B1, 1, 1); PG8_SCHED; PG8_LDA(At, 1, 0); PG8_STAGE(PG8_SA(0, 1), a2 + hstepA, voffA);
;             PG8_WAIT_V(8); PG8_WAIT_L(0); PG8_BAR; PG8_MMA(0, 0, At, B0); PG8_MMA(0, 1, At, B1); PG8_BAR; PG8_SCHED;
;             PG8_LDA(At, 1, 1); PG8_STAGE(PG8_SB(1, 0), b3, voffB); PG8_STAGE(PG8_SB(1, 1), b3 + hstepB, voffB); PG8_STAGE(PG8_SA(1, 0), a3, voffA);
;             PG8_WAIT_V(8); PG8_WAIT_L(0); PG8_BAR; PG8_MMA(1, 0, At, B0); PG8_MMA(1, 1, At, B1); PG8_BAR; PG8_SCHED;
	v_mfma_f32_16x16x32_bf16 v[68:71], v[180:183], v[220:223], v[68:71]
	v_mfma_f32_16x16x32_bf16 v[64:67], v[188:191], v[220:223], v[64:67]
	s_setprio 0
	s_add_i32 s28, s55, s31
	v_lshl_add_u64 v[146:147], v[146:147], 0, s[6:7]
	s_mov_b32 m0, s28
	ds_read_b128 v[192:195], v151 offset:49152
	ds_read_b128 v[196:199], v151 offset:50176
	ds_read_b128 v[200:203], v151 offset:51200
	ds_read_b128 v[204:207], v151 offset:52224
	ds_read_b128 v[208:211], v151 offset:53248
	ds_read_b128 v[212:215], v151 offset:54272
	ds_read_b128 v[216:219], v151 offset:55296
	ds_read_b128 v[220:223], v151 offset:56320
	global_load_lds_dwordx4 v[146:147], off
	s_add_i32 m0, s28, 0x2000
	s_add_u32 s26, s26, 0x80080
	v_lshl_add_u64 v[146:147], v[164:165], 0, s[6:7]
	s_addc_u32 s27, s27, 0
	s_add_i32 s28, s58, s31
	global_load_lds_dwordx4 v[146:147], off
	v_lshl_add_u64 v[146:147], s[26:27], 0, v[130:131]
	s_mov_b32 m0, s28
	s_nop 0
	global_load_lds_dwordx4 v[146:147], off
	v_lshl_add_u64 v[146:147], s[26:27], 0, v[134:135]
	s_add_i32 m0, s28, 0x2000
	s_nop 0
	global_load_lds_dwordx4 v[146:147], off
	v_lshl_add_u64 v[146:147], v[224:225], 0, s[6:7]
	s_mov_b32 m0, s40
	s_nop 0
	global_load_lds_dwordx4 v[146:147], off
	v_lshl_add_u64 v[146:147], v[226:227], 0, s[6:7]
	s_mov_b32 m0, s41
	s_nop 0
	global_load_lds_dwordx4 v[146:147], off
	s_waitcnt vmcnt(8)
	s_waitcnt lgkmcnt(0)
	s_barrier
	s_setprio 1
	s_waitcnt lgkmcnt(0)
	v_mfma_f32_16x16x32_bf16 v[60:63], v[152:155], v[192:195], v[60:63]
	v_mfma_f32_16x16x32_bf16 v[56:59], v[160:163], v[192:195], v[56:59]
	v_mfma_f32_16x16x32_bf16 v[44:47], v[152:155], v[200:203], v[44:47]
	v_mfma_f32_16x16x32_bf16 v[40:43], v[160:163], v[200:203], v[40:43]
	v_mfma_f32_16x16x32_bf16 v[28:31], v[152:155], v[208:211], v[28:31]
	v_mfma_f32_16x16x32_bf16 v[24:27], v[160:163], v[208:211], v[24:27]
	v_mfma_f32_16x16x32_bf16 v[12:15], v[152:155], v[216:219], v[12:15]
	v_mfma_f32_16x16x32_bf16 v[8:11], v[160:163], v[216:219], v[8:11]
	v_mfma_f32_16x16x32_bf16 v[60:63], v[156:159], v[196:199], v[60:63]
	v_mfma_f32_16x16x32_bf16 v[56:59], v[168:171], v[196:199], v[56:59]
	v_mfma_f32_16x16x32_bf16 v[44:47], v[156:159], v[204:207], v[44:47]
	v_mfma_f32_16x16x32_bf16 v[40:43], v[168:171], v[204:207], v[40:43]
	v_mfma_f32_16x16x32_bf16 v[28:31], v[156:159], v[212:215], v[28:31]
	v_mfma_f32_16x16x32_bf16 v[24:27], v[168:171], v[212:215], v[24:27]
	v_mfma_f32_16x16x32_bf16 v[12:15], v[156:159], v[220:223], v[12:15]
	v_mfma_f32_16x16x32_bf16 v[8:11], v[168:171], v[220:223], v[8:11]
	v_mfma_f32_16x16x32_bf16 v[52:55], v[172:175], v[192:195], v[52:55]
	v_mfma_f32_16x16x32_bf16 v[48:51], v[184:187], v[192:195], v[48:51]
	v_mfma_f32_16x16x32_bf16 v[36:39], v[172:175], v[200:203], v[36:39]
	v_mfma_f32_16x16x32_bf16 v[32:35], v[184:187], v[200:203], v[32:35]
	v_mfma_f32_16x16x32_bf16 v[20:23], v[172:175], v[208:211], v[20:23]
	v_mfma_f32_16x16x32_bf16 v[16:19], v[184:187], v[208:211], v[16:19]
	v_mfma_f32_16x16x32_bf16 v[4:7], v[172:175], v[216:219], v[4:7]
	v_mfma_f32_16x16x32_bf16 v[0:3], v[184:187], v[216:219], v[0:3]
	v_mfma_f32_16x16x32_bf16 v[52:55], v[180:183], v[196:199], v[52:55]
	v_mfma_f32_16x16x32_bf16 v[48:51], v[188:191], v[196:199], v[48:51]
	v_mfma_f32_16x16x32_bf16 v[36:39], v[180:183], v[204:207], v[36:39]
	v_mfma_f32_16x16x32_bf16 v[32:35], v[188:191], v[204:207], v[32:35]
	v_mfma_f32_16x16x32_bf16 v[20:23], v[180:183], v[212:215], v[20:23]
	v_mfma_f32_16x16x32_bf16 v[16:19], v[188:191], v[212:215], v[16:19]
	s_setprio 2
	s_barrier
	v_mfma_f32_16x16x32_bf16 v[4:7], v[180:183], v[220:223], v[4:7]
	v_mfma_f32_16x16x32_bf16 v[0:3], v[188:191], v[220:223], v[0:3]
	s_setprio 0
	s_add_i32 s54, s54, 2
	s_add_u32 s24, s24, 0x100
	s_addc_u32 s25, s25, 0
	s_add_u32 s52, s52, 0x100
	s_addc_u32 s53, s53, 0
	s_cmp_gt_u32 s54, 29
	s_cbranch_scc0 .LBB0_969
	s_and_b64 vcc, exec, s[8:9]
	s_cbranch_vccz .LBB0_972
	s_barrier

; #define PG8_STAGE(bufoff, gbase, voff) do { _Pragma("unroll") for (int _i = 0; _i < 2; ++_i) \
;         __builtin_amdgcn_global_load_lds((const unsigned*)((const char*)(gbase) + (voff)[_i]), (LAS unsigned*)(lds + (bufoff) + ldsw + _i * 8192), 16, 0, 0); } while (0)
; #define PG8_LDA(dst, b, h) do { _Pragma("unroll") for (int m = 0; m < 4; ++m) _Pragma("unroll") for (int k = 0; k < 2; ++k) dst[m][k] = *(const LAS bf16x8*)(lds + PG8_SA(b, h) + aoff + m * 2048 + k * 1024); } while (0)
; #define PG8_LDB(dst, b, h) do { _Pragma("unroll") for (int n = 0; n < 2; ++n) _Pragma("unroll") for (int k = 0; k < 2; ++k) dst[n][k] = *(const LAS bf16x8*)(lds + PG8_SB(b, h) + boff + n * 2048 + k * 1024); } while (0)
; #define PG8_MMA(ai, bj, At, Bt) do { __builtin_amdgcn_s_setprio(1); _Pragma("unroll") for (int m = 0; m < 4; ++m) _Pragma("unroll") for (int n = 0; n < 2; ++n) _Pragma("unroll") for (int k = 0; k < 2; ++k) \
;         acc[ai][bj][m][n] = __builtin_amdgcn_mfma_f32_16x16x32_bf16(Bt[n][k], At[m][k], acc[ai][bj][m][n], 0, 0, 0); __builtin_amdgcn_s_setprio(0); } while (0)
; #define PG8_WAIT_V(n) asm volatile("s_waitcnt vmcnt(" #n ")" ::: "memory")
; #define PG8_WAIT_L(n) asm volatile("s_waitcnt lgkmcnt(" #n ")" ::: "memory")
; #define PG8_BAR __builtin_amdgcn_s_barrier()
; #define PG8_SCHED __builtin_amdgcn_sched_barrier(0)
; template <class Epi, class Sched, bool ALIGN_EPI = true, bool SP2 = true>
; __device__ __forceinline__ void gemm_phase(LAS unsigned char* lds, const bf16_t* Ag, const bf16_t* Btg, const int K, const int lda, const int ldb, const Sched& S, const Epi& E) {
;     ...
;         for (int t = 0; t < nt; t += 2) {
;             const bool last = (t == nt - 2);
;             const char* a1 = cA + (size_t)(t + 1) * kstep;
;             const char* a2 = last ? nA : cA + (size_t)(t + 2) * kstep; const char* b2 = last ? nB : cB + (size_t)(t + 2) * kstep;
;             const char* a3 = a2 + kstep; const char* b3 = b2 + kstep;
;             if constexpr (SP2) {
;             PG8_LDB(B0, 0, 0); PG8_LDB(B1, 0, 1); PG8_SCHED; PG8_LDA(At, 0, 0); PG8_STAGE(PG8_SA(1, 1), a1 + hstepA, voffA);
;             PG8_WAIT_V(8); PG8_WAIT_L(0); PG8_BAR; PG8_MMA(0, 0, At, B0); PG8_MMA(0, 1, At, B1); PG8_BAR; PG8_SCHED;
;             PG8_LDA(At, 0, 1); PG8_STAGE(PG8_SB(0, 0), b2, voffB); PG8_STAGE(PG8_SB(0, 1), b2 + hstepB, voffB); PG8_STAGE(PG8_SA(0, 0), a2, voffA);
.LBB0_1236:
	ds_read_b128 v[152:155], v149
	ds_read_b128 v[156:159], v149 offset:1024
	ds_read_b128 v[160:163], v149 offset:2048
	ds_read_b128 v[168:171], v149 offset:3072
	ds_read_b128 v[172:175], v150
	ds_read_b128 v[180:183], v150 offset:1024
	ds_read_b128 v[184:187], v150 offset:2048
	ds_read_b128 v[188:191], v150 offset:3072
	s_add_u32 s44, s42, 0xfffc0080
	s_addc_u32 s45, s43, -1
	s_cmp_eq_u32 s70, 12
	s_cselect_b32 s51, s33, s45
	s_cselect_b32 s50, s65, s44
	s_cselect_b32 s45, s66, s69
	s_cselect_b32 s44, s67, s68
	v_lshl_add_u64 v[146:147], s[42:43], 0, v[138:139]
	s_add_i32 m0, s41, 0xc000
	ds_read_b128 v[192:195], v151
	ds_read_b128 v[196:199], v151 offset:1024
	ds_read_b128 v[200:203], v151 offset:2048
	ds_read_b128 v[204:207], v151 offset:3072
	ds_read_b128 v[208:211], v151 offset:4096
	ds_read_b128 v[212:215], v151 offset:5120
	ds_read_b128 v[216:219], v151 offset:6144
	ds_read_b128 v[220:223], v151 offset:7168
	global_load_lds_dwordx4 v[146:147], off
	v_lshl_add_u64 v[146:147], s[42:43], 0, v[140:141]
	s_add_i32 m0, s41, 0xe000
	s_nop 0
	global_load_lds_dwordx4 v[146:147], off
	s_waitcnt vmcnt(8)
	s_waitcnt lgkmcnt(0)
	s_barrier
	s_setprio 1
	s_waitcnt lgkmcnt(0)
	v_mfma_f32_16x16x32_bf16 v[124:127], v[152:155], v[192:195], v[124:127]
	v_mfma_f32_16x16x32_bf16 v[120:123], v[160:163], v[192:195], v[120:123]
	v_mfma_f32_16x16x32_bf16 v[116:119], v[152:155], v[200:203], v[116:119]
	v_mfma_f32_16x16x32_bf16 v[108:111], v[160:163], v[200:203], v[108:111]
	v_mfma_f32_16x16x32_bf16 v[92:95], v[152:155], v[208:211], v[92:95]
	v_mfma_f32_16x16x32_bf16 v[88:91], v[160:163], v[208:211], v[88:91]
	v_mfma_f32_16x16x32_bf16 v[76:79], v[152:155], v[216:219], v[76:79]
	v_mfma_f32_16x16x32_bf16 v[72:75], v[160:163], v[216:219], v[72:75]
	v_mfma_f32_16x16x32_bf16 v[124:127], v[156:159], v[196:199], v[124:127]
	v_mfma_f32_16x16x32_bf16 v[120:123], v[168:171], v[196:199], v[120:123]
	v_mfma_f32_16x16x32_bf16 v[116:119], v[156:159], v[204:207], v[116:119]
	v_mfma_f32_16x16x32_bf16 v[108:111], v[168:171], v[204:207], v[108:111]
	v_mfma_f32_16x16x32_bf16 v[92:95], v[156:159], v[212:215], v[92:95]
	v_mfma_f32_16x16x32_bf16 v[88:91], v[168:171], v[212:215], v[88:91]
	v_mfma_f32_16x16x32_bf16 v[76:79], v[156:159], v[220:223], v[76:79]
	v_mfma_f32_16x16x32_bf16 v[72:75], v[168:171], v[220:223], v[72:75]
	v_mfma_f32_16x16x32_bf16 v[112:115], v[172:175], v[192:195], v[112:115]
	v_mfma_f32_16x16x32_bf16 v[104:107], v[184:187], v[192:195], v[104:107]
	v_mfma_f32_16x16x32_bf16 v[100:103], v[172:175], v[200:203], v[100:103]
	v_mfma_f32_16x16x32_bf16 v[96:99], v[184:187], v[200:203], v[96:99]
	v_mfma_f32_16x16x32_bf16 v[84:87], v[172:175], v[208:211], v[84:87]
	v_mfma_f32_16x16x32_bf16 v[80:83], v[184:187], v[208:211], v[80:83]
	v_mfma_f32_16x16x32_bf16 v[68:71], v[172:175], v[216:219], v[68:71]
	v_mfma_f32_16x16x32_bf16 v[64:67], v[184:187], v[216:219], v[64:67]
	v_mfma_f32_16x16x32_bf16 v[112:115], v[180:183], v[196:199], v[112:115]
	v_mfma_f32_16x16x32_bf16 v[104:107], v[188:191], v[196:199], v[104:107]
	v_mfma_f32_16x16x32_bf16 v[100:103], v[180:183], v[204:207], v[100:103]
	v_mfma_f32_16x16x32_bf16 v[96:99], v[188:191], v[204:207], v[96:99]
	v_mfma_f32_16x16x32_bf16 v[84:87], v[180:183], v[212:215], v[84:87]
	v_mfma_f32_16x16x32_bf16 v[80:83], v[188:191], v[212:215], v[80:83]
	s_setprio 2
	s_barrier
	v_mfma_f32_16x16x32_bf16 v[68:71], v[180:183], v[220:223], v[68:71]
	v_mfma_f32_16x16x32_bf16 v[64:67], v[188:191], v[220:223], v[64:67]
	s_setprio 0
	s_add_i32 s71, s60, s40
	v_lshl_add_u64 v[146:147], s[44:45], 0, v[130:131]
	s_mov_b32 m0, s71
	ds_read_b128 v[192:195], v151 offset:16384
	ds_read_b128 v[196:199], v151 offset:17408
	ds_read_b128 v[200:203], v151 offset:18432
	ds_read_b128 v[204:207], v151 offset:19456
	ds_read_b128 v[208:211], v151 offset:20480
	ds_read_b128 v[212:215], v151 offset:21504
	ds_read_b128 v[216:219], v151 offset:22528
	ds_read_b128 v[220:223], v151 offset:23552
	global_load_lds_dwordx4 v[146:147], off
	s_add_i32 m0, s71, 0x2000
	s_add_u32 s72, s44, 0x40000
	v_lshl_add_u64 v[164:165], s[44:45], 0, v[134:135]
	s_addc_u32 s73, s45, 0
	s_add_i32 s71, s61, s40
	global_load_lds_dwordx4 v[164:165], off
	v_lshl_add_u64 v[224:225], s[72:73], 0, v[130:131]
	s_mov_b32 m0, s71
	v_lshl_add_u64 v[226:227], s[50:51], 0, v[132:133]
	global_load_lds_dwordx4 v[224:225], off
	v_lshl_add_u64 v[224:225], s[72:73], 0, v[134:135]
	s_add_i32 m0, s71, 0x2000
	s_nop 0
	global_load_lds_dwordx4 v[224:225], off
	v_lshl_add_u64 v[224:225], s[50:51], 0, v[128:129]
	s_mov_b32 m0, s41
	s_nop 0
	global_load_lds_dwordx4 v[224:225], off
	s_mov_b32 m0, s46
	s_nop 0
	global_load_lds_dwordx4 v[226:227], off
	s_waitcnt vmcnt(8)
	s_waitcnt lgkmcnt(0)
	s_barrier
; #define PG8_STAGE(bufoff, gbase, voff) do { _Pragma("unroll") for (int _i = 0; _i < 2; ++_i) \
;         __builtin_amdgcn_global_load_lds((const unsigned*)((const char*)(gbase) + (voff)[_i]), (LAS unsigned*)(lds + (bufoff) + ldsw + _i * 8192), 16, 0, 0); } while (0)
; #define PG8_LDA(dst, b, h) do { _Pragma("unroll") for (int m = 0; m < 4; ++m) _Pragma("unroll") for (int k = 0; k < 2; ++k) dst[m][k] = *(const LAS bf16x8*)(lds + PG8_SA(b, h) + aoff + m * 2048 + k * 1024); } while (0)
; #define PG8_LDB(dst, b, h) do { _Pragma("unroll") for (int n = 0; n < 2; ++n) _Pragma("unroll") for (int k = 0; k < 2; ++k) dst[n][k] = *(const LAS bf16x8*)(lds + PG8_SB(b, h) + boff + n * 2048 + k * 1024); } while (0)
; #define PG8_MMA(ai, bj, At, Bt) do { __builtin_amdgcn_s_setprio(1); _Pragma("unroll") for (int m = 0; m < 4; ++m) _Pragma("unroll") for (int n = 0; n < 2; ++n) _Pragma("unroll") for (int k = 0; k < 2; ++k) \
;         acc[ai][bj][m][n] = __builtin_amdgcn_mfma_f32_16x16x32_bf16(Bt[n][k], At[m][k], acc[ai][bj][m][n], 0, 0, 0); __builtin_amdgcn_s_setprio(0); } while (0)
; #define PG8_WAIT_V(n) asm volatile("s_waitcnt vmcnt(" #n ")" ::: "memory")
; #define PG8_WAIT_L(n) asm volatile("s_waitcnt lgkmcnt(" #n ")" ::: "memory")
; #define PG8_BAR __builtin_amdgcn_s_barrier()
; #define PG8_SCHED __builtin_amdgcn_sched_barrier(0)
; template <class Epi, class Sched, bool ALIGN_EPI = true, bool SP2 = true>
; __device__ __forceinline__ void gemm_phase(LAS unsigned char* lds, const bf16_t* Ag, const bf16_t* Btg, const int K, const int lda, const int ldb, const Sched& S, const Epi& E) {
;     ...
;             PG8_WAIT_V(8); PG8_WAIT_L(0); PG8_BAR; PG8_MMA(1, 0, At, B0); PG8_MMA(1, 1, At, B1); PG8_BAR; PG8_SCHED;
;             PG8_LDB(B0, 1, 0); PG8_LDB(B1, 1, 1); PG8_SCHED; PG8_LDA(At, 1, 0); PG8_STAGE(PG8_SA(0, 1), a2 + hstepA, voffA);
;             PG8_WAIT_V(8); PG8_WAIT_L(0); PG8_BAR; PG8_MMA(0, 0, At, B0); PG8_MMA(0, 1, At, B1); PG8_BAR; PG8_SCHED;
	s_setprio 1
	s_waitcnt lgkmcnt(0)
	v_mfma_f32_16x16x32_bf16 v[60:63], v[152:155], v[192:195], v[60:63]
	v_mfma_f32_16x16x32_bf16 v[56:59], v[160:163], v[192:195], v[56:59]
	v_mfma_f32_16x16x32_bf16 v[44:47], v[152:155], v[200:203], v[44:47]
	v_mfma_f32_16x16x32_bf16 v[40:43], v[160:163], v[200:203], v[40:43]
	v_mfma_f32_16x16x32_bf16 v[28:31], v[152:155], v[208:211], v[28:31]
	v_mfma_f32_16x16x32_bf16 v[24:27], v[160:163], v[208:211], v[24:27]
	v_mfma_f32_16x16x32_bf16 v[12:15], v[152:155], v[216:219], v[12:15]
	v_mfma_f32_16x16x32_bf16 v[8:11], v[160:163], v[216:219], v[8:11]
	v_mfma_f32_16x16x32_bf16 v[60:63], v[156:159], v[196:199], v[60:63]
	v_mfma_f32_16x16x32_bf16 v[56:59], v[168:171], v[196:199], v[56:59]
	v_mfma_f32_16x16x32_bf16 v[44:47], v[156:159], v[204:207], v[44:47]
	v_mfma_f32_16x16x32_bf16 v[40:43], v[168:171], v[204:207], v[40:43]
	v_mfma_f32_16x16x32_bf16 v[28:31], v[156:159], v[212:215], v[28:31]
	v_mfma_f32_16x16x32_bf16 v[24:27], v[168:171], v[212:215], v[24:27]
	v_mfma_f32_16x16x32_bf16 v[12:15], v[156:159], v[220:223], v[12:15]
	v_mfma_f32_16x16x32_bf16 v[8:11], v[168:171], v[220:223], v[8:11]
	v_mfma_f32_16x16x32_bf16 v[52:55], v[172:175], v[192:195], v[52:55]
	v_mfma_f32_16x16x32_bf16 v[48:51], v[184:187], v[192:195], v[48:51]
	v_mfma_f32_16x16x32_bf16 v[36:39], v[172:175], v[200:203], v[36:39]
	v_mfma_f32_16x16x32_bf16 v[32:35], v[184:187], v[200:203], v[32:35]
	v_mfma_f32_16x16x32_bf16 v[20:23], v[172:175], v[208:211], v[20:23]
	v_mfma_f32_16x16x32_bf16 v[16:19], v[184:187], v[208:211], v[16:19]
	v_mfma_f32_16x16x32_bf16 v[4:7], v[172:175], v[216:219], v[4:7]
	v_mfma_f32_16x16x32_bf16 v[0:3], v[184:187], v[216:219], v[0:3]
	v_mfma_f32_16x16x32_bf16 v[52:55], v[180:183], v[196:199], v[52:55]
	v_mfma_f32_16x16x32_bf16 v[48:51], v[188:191], v[196:199], v[48:51]
	v_mfma_f32_16x16x32_bf16 v[36:39], v[180:183], v[204:207], v[36:39]
	v_mfma_f32_16x16x32_bf16 v[32:35], v[188:191], v[204:207], v[32:35]
	v_mfma_f32_16x16x32_bf16 v[20:23], v[180:183], v[212:215], v[20:23]
	v_mfma_f32_16x16x32_bf16 v[16:19], v[188:191], v[212:215], v[16:19]
	s_setprio 2
	s_barrier
	v_mfma_f32_16x16x32_bf16 v[4:7], v[180:183], v[220:223], v[4:7]
	v_mfma_f32_16x16x32_bf16 v[0:3], v[188:191], v[220:223], v[0:3]
	s_setprio 0
	s_add_i32 s71, 0, 0x18000
	s_add_i32 s72, 0, 0x1c000
	v_add_u32_e32 v168, s71, v148
	v_add_u32_e32 v188, s72, v148
	ds_read_b128 v[152:155], v168
	ds_read_b128 v[156:159], v168 offset:1024
	ds_read_b128 v[160:163], v168 offset:2048
	ds_read_b128 v[168:171], v168 offset:3072
	ds_read_b128 v[172:175], v188
	ds_read_b128 v[180:183], v188 offset:1024
	ds_read_b128 v[184:187], v188 offset:2048
	ds_read_b128 v[188:191], v188 offset:3072
	s_add_u32 s50, s50, 0x40000
	s_addc_u32 s51, s51, 0
	s_mov_b32 m0, s47
	v_lshl_add_u64 v[228:229], s[50:51], 0, v[128:129]
	ds_read_b128 v[192:195], v151 offset:32768
	ds_read_b128 v[196:199], v151 offset:33792
	ds_read_b128 v[200:203], v151 offset:34816
	ds_read_b128 v[204:207], v151 offset:35840
	ds_read_b128 v[208:211], v151 offset:36864
	ds_read_b128 v[212:215], v151 offset:37888
	ds_read_b128 v[216:219], v151 offset:38912
	ds_read_b128 v[220:223], v151 offset:39936
	global_load_lds_dwordx4 v[228:229], off
	v_lshl_add_u64 v[228:229], s[50:51], 0, v[132:133]
	s_mov_b32 m0, s52
	s_nop 0
	global_load_lds_dwordx4 v[228:229], off
	s_waitcnt vmcnt(8)
	s_waitcnt lgkmcnt(0)
	s_barrier
	s_setprio 1
	s_waitcnt lgkmcnt(0)
	v_mfma_f32_16x16x32_bf16 v[124:127], v[152:155], v[192:195], v[124:127]
	v_mfma_f32_16x16x32_bf16 v[120:123], v[160:163], v[192:195], v[120:123]
	v_mfma_f32_16x16x32_bf16 v[116:119], v[152:155], v[200:203], v[116:119]
	v_mfma_f32_16x16x32_bf16 v[108:111], v[160:163], v[200:203], v[108:111]
	v_mfma_f32_16x16x32_bf16 v[92:95], v[152:155], v[208:211], v[92:95]
	v_mfma_f32_16x16x32_bf16 v[88:91], v[160:163], v[208:211], v[88:91]
	v_mfma_f32_16x16x32_bf16 v[76:79], v[152:155], v[216:219], v[76:79]
	v_mfma_f32_16x16x32_bf16 v[72:75], v[160:163], v[216:219], v[72:75]
	v_mfma_f32_16x16x32_bf16 v[124:127], v[156:159], v[196:199], v[124:127]
	v_mfma_f32_16x16x32_bf16 v[120:123], v[168:171], v[196:199], v[120:123]
	v_mfma_f32_16x16x32_bf16 v[116:119], v[156:159], v[204:207], v[116:119]
	v_mfma_f32_16x16x32_bf16 v[108:111], v[168:171], v[204:207], v[108:111]
	v_mfma_f32_16x16x32_bf16 v[92:95], v[156:159], v[212:215], v[92:95]
	v_mfma_f32_16x16x32_bf16 v[88:91], v[168:171], v[212:215], v[88:91]
	v_mfma_f32_16x16x32_bf16 v[76:79], v[156:159], v[220:223], v[76:79]
	v_mfma_f32_16x16x32_bf16 v[72:75], v[168:171], v[220:223], v[72:75]
	v_mfma_f32_16x16x32_bf16 v[112:115], v[172:175], v[192:195], v[112:115]
	v_mfma_f32_16x16x32_bf16 v[104:107], v[184:187], v[192:195], v[104:107]
	v_mfma_f32_16x16x32_bf16 v[100:103], v[172:175], v[200:203], v[100:103]
	v_mfma_f32_16x16x32_bf16 v[96:99], v[184:187], v[200:203], v[96:99]
	v_mfma_f32_16x16x32_bf16 v[84:87], v[172:175], v[208:211], v[84:87]
	v_mfma_f32_16x16x32_bf16 v[80:83], v[184:187], v[208:211], v[80:83]
	v_mfma_f32_16x16x32_bf16 v[68:71], v[172:175], v[216:219], v[68:71]
	v_mfma_f32_16x16x32_bf16 v[64:67], v[184:187], v[216:219], v[64:67]
	v_mfma_f32_16x16x32_bf16 v[112:115], v[180:183], v[196:199], v[112:115]
	v_mfma_f32_16x16x32_bf16 v[104:107], v[188:191], v[196:199], v[104:107]
	v_mfma_f32_16x16x32_bf16 v[100:103], v[180:183], v[204:207], v[100:103]
	v_mfma_f32_16x16x32_bf16 v[96:99], v[188:191], v[204:207], v[96:99]
	v_mfma_f32_16x16x32_bf16 v[84:87], v[180:183], v[212:215], v[84:87]
	v_mfma_f32_16x16x32_bf16 v[80:83], v[188:191], v[212:215], v[80:83]
	s_setprio 2
	s_barrier
; #define PG8_STAGE(bufoff, gbase, voff) do { _Pragma("unroll") for (int _i = 0; _i < 2; ++_i) \
;         __builtin_amdgcn_global_load_lds((const unsigned*)((const char*)(gbase) + (voff)[_i]), (LAS unsigned*)(lds + (bufoff) + ldsw + _i * 8192), 16, 0, 0); } while (0)
; #define PG8_LDA(dst, b, h) do { _Pragma("unroll") for (int m = 0; m < 4; ++m) _Pragma("unroll") for (int k = 0; k < 2; ++k) dst[m][k] = *(const LAS bf16x8*)(lds + PG8_SA(b, h) + aoff + m * 2048 + k * 1024); } while (0)
; #define PG8_LDB(dst, b, h) do { _Pragma("unroll") for (int n = 0; n < 2; ++n) _Pragma("unroll") for (int k = 0; k < 2; ++k) dst[n][k] = *(const LAS bf16x8*)(lds + PG8_SB(b, h) + boff + n * 2048 + k * 1024); } while (0)
; template <class Epi, class Sched, bool ALIGN_EPI = true, bool SP2 = true>
; __device__ __forceinline__ void gemm_phase(LAS unsigned char* lds, const bf16_t* Ag, const bf16_t* Btg, const int K, const int lda, const int ldb, const Sched& S, const Epi& E) {
;     ...
;         for (int t = 0; t < nt; t += 2) {
;             const bool last = (t == nt - 2);
;             const char* a1 = cA + (size_t)(t + 1) * kstep;
;             const char* a2 = last ? nA : cA + (size_t)(t + 2) * kstep; const char* b2 = last ? nB : cB + (size_t)(t + 2) * kstep;
;             const char* a3 = a2 + kstep; const char* b3 = b2 + kstep;
;             if constexpr (SP2) {
;             PG8_LDB(B0, 0, 0); PG8_LDB(B1, 0, 1); PG8_SCHED; PG8_LDA(At, 0, 0); PG8_STAGE(PG8_SA(1, 1), a1 + hstepA, voffA);
;             PG8_WAIT_V(8); PG8_WAIT_L(0); PG8_BAR; PG8_MMA(0, 0, At, B0); PG8_MMA(0, 1, At, B1); PG8_BAR; PG8_SCHED;
;             PG8_LDA(At, 0, 1); PG8_STAGE(PG8_SB(0, 0), b2, voffB); PG8_STAGE(PG8_SB(0, 1), b2 + hstepB, voffB); PG8_STAGE(PG8_SA(0, 0), a2, voffA);
;             PG8_WAIT_V(8); PG8_WAIT_L(0); PG8_BAR; PG8_MMA(1, 0, At, B0); PG8_MMA(1, 1, At, B1); PG8_BAR; PG8_SCHED;
;             PG8_LDB(B0, 1, 0); PG8_LDB(B1, 1, 1); PG8_SCHED; PG8_LDA(At, 1, 0); PG8_STAGE(PG8_SA(0, 1), a2 + hstepA, voffA);
;             PG8_WAIT_V(8); PG8_WAIT_L(0); PG8_BAR; PG8_MMA(0, 0, At, B0); PG8_MMA(0, 1, At, B1); PG8_BAR; PG8_SCHED;
;             PG8_LDA(At, 1, 1); PG8_STAGE(PG8_SB(1, 0), b3, voffB); PG8_STAGE(PG8_SB(1, 1), b3 + hstepB, voffB); PG8_STAGE(PG8_SA(1, 0), a3, voffA);
;             PG8_WAIT_V(8); PG8_WAIT_L(0); PG8_BAR; PG8_MMA(1, 0, At, B0); PG8_MMA(1, 1, At, B1); PG8_BAR; PG8_SCHED;
	v_mfma_f32_16x16x32_bf16 v[68:71], v[180:183], v[220:223], v[68:71]
	v_mfma_f32_16x16x32_bf16 v[64:67], v[188:191], v[220:223], v[64:67]
	s_setprio 0
	s_add_i32 s50, s71, s40
	v_lshl_add_u64 v[146:147], v[146:147], 0, s[8:9]
	s_mov_b32 m0, s50
	ds_read_b128 v[192:195], v151 offset:49152
	ds_read_b128 v[196:199], v151 offset:50176
	ds_read_b128 v[200:203], v151 offset:51200
	ds_read_b128 v[204:207], v151 offset:52224
	ds_read_b128 v[208:211], v151 offset:53248
	ds_read_b128 v[212:215], v151 offset:54272
	ds_read_b128 v[216:219], v151 offset:55296
	ds_read_b128 v[220:223], v151 offset:56320
	global_load_lds_dwordx4 v[146:147], off
	s_add_i32 m0, s50, 0x2000
	s_add_u32 s44, s44, 0x40080
	v_lshl_add_u64 v[146:147], v[164:165], 0, s[8:9]
	s_addc_u32 s45, s45, 0
	s_add_i32 s50, s72, s40
	global_load_lds_dwordx4 v[146:147], off
	v_lshl_add_u64 v[146:147], s[44:45], 0, v[130:131]
	s_mov_b32 m0, s50
	s_nop 0
	global_load_lds_dwordx4 v[146:147], off
	v_lshl_add_u64 v[146:147], s[44:45], 0, v[134:135]
	s_add_i32 m0, s50, 0x2000
	s_nop 0
	global_load_lds_dwordx4 v[146:147], off
	v_lshl_add_u64 v[146:147], v[224:225], 0, s[8:9]
	s_mov_b32 m0, s54
	s_nop 0
	global_load_lds_dwordx4 v[146:147], off
	v_lshl_add_u64 v[146:147], v[226:227], 0, s[8:9]
	s_mov_b32 m0, s55
	s_nop 0
	global_load_lds_dwordx4 v[146:147], off
	s_waitcnt vmcnt(8)
	s_waitcnt lgkmcnt(0)
	s_barrier
	s_setprio 1
	s_waitcnt lgkmcnt(0)
	v_mfma_f32_16x16x32_bf16 v[60:63], v[152:155], v[192:195], v[60:63]
	v_mfma_f32_16x16x32_bf16 v[56:59], v[160:163], v[192:195], v[56:59]
	v_mfma_f32_16x16x32_bf16 v[44:47], v[152:155], v[200:203], v[44:47]
	v_mfma_f32_16x16x32_bf16 v[40:43], v[160:163], v[200:203], v[40:43]
	v_mfma_f32_16x16x32_bf16 v[28:31], v[152:155], v[208:211], v[28:31]
	v_mfma_f32_16x16x32_bf16 v[24:27], v[160:163], v[208:211], v[24:27]
	v_mfma_f32_16x16x32_bf16 v[12:15], v[152:155], v[216:219], v[12:15]
	v_mfma_f32_16x16x32_bf16 v[8:11], v[160:163], v[216:219], v[8:11]
	v_mfma_f32_16x16x32_bf16 v[60:63], v[156:159], v[196:199], v[60:63]
	v_mfma_f32_16x16x32_bf16 v[56:59], v[168:171], v[196:199], v[56:59]
	v_mfma_f32_16x16x32_bf16 v[44:47], v[156:159], v[204:207], v[44:47]
	v_mfma_f32_16x16x32_bf16 v[40:43], v[168:171], v[204:207], v[40:43]
	v_mfma_f32_16x16x32_bf16 v[28:31], v[156:159], v[212:215], v[28:31]
	v_mfma_f32_16x16x32_bf16 v[24:27], v[168:171], v[212:215], v[24:27]
	v_mfma_f32_16x16x32_bf16 v[12:15], v[156:159], v[220:223], v[12:15]
	v_mfma_f32_16x16x32_bf16 v[8:11], v[168:171], v[220:223], v[8:11]
	v_mfma_f32_16x16x32_bf16 v[52:55], v[172:175], v[192:195], v[52:55]
	v_mfma_f32_16x16x32_bf16 v[48:51], v[184:187], v[192:195], v[48:51]
	v_mfma_f32_16x16x32_bf16 v[36:39], v[172:175], v[200:203], v[36:39]
	v_mfma_f32_16x16x32_bf16 v[32:35], v[184:187], v[200:203], v[32:35]
	v_mfma_f32_16x16x32_bf16 v[20:23], v[172:175], v[208:211], v[20:23]
	v_mfma_f32_16x16x32_bf16 v[16:19], v[184:187], v[208:211], v[16:19]
	v_mfma_f32_16x16x32_bf16 v[4:7], v[172:175], v[216:219], v[4:7]
	v_mfma_f32_16x16x32_bf16 v[0:3], v[184:187], v[216:219], v[0:3]
	v_mfma_f32_16x16x32_bf16 v[52:55], v[180:183], v[196:199], v[52:55]
	v_mfma_f32_16x16x32_bf16 v[48:51], v[188:191], v[196:199], v[48:51]
	v_mfma_f32_16x16x32_bf16 v[36:39], v[180:183], v[204:207], v[36:39]
	v_mfma_f32_16x16x32_bf16 v[32:35], v[188:191], v[204:207], v[32:35]
	v_mfma_f32_16x16x32_bf16 v[20:23], v[180:183], v[212:215], v[20:23]
	v_mfma_f32_16x16x32_bf16 v[16:19], v[188:191], v[212:215], v[16:19]
	s_setprio 2
	s_barrier
	v_mfma_f32_16x16x32_bf16 v[4:7], v[180:183], v[220:223], v[4:7]
	v_mfma_f32_16x16x32_bf16 v[0:3], v[188:191], v[220:223], v[0:3]
	s_setprio 0
	s_add_i32 s70, s70, 2
	s_add_u32 s42, s42, 0x100
	s_addc_u32 s43, s43, 0
	s_add_u32 s68, s68, 0x100
	s_addc_u32 s69, s69, 0
	s_cmp_gt_u32 s70, 13
	s_cbranch_scc0 .LBB0_1236
	v_readlane_b32 s80, v244, 16
	s_and_b64 vcc, exec, s[10:11]
	v_readlane_b32 s81, v244, 17
	s_cbranch_vccz .LBB0_1239
	s_barrier

; #define PG8_STAGE(bufoff, gbase, voff) do { _Pragma("unroll") for (int _i = 0; _i < 2; ++_i) \
;         __builtin_amdgcn_global_load_lds((const unsigned*)((const char*)(gbase) + (voff)[_i]), (LAS unsigned*)(lds + (bufoff) + ldsw + _i * 8192), 16, 0, 0); } while (0)
; #define PG8_LDA(dst, b, h) do { _Pragma("unroll") for (int m = 0; m < 4; ++m) _Pragma("unroll") for (int k = 0; k < 2; ++k) dst[m][k] = *(const LAS bf16x8*)(lds + PG8_SA(b, h) + aoff + m * 2048 + k * 1024); } while (0)
; #define PG8_LDB(dst, b, h) do { _Pragma("unroll") for (int n = 0; n < 2; ++n) _Pragma("unroll") for (int k = 0; k < 2; ++k) dst[n][k] = *(const LAS bf16x8*)(lds + PG8_SB(b, h) + boff + n * 2048 + k * 1024); } while (0)
; #define PG8_MMA(ai, bj, At, Bt) do { __builtin_amdgcn_s_setprio(1); _Pragma("unroll") for (int m = 0; m < 4; ++m) _Pragma("unroll") for (int n = 0; n < 2; ++n) _Pragma("unroll") for (int k = 0; k < 2; ++k) \
;         acc[ai][bj][m][n] = __builtin_amdgcn_mfma_f32_16x16x32_bf16(Bt[n][k], At[m][k], acc[ai][bj][m][n], 0, 0, 0); __builtin_amdgcn_s_setprio(0); } while (0)
; #define PG8_WAIT_V(n) asm volatile("s_waitcnt vmcnt(" #n ")" ::: "memory")
; #define PG8_WAIT_L(n) asm volatile("s_waitcnt lgkmcnt(" #n ")" ::: "memory")
; #define PG8_BAR __builtin_amdgcn_s_barrier()
; #define PG8_SCHED __builtin_amdgcn_sched_barrier(0)
; template <class Epi, class Sched, bool ALIGN_EPI = true, bool SP2 = true>
; __device__ __forceinline__ void gemm_phase(LAS unsigned char* lds, const bf16_t* Ag, const bf16_t* Btg, const int K, const int lda, const int ldb, const Sched& S, const Epi& E) {
;     ...
;         for (int t = 0; t < nt; t += 2) {
;             const bool last = (t == nt - 2);
;             const char* a1 = cA + (size_t)(t + 1) * kstep;
;             const char* a2 = last ? nA : cA + (size_t)(t + 2) * kstep; const char* b2 = last ? nB : cB + (size_t)(t + 2) * kstep;
;             const char* a3 = a2 + kstep; const char* b3 = b2 + kstep;
;             if constexpr (SP2) {
;             PG8_LDB(B0, 0, 0); PG8_LDB(B1, 0, 1); PG8_SCHED; PG8_LDA(At, 0, 0); PG8_STAGE(PG8_SA(1, 1), a1 + hstepA, voffA);
;             PG8_WAIT_V(8); PG8_WAIT_L(0); PG8_BAR; PG8_MMA(0, 0, At, B0); PG8_MMA(0, 1, At, B1); PG8_BAR; PG8_SCHED;
;             PG8_LDA(At, 0, 1); PG8_STAGE(PG8_SB(0, 0), b2, voffB); PG8_STAGE(PG8_SB(0, 1), b2 + hstepB, voffB); PG8_STAGE(PG8_SA(0, 0), a2, voffA);
.LBB0_1369:
	ds_read_b128 v[152:155], v149
	ds_read_b128 v[156:159], v149 offset:1024
	ds_read_b128 v[160:163], v149 offset:2048
	ds_read_b128 v[168:171], v149 offset:3072
	ds_read_b128 v[172:175], v150
	ds_read_b128 v[180:183], v150 offset:1024
	ds_read_b128 v[184:187], v150 offset:2048
	ds_read_b128 v[188:191], v150 offset:3072
	s_add_u32 s26, s24, 0xfff80080
	s_addc_u32 s27, s25, -1
	s_cmp_eq_u32 s58, 28
	s_cselect_b32 s29, s52, s27
	s_cselect_b32 s28, s53, s26
	s_cselect_b32 s27, s54, s57
	s_cselect_b32 s26, s55, s56
	v_lshl_add_u64 v[146:147], s[24:25], 0, v[138:139]
	s_add_i32 m0, s34, 0xc000
	ds_read_b128 v[192:195], v151
	ds_read_b128 v[196:199], v151 offset:1024
	ds_read_b128 v[200:203], v151 offset:2048
	ds_read_b128 v[204:207], v151 offset:3072
	ds_read_b128 v[208:211], v151 offset:4096
	ds_read_b128 v[212:215], v151 offset:5120
	ds_read_b128 v[216:219], v151 offset:6144
	ds_read_b128 v[220:223], v151 offset:7168
	global_load_lds_dwordx4 v[146:147], off
	v_lshl_add_u64 v[146:147], s[24:25], 0, v[140:141]
	s_add_i32 m0, s34, 0xe000
	s_nop 0
	global_load_lds_dwordx4 v[146:147], off
	s_waitcnt vmcnt(8)
	s_waitcnt lgkmcnt(0)
	s_barrier
	s_setprio 1
	s_waitcnt lgkmcnt(0)
	v_mfma_f32_16x16x32_bf16 v[124:127], v[152:155], v[192:195], v[124:127]
	v_mfma_f32_16x16x32_bf16 v[120:123], v[160:163], v[192:195], v[120:123]
	v_mfma_f32_16x16x32_bf16 v[108:111], v[152:155], v[200:203], v[108:111]
	v_mfma_f32_16x16x32_bf16 v[104:107], v[160:163], v[200:203], v[104:107]
	v_mfma_f32_16x16x32_bf16 v[92:95], v[152:155], v[208:211], v[92:95]
	v_mfma_f32_16x16x32_bf16 v[88:91], v[160:163], v[208:211], v[88:91]
	v_mfma_f32_16x16x32_bf16 v[76:79], v[152:155], v[216:219], v[76:79]
	v_mfma_f32_16x16x32_bf16 v[72:75], v[160:163], v[216:219], v[72:75]
	v_mfma_f32_16x16x32_bf16 v[124:127], v[156:159], v[196:199], v[124:127]
	v_mfma_f32_16x16x32_bf16 v[120:123], v[168:171], v[196:199], v[120:123]
	v_mfma_f32_16x16x32_bf16 v[108:111], v[156:159], v[204:207], v[108:111]
	v_mfma_f32_16x16x32_bf16 v[104:107], v[168:171], v[204:207], v[104:107]
	v_mfma_f32_16x16x32_bf16 v[92:95], v[156:159], v[212:215], v[92:95]
	v_mfma_f32_16x16x32_bf16 v[88:91], v[168:171], v[212:215], v[88:91]
	v_mfma_f32_16x16x32_bf16 v[76:79], v[156:159], v[220:223], v[76:79]
	v_mfma_f32_16x16x32_bf16 v[72:75], v[168:171], v[220:223], v[72:75]
	v_mfma_f32_16x16x32_bf16 v[116:119], v[172:175], v[192:195], v[116:119]
	v_mfma_f32_16x16x32_bf16 v[112:115], v[184:187], v[192:195], v[112:115]
	v_mfma_f32_16x16x32_bf16 v[100:103], v[172:175], v[200:203], v[100:103]
	v_mfma_f32_16x16x32_bf16 v[96:99], v[184:187], v[200:203], v[96:99]
	v_mfma_f32_16x16x32_bf16 v[84:87], v[172:175], v[208:211], v[84:87]
	v_mfma_f32_16x16x32_bf16 v[80:83], v[184:187], v[208:211], v[80:83]
	v_mfma_f32_16x16x32_bf16 v[68:71], v[172:175], v[216:219], v[68:71]
	v_mfma_f32_16x16x32_bf16 v[64:67], v[184:187], v[216:219], v[64:67]
	v_mfma_f32_16x16x32_bf16 v[116:119], v[180:183], v[196:199], v[116:119]
	v_mfma_f32_16x16x32_bf16 v[112:115], v[188:191], v[196:199], v[112:115]
	v_mfma_f32_16x16x32_bf16 v[100:103], v[180:183], v[204:207], v[100:103]
	v_mfma_f32_16x16x32_bf16 v[96:99], v[188:191], v[204:207], v[96:99]
	v_mfma_f32_16x16x32_bf16 v[84:87], v[180:183], v[212:215], v[84:87]
	v_mfma_f32_16x16x32_bf16 v[80:83], v[188:191], v[212:215], v[80:83]
	s_setprio 2
	s_barrier
	v_mfma_f32_16x16x32_bf16 v[68:71], v[180:183], v[220:223], v[68:71]
	v_mfma_f32_16x16x32_bf16 v[64:67], v[188:191], v[220:223], v[64:67]
	s_setprio 0
	s_add_i32 s59, s43, s30
	v_lshl_add_u64 v[146:147], s[26:27], 0, v[132:133]
	s_mov_b32 m0, s59
	ds_read_b128 v[192:195], v151 offset:16384
	ds_read_b128 v[196:199], v151 offset:17408
	ds_read_b128 v[200:203], v151 offset:18432
	ds_read_b128 v[204:207], v151 offset:19456
	ds_read_b128 v[208:211], v151 offset:20480
	ds_read_b128 v[212:215], v151 offset:21504
	ds_read_b128 v[216:219], v151 offset:22528
	ds_read_b128 v[220:223], v151 offset:23552
	global_load_lds_dwordx4 v[146:147], off
	s_add_i32 m0, s59, 0x2000
	s_add_u32 s60, s26, 0x80000
	v_lshl_add_u64 v[164:165], s[26:27], 0, v[128:129]
	s_addc_u32 s61, s27, 0
	s_add_i32 s59, s44, s30
	global_load_lds_dwordx4 v[164:165], off
	v_lshl_add_u64 v[224:225], s[60:61], 0, v[132:133]
	s_mov_b32 m0, s59
	v_lshl_add_u64 v[226:227], s[28:29], 0, v[130:131]
	global_load_lds_dwordx4 v[224:225], off
	v_lshl_add_u64 v[224:225], s[60:61], 0, v[128:129]
	s_add_i32 m0, s59, 0x2000
	s_nop 0
	global_load_lds_dwordx4 v[224:225], off
	v_lshl_add_u64 v[224:225], s[28:29], 0, v[134:135]
	s_mov_b32 m0, s34
	s_nop 0
	global_load_lds_dwordx4 v[224:225], off
	s_mov_b32 m0, s35
	s_nop 0
	global_load_lds_dwordx4 v[226:227], off
	s_waitcnt vmcnt(8)
	s_waitcnt lgkmcnt(0)
	s_barrier
; #define PG8_STAGE(bufoff, gbase, voff) do { _Pragma("unroll") for (int _i = 0; _i < 2; ++_i) \
;         __builtin_amdgcn_global_load_lds((const unsigned*)((const char*)(gbase) + (voff)[_i]), (LAS unsigned*)(lds + (bufoff) + ldsw + _i * 8192), 16, 0, 0); } while (0)
; #define PG8_LDA(dst, b, h) do { _Pragma("unroll") for (int m = 0; m < 4; ++m) _Pragma("unroll") for (int k = 0; k < 2; ++k) dst[m][k] = *(const LAS bf16x8*)(lds + PG8_SA(b, h) + aoff + m * 2048 + k * 1024); } while (0)
; #define PG8_LDB(dst, b, h) do { _Pragma("unroll") for (int n = 0; n < 2; ++n) _Pragma("unroll") for (int k = 0; k < 2; ++k) dst[n][k] = *(const LAS bf16x8*)(lds + PG8_SB(b, h) + boff + n * 2048 + k * 1024); } while (0)
; #define PG8_MMA(ai, bj, At, Bt) do { __builtin_amdgcn_s_setprio(1); _Pragma("unroll") for (int m = 0; m < 4; ++m) _Pragma("unroll") for (int n = 0; n < 2; ++n) _Pragma("unroll") for (int k = 0; k < 2; ++k) \
;         acc[ai][bj][m][n] = __builtin_amdgcn_mfma_f32_16x16x32_bf16(Bt[n][k], At[m][k], acc[ai][bj][m][n], 0, 0, 0); __builtin_amdgcn_s_setprio(0); } while (0)
; #define PG8_WAIT_V(n) asm volatile("s_waitcnt vmcnt(" #n ")" ::: "memory")
; #define PG8_WAIT_L(n) asm volatile("s_waitcnt lgkmcnt(" #n ")" ::: "memory")
; #define PG8_BAR __builtin_amdgcn_s_barrier()
; #define PG8_SCHED __builtin_amdgcn_sched_barrier(0)
; template <class Epi, class Sched, bool ALIGN_EPI = true, bool SP2 = true>
; __device__ __forceinline__ void gemm_phase(LAS unsigned char* lds, const bf16_t* Ag, const bf16_t* Btg, const int K, const int lda, const int ldb, const Sched& S, const Epi& E) {
;     ...
;             PG8_WAIT_V(8); PG8_WAIT_L(0); PG8_BAR; PG8_MMA(1, 0, At, B0); PG8_MMA(1, 1, At, B1); PG8_BAR; PG8_SCHED;
;             PG8_LDB(B0, 1, 0); PG8_LDB(B1, 1, 1); PG8_SCHED; PG8_LDA(At, 1, 0); PG8_STAGE(PG8_SA(0, 1), a2 + hstepA, voffA);
;             PG8_WAIT_V(8); PG8_WAIT_L(0); PG8_BAR; PG8_MMA(0, 0, At, B0); PG8_MMA(0, 1, At, B1); PG8_BAR; PG8_SCHED;
	s_setprio 1
	s_waitcnt lgkmcnt(0)
	v_mfma_f32_16x16x32_bf16 v[60:63], v[152:155], v[192:195], v[60:63]
	v_mfma_f32_16x16x32_bf16 v[56:59], v[160:163], v[192:195], v[56:59]
	v_mfma_f32_16x16x32_bf16 v[44:47], v[152:155], v[200:203], v[44:47]
	v_mfma_f32_16x16x32_bf16 v[40:43], v[160:163], v[200:203], v[40:43]
	v_mfma_f32_16x16x32_bf16 v[28:31], v[152:155], v[208:211], v[28:31]
	v_mfma_f32_16x16x32_bf16 v[24:27], v[160:163], v[208:211], v[24:27]
	v_mfma_f32_16x16x32_bf16 v[12:15], v[152:155], v[216:219], v[12:15]
	v_mfma_f32_16x16x32_bf16 v[8:11], v[160:163], v[216:219], v[8:11]
	v_mfma_f32_16x16x32_bf16 v[60:63], v[156:159], v[196:199], v[60:63]
	v_mfma_f32_16x16x32_bf16 v[56:59], v[168:171], v[196:199], v[56:59]
	v_mfma_f32_16x16x32_bf16 v[44:47], v[156:159], v[204:207], v[44:47]
	v_mfma_f32_16x16x32_bf16 v[40:43], v[168:171], v[204:207], v[40:43]
	v_mfma_f32_16x16x32_bf16 v[28:31], v[156:159], v[212:215], v[28:31]
	v_mfma_f32_16x16x32_bf16 v[24:27], v[168:171], v[212:215], v[24:27]
	v_mfma_f32_16x16x32_bf16 v[12:15], v[156:159], v[220:223], v[12:15]
	v_mfma_f32_16x16x32_bf16 v[8:11], v[168:171], v[220:223], v[8:11]
	v_mfma_f32_16x16x32_bf16 v[52:55], v[172:175], v[192:195], v[52:55]
	v_mfma_f32_16x16x32_bf16 v[48:51], v[184:187], v[192:195], v[48:51]
	v_mfma_f32_16x16x32_bf16 v[36:39], v[172:175], v[200:203], v[36:39]
	v_mfma_f32_16x16x32_bf16 v[32:35], v[184:187], v[200:203], v[32:35]
	v_mfma_f32_16x16x32_bf16 v[20:23], v[172:175], v[208:211], v[20:23]
	v_mfma_f32_16x16x32_bf16 v[16:19], v[184:187], v[208:211], v[16:19]
	v_mfma_f32_16x16x32_bf16 v[4:7], v[172:175], v[216:219], v[4:7]
	v_mfma_f32_16x16x32_bf16 v[0:3], v[184:187], v[216:219], v[0:3]
	v_mfma_f32_16x16x32_bf16 v[52:55], v[180:183], v[196:199], v[52:55]
	v_mfma_f32_16x16x32_bf16 v[48:51], v[188:191], v[196:199], v[48:51]
	v_mfma_f32_16x16x32_bf16 v[36:39], v[180:183], v[204:207], v[36:39]
	v_mfma_f32_16x16x32_bf16 v[32:35], v[188:191], v[204:207], v[32:35]
	v_mfma_f32_16x16x32_bf16 v[20:23], v[180:183], v[212:215], v[20:23]
	v_mfma_f32_16x16x32_bf16 v[16:19], v[188:191], v[212:215], v[16:19]
	s_setprio 2
	s_barrier
	v_mfma_f32_16x16x32_bf16 v[4:7], v[180:183], v[220:223], v[4:7]
	v_mfma_f32_16x16x32_bf16 v[0:3], v[188:191], v[220:223], v[0:3]
	s_setprio 0
	s_add_i32 s59, 0, 0x18000
	v_add_u32_e32 v167, s59, v148
	s_add_i32 s60, 0, 0x1c000
	ds_read_b128 v[152:155], v167
	ds_read_b128 v[156:159], v167 offset:1024
	ds_read_b128 v[160:163], v167 offset:2048
	ds_read_b128 v[168:171], v167 offset:3072
	v_add_u32_e32 v167, s60, v148
	ds_read_b128 v[172:175], v167
	ds_read_b128 v[180:183], v167 offset:1024
	ds_read_b128 v[184:187], v167 offset:2048
	ds_read_b128 v[188:191], v167 offset:3072
	s_add_u32 s28, s28, 0x80000
	s_addc_u32 s29, s29, 0
	s_mov_b32 m0, s37
	v_lshl_add_u64 v[228:229], s[28:29], 0, v[134:135]
	ds_read_b128 v[192:195], v151 offset:32768
	ds_read_b128 v[196:199], v151 offset:33792
	ds_read_b128 v[200:203], v151 offset:34816
	ds_read_b128 v[204:207], v151 offset:35840
	ds_read_b128 v[208:211], v151 offset:36864
	ds_read_b128 v[212:215], v151 offset:37888
	ds_read_b128 v[216:219], v151 offset:38912
	ds_read_b128 v[220:223], v151 offset:39936
	global_load_lds_dwordx4 v[228:229], off
	v_lshl_add_u64 v[228:229], s[28:29], 0, v[130:131]
	s_mov_b32 m0, s38
	s_nop 0
	global_load_lds_dwordx4 v[228:229], off
	s_waitcnt vmcnt(8)
	s_waitcnt lgkmcnt(0)
	s_barrier
	s_setprio 1
	s_waitcnt lgkmcnt(0)
	v_mfma_f32_16x16x32_bf16 v[124:127], v[152:155], v[192:195], v[124:127]
	v_mfma_f32_16x16x32_bf16 v[120:123], v[160:163], v[192:195], v[120:123]
	v_mfma_f32_16x16x32_bf16 v[108:111], v[152:155], v[200:203], v[108:111]
	v_mfma_f32_16x16x32_bf16 v[104:107], v[160:163], v[200:203], v[104:107]
	v_mfma_f32_16x16x32_bf16 v[92:95], v[152:155], v[208:211], v[92:95]
	v_mfma_f32_16x16x32_bf16 v[88:91], v[160:163], v[208:211], v[88:91]
	v_mfma_f32_16x16x32_bf16 v[76:79], v[152:155], v[216:219], v[76:79]
	v_mfma_f32_16x16x32_bf16 v[72:75], v[160:163], v[216:219], v[72:75]
	v_mfma_f32_16x16x32_bf16 v[124:127], v[156:159], v[196:199], v[124:127]
	v_mfma_f32_16x16x32_bf16 v[120:123], v[168:171], v[196:199], v[120:123]
	v_mfma_f32_16x16x32_bf16 v[108:111], v[156:159], v[204:207], v[108:111]
	v_mfma_f32_16x16x32_bf16 v[104:107], v[168:171], v[204:207], v[104:107]
	v_mfma_f32_16x16x32_bf16 v[92:95], v[156:159], v[212:215], v[92:95]
	v_mfma_f32_16x16x32_bf16 v[88:91], v[168:171], v[212:215], v[88:91]
	v_mfma_f32_16x16x32_bf16 v[76:79], v[156:159], v[220:223], v[76:79]
	v_mfma_f32_16x16x32_bf16 v[72:75], v[168:171], v[220:223], v[72:75]
	v_mfma_f32_16x16x32_bf16 v[116:119], v[172:175], v[192:195], v[116:119]
	v_mfma_f32_16x16x32_bf16 v[112:115], v[184:187], v[192:195], v[112:115]
	v_mfma_f32_16x16x32_bf16 v[100:103], v[172:175], v[200:203], v[100:103]
	v_mfma_f32_16x16x32_bf16 v[96:99], v[184:187], v[200:203], v[96:99]
	v_mfma_f32_16x16x32_bf16 v[84:87], v[172:175], v[208:211], v[84:87]
	v_mfma_f32_16x16x32_bf16 v[80:83], v[184:187], v[208:211], v[80:83]
	v_mfma_f32_16x16x32_bf16 v[68:71], v[172:175], v[216:219], v[68:71]
	v_mfma_f32_16x16x32_bf16 v[64:67], v[184:187], v[216:219], v[64:67]
	v_mfma_f32_16x16x32_bf16 v[116:119], v[180:183], v[196:199], v[116:119]
	v_mfma_f32_16x16x32_bf16 v[112:115], v[188:191], v[196:199], v[112:115]
	v_mfma_f32_16x16x32_bf16 v[100:103], v[180:183], v[204:207], v[100:103]
	v_mfma_f32_16x16x32_bf16 v[96:99], v[188:191], v[204:207], v[96:99]
	v_mfma_f32_16x16x32_bf16 v[84:87], v[180:183], v[212:215], v[84:87]
	v_mfma_f32_16x16x32_bf16 v[80:83], v[188:191], v[212:215], v[80:83]
	s_setprio 2
	s_barrier
; #define PG8_STAGE(bufoff, gbase, voff) do { _Pragma("unroll") for (int _i = 0; _i < 2; ++_i) \
;         __builtin_amdgcn_global_load_lds((const unsigned*)((const char*)(gbase) + (voff)[_i]), (LAS unsigned*)(lds + (bufoff) + ldsw + _i * 8192), 16, 0, 0); } while (0)
; #define PG8_LDA(dst, b, h) do { _Pragma("unroll") for (int m = 0; m < 4; ++m) _Pragma("unroll") for (int k = 0; k < 2; ++k) dst[m][k] = *(const LAS bf16x8*)(lds + PG8_SA(b, h) + aoff + m * 2048 + k * 1024); } while (0)
; #define PG8_LDB(dst, b, h) do { _Pragma("unroll") for (int n = 0; n < 2; ++n) _Pragma("unroll") for (int k = 0; k < 2; ++k) dst[n][k] = *(const LAS bf16x8*)(lds + PG8_SB(b, h) + boff + n * 2048 + k * 1024); } while (0)
; template <class Epi, class Sched, bool ALIGN_EPI = true, bool SP2 = true>
; __device__ __forceinline__ void gemm_phase(LAS unsigned char* lds, const bf16_t* Ag, const bf16_t* Btg, const int K, const int lda, const int ldb, const Sched& S, const Epi& E) {
;     ...
;         for (int t = 0; t < nt; t += 2) {
;             const bool last = (t == nt - 2);
;             const char* a1 = cA + (size_t)(t + 1) * kstep;
;             const char* a2 = last ? nA : cA + (size_t)(t + 2) * kstep; const char* b2 = last ? nB : cB + (size_t)(t + 2) * kstep;
;             const char* a3 = a2 + kstep; const char* b3 = b2 + kstep;
;             if constexpr (SP2) {
;             PG8_LDB(B0, 0, 0); PG8_LDB(B1, 0, 1); PG8_SCHED; PG8_LDA(At, 0, 0); PG8_STAGE(PG8_SA(1, 1), a1 + hstepA, voffA);
;             PG8_WAIT_V(8); PG8_WAIT_L(0); PG8_BAR; PG8_MMA(0, 0, At, B0); PG8_MMA(0, 1, At, B1); PG8_BAR; PG8_SCHED;
;             PG8_LDA(At, 0, 1); PG8_STAGE(PG8_SB(0, 0), b2, voffB); PG8_STAGE(PG8_SB(0, 1), b2 + hstepB, voffB); PG8_STAGE(PG8_SA(0, 0), a2, voffA);
;             PG8_WAIT_V(8); PG8_WAIT_L(0); PG8_BAR; PG8_MMA(1, 0, At, B0); PG8_MMA(1, 1, At, B1); PG8_BAR; PG8_SCHED;
;             PG8_LDB(B0, 1, 0); PG8_LDB(B1, 1, 1); PG8_SCHED; PG8_LDA(At, 1, 0); PG8_STAGE(PG8_SA(0, 1), a2 + hstepA, voffA);
;             PG8_WAIT_V(8); PG8_WAIT_L(0); PG8_BAR; PG8_MMA(0, 0, At, B0); PG8_MMA(0, 1, At, B1); PG8_BAR; PG8_SCHED;
;             PG8_LDA(At, 1, 1); PG8_STAGE(PG8_SB(1, 0), b3, voffB); PG8_STAGE(PG8_SB(1, 1), b3 + hstepB, voffB); PG8_STAGE(PG8_SA(1, 0), a3, voffA);
;             PG8_WAIT_V(8); PG8_WAIT_L(0); PG8_BAR; PG8_MMA(1, 0, At, B0); PG8_MMA(1, 1, At, B1); PG8_BAR; PG8_SCHED;
	v_mfma_f32_16x16x32_bf16 v[68:71], v[180:183], v[220:223], v[68:71]
	v_mfma_f32_16x16x32_bf16 v[64:67], v[188:191], v[220:223], v[64:67]
	s_setprio 0
	s_add_i32 s28, s59, s30
	v_lshl_add_u64 v[146:147], v[146:147], 0, s[8:9]
	s_mov_b32 m0, s28
	ds_read_b128 v[192:195], v151 offset:49152
	ds_read_b128 v[196:199], v151 offset:50176
	ds_read_b128 v[200:203], v151 offset:51200
	ds_read_b128 v[204:207], v151 offset:52224
	ds_read_b128 v[208:211], v151 offset:53248
	ds_read_b128 v[212:215], v151 offset:54272
	ds_read_b128 v[216:219], v151 offset:55296
	ds_read_b128 v[220:223], v151 offset:56320
	global_load_lds_dwordx4 v[146:147], off
	s_add_i32 m0, s28, 0x2000
	s_add_u32 s26, s26, 0x80080
	v_lshl_add_u64 v[146:147], v[164:165], 0, s[8:9]
	s_addc_u32 s27, s27, 0
	s_add_i32 s28, s60, s30
	global_load_lds_dwordx4 v[146:147], off
	v_lshl_add_u64 v[146:147], s[26:27], 0, v[132:133]
	s_mov_b32 m0, s28
	s_nop 0
	global_load_lds_dwordx4 v[146:147], off
	v_lshl_add_u64 v[146:147], s[26:27], 0, v[128:129]
	s_add_i32 m0, s28, 0x2000
	s_nop 0
	global_load_lds_dwordx4 v[146:147], off
	v_lshl_add_u64 v[146:147], v[224:225], 0, s[8:9]
	s_mov_b32 m0, s39
	s_nop 0
	global_load_lds_dwordx4 v[146:147], off
	v_lshl_add_u64 v[146:147], v[226:227], 0, s[8:9]
	s_mov_b32 m0, s40
	s_nop 0
	global_load_lds_dwordx4 v[146:147], off
	s_waitcnt vmcnt(8)
	s_waitcnt lgkmcnt(0)
	s_barrier
	s_setprio 1
	s_waitcnt lgkmcnt(0)
	v_mfma_f32_16x16x32_bf16 v[60:63], v[152:155], v[192:195], v[60:63]
	v_mfma_f32_16x16x32_bf16 v[56:59], v[160:163], v[192:195], v[56:59]
	v_mfma_f32_16x16x32_bf16 v[44:47], v[152:155], v[200:203], v[44:47]
	v_mfma_f32_16x16x32_bf16 v[40:43], v[160:163], v[200:203], v[40:43]
	v_mfma_f32_16x16x32_bf16 v[28:31], v[152:155], v[208:211], v[28:31]
	v_mfma_f32_16x16x32_bf16 v[24:27], v[160:163], v[208:211], v[24:27]
	v_mfma_f32_16x16x32_bf16 v[12:15], v[152:155], v[216:219], v[12:15]
	v_mfma_f32_16x16x32_bf16 v[8:11], v[160:163], v[216:219], v[8:11]
	v_mfma_f32_16x16x32_bf16 v[60:63], v[156:159], v[196:199], v[60:63]
	v_mfma_f32_16x16x32_bf16 v[56:59], v[168:171], v[196:199], v[56:59]
	v_mfma_f32_16x16x32_bf16 v[44:47], v[156:159], v[204:207], v[44:47]
	v_mfma_f32_16x16x32_bf16 v[40:43], v[168:171], v[204:207], v[40:43]
	v_mfma_f32_16x16x32_bf16 v[28:31], v[156:159], v[212:215], v[28:31]
	v_mfma_f32_16x16x32_bf16 v[24:27], v[168:171], v[212:215], v[24:27]
	v_mfma_f32_16x16x32_bf16 v[12:15], v[156:159], v[220:223], v[12:15]
	v_mfma_f32_16x16x32_bf16 v[8:11], v[168:171], v[220:223], v[8:11]
	v_mfma_f32_16x16x32_bf16 v[52:55], v[172:175], v[192:195], v[52:55]
	v_mfma_f32_16x16x32_bf16 v[48:51], v[184:187], v[192:195], v[48:51]
	v_mfma_f32_16x16x32_bf16 v[36:39], v[172:175], v[200:203], v[36:39]
	v_mfma_f32_16x16x32_bf16 v[32:35], v[184:187], v[200:203], v[32:35]
	v_mfma_f32_16x16x32_bf16 v[20:23], v[172:175], v[208:211], v[20:23]
	v_mfma_f32_16x16x32_bf16 v[16:19], v[184:187], v[208:211], v[16:19]
	v_mfma_f32_16x16x32_bf16 v[4:7], v[172:175], v[216:219], v[4:7]
	v_mfma_f32_16x16x32_bf16 v[0:3], v[184:187], v[216:219], v[0:3]
	v_mfma_f32_16x16x32_bf16 v[52:55], v[180:183], v[196:199], v[52:55]
	v_mfma_f32_16x16x32_bf16 v[48:51], v[188:191], v[196:199], v[48:51]
	v_mfma_f32_16x16x32_bf16 v[36:39], v[180:183], v[204:207], v[36:39]
	v_mfma_f32_16x16x32_bf16 v[32:35], v[188:191], v[204:207], v[32:35]
	v_mfma_f32_16x16x32_bf16 v[20:23], v[180:183], v[212:215], v[20:23]
	v_mfma_f32_16x16x32_bf16 v[16:19], v[188:191], v[212:215], v[16:19]
	s_setprio 2
	s_barrier
	v_mfma_f32_16x16x32_bf16 v[4:7], v[180:183], v[220:223], v[4:7]
	v_mfma_f32_16x16x32_bf16 v[0:3], v[188:191], v[220:223], v[0:3]
	s_setprio 0
	s_add_i32 s58, s58, 2
	s_add_u32 s24, s24, 0x100
	s_addc_u32 s25, s25, 0
	s_add_u32 s56, s56, 0x100
	s_addc_u32 s57, s57, 0
	s_cmp_gt_u32 s58, 29
	s_cbranch_scc0 .LBB0_1369
	s_and_b64 vcc, exec, s[10:11]
	s_cbranch_vccz .LBB0_1372
	s_barrier

; #define PG8_STAGE(bufoff, gbase, voff) do { _Pragma("unroll") for (int _i = 0; _i < 2; ++_i) \
;         __builtin_amdgcn_global_load_lds((const unsigned*)((const char*)(gbase) + (voff)[_i]), (LAS unsigned*)(lds + (bufoff) + ldsw + _i * 8192), 16, 0, 0); } while (0)
; #define PG8_LDA(dst, b, h) do { _Pragma("unroll") for (int m = 0; m < 4; ++m) _Pragma("unroll") for (int k = 0; k < 2; ++k) dst[m][k] = *(const LAS bf16x8*)(lds + PG8_SA(b, h) + aoff + m * 2048 + k * 1024); } while (0)
; #define PG8_LDB(dst, b, h) do { _Pragma("unroll") for (int n = 0; n < 2; ++n) _Pragma("unroll") for (int k = 0; k < 2; ++k) dst[n][k] = *(const LAS bf16x8*)(lds + PG8_SB(b, h) + boff + n * 2048 + k * 1024); } while (0)
; #define PG8_MMA(ai, bj, At, Bt) do { __builtin_amdgcn_s_setprio(1); _Pragma("unroll") for (int m = 0; m < 4; ++m) _Pragma("unroll") for (int n = 0; n < 2; ++n) _Pragma("unroll") for (int k = 0; k < 2; ++k) \
;         acc[ai][bj][m][n] = __builtin_amdgcn_mfma_f32_16x16x32_bf16(Bt[n][k], At[m][k], acc[ai][bj][m][n], 0, 0, 0); __builtin_amdgcn_s_setprio(0); } while (0)
; #define PG8_WAIT_V(n) asm volatile("s_waitcnt vmcnt(" #n ")" ::: "memory")
; #define PG8_WAIT_L(n) asm volatile("s_waitcnt lgkmcnt(" #n ")" ::: "memory")
; #define PG8_BAR __builtin_amdgcn_s_barrier()
; #define PG8_SCHED __builtin_amdgcn_sched_barrier(0)
; template <class Epi, class Sched, bool ALIGN_EPI = true, bool SP2 = true>
; __device__ __forceinline__ void gemm_phase(LAS unsigned char* lds, const bf16_t* Ag, const bf16_t* Btg, const int K, const int lda, const int ldb, const Sched& S, const Epi& E) {
;     ...
;         for (int t = 0; t < nt; t += 2) {
;             const bool last = (t == nt - 2);
;             const char* a1 = cA + (size_t)(t + 1) * kstep;
;             const char* a2 = last ? nA : cA + (size_t)(t + 2) * kstep; const char* b2 = last ? nB : cB + (size_t)(t + 2) * kstep;
;             const char* a3 = a2 + kstep; const char* b3 = b2 + kstep;
;             if constexpr (SP2) {
;             PG8_LDB(B0, 0, 0); PG8_LDB(B1, 0, 1); PG8_SCHED; PG8_LDA(At, 0, 0); PG8_STAGE(PG8_SA(1, 1), a1 + hstepA, voffA);
;             PG8_WAIT_V(8); PG8_WAIT_L(0); PG8_BAR; PG8_MMA(0, 0, At, B0); PG8_MMA(0, 1, At, B1); PG8_BAR; PG8_SCHED;
;             PG8_LDA(At, 0, 1); PG8_STAGE(PG8_SB(0, 0), b2, voffB); PG8_STAGE(PG8_SB(0, 1), b2 + hstepB, voffB); PG8_STAGE(PG8_SA(0, 0), a2, voffA);
.LBB0_1448:
	ds_read_b128 v[152:155], v149
	ds_read_b128 v[156:159], v149 offset:1024
	ds_read_b128 v[160:163], v149 offset:2048
	ds_read_b128 v[164:167], v149 offset:3072
	ds_read_b128 v[168:171], v150
	ds_read_b128 v[172:175], v150 offset:1024
	ds_read_b128 v[178:181], v150 offset:2048
	ds_read_b128 v[182:185], v150 offset:3072
	s_add_u32 s54, s52, 0xffea0080
	s_addc_u32 s55, s53, -1
	s_cmpk_eq_i32 s79, 0x54
	s_cselect_b32 s57, s33, s55
	s_cselect_b32 s56, s74, s54
	s_cselect_b32 s55, s75, s78
	s_cselect_b32 s54, s76, s77
	v_lshl_add_u64 v[146:147], s[52:53], 0, v[138:139]
	s_add_i32 m0, s41, 0xc000
	ds_read_b128 v[186:189], v151
	ds_read_b128 v[190:193], v151 offset:1024
	ds_read_b128 v[194:197], v151 offset:2048
	ds_read_b128 v[198:201], v151 offset:3072
	ds_read_b128 v[202:205], v151 offset:4096
	ds_read_b128 v[206:209], v151 offset:5120
	ds_read_b128 v[210:213], v151 offset:6144
	ds_read_b128 v[214:217], v151 offset:7168
	global_load_lds_dwordx4 v[146:147], off
	v_lshl_add_u64 v[146:147], s[52:53], 0, v[140:141]
	s_add_i32 m0, s41, 0xe000
	s_nop 0
	global_load_lds_dwordx4 v[146:147], off
	s_waitcnt vmcnt(8)
	s_waitcnt lgkmcnt(0)
	s_barrier
	s_setprio 1
	s_waitcnt lgkmcnt(0)
	v_mfma_f32_16x16x32_bf16 v[124:127], v[152:155], v[186:189], v[124:127]
	v_mfma_f32_16x16x32_bf16 v[120:123], v[160:163], v[186:189], v[120:123]
	v_mfma_f32_16x16x32_bf16 v[108:111], v[152:155], v[194:197], v[108:111]
	v_mfma_f32_16x16x32_bf16 v[104:107], v[160:163], v[194:197], v[104:107]
	v_mfma_f32_16x16x32_bf16 v[92:95], v[152:155], v[202:205], v[92:95]
	v_mfma_f32_16x16x32_bf16 v[88:91], v[160:163], v[202:205], v[88:91]
	v_mfma_f32_16x16x32_bf16 v[76:79], v[152:155], v[210:213], v[76:79]
	v_mfma_f32_16x16x32_bf16 v[72:75], v[160:163], v[210:213], v[72:75]
	v_mfma_f32_16x16x32_bf16 v[124:127], v[156:159], v[190:193], v[124:127]
	v_mfma_f32_16x16x32_bf16 v[120:123], v[164:167], v[190:193], v[120:123]
	v_mfma_f32_16x16x32_bf16 v[108:111], v[156:159], v[198:201], v[108:111]
	v_mfma_f32_16x16x32_bf16 v[104:107], v[164:167], v[198:201], v[104:107]
	v_mfma_f32_16x16x32_bf16 v[92:95], v[156:159], v[206:209], v[92:95]
	v_mfma_f32_16x16x32_bf16 v[88:91], v[164:167], v[206:209], v[88:91]
	v_mfma_f32_16x16x32_bf16 v[76:79], v[156:159], v[214:217], v[76:79]
	v_mfma_f32_16x16x32_bf16 v[72:75], v[164:167], v[214:217], v[72:75]
	v_mfma_f32_16x16x32_bf16 v[116:119], v[168:171], v[186:189], v[116:119]
	v_mfma_f32_16x16x32_bf16 v[112:115], v[178:181], v[186:189], v[112:115]
	v_mfma_f32_16x16x32_bf16 v[100:103], v[168:171], v[194:197], v[100:103]
	v_mfma_f32_16x16x32_bf16 v[96:99], v[178:181], v[194:197], v[96:99]
	v_mfma_f32_16x16x32_bf16 v[84:87], v[168:171], v[202:205], v[84:87]
	v_mfma_f32_16x16x32_bf16 v[80:83], v[178:181], v[202:205], v[80:83]
	v_mfma_f32_16x16x32_bf16 v[68:71], v[168:171], v[210:213], v[68:71]
	v_mfma_f32_16x16x32_bf16 v[64:67], v[178:181], v[210:213], v[64:67]
	v_mfma_f32_16x16x32_bf16 v[116:119], v[172:175], v[190:193], v[116:119]
	v_mfma_f32_16x16x32_bf16 v[112:115], v[182:185], v[190:193], v[112:115]
	v_mfma_f32_16x16x32_bf16 v[100:103], v[172:175], v[198:201], v[100:103]
	v_mfma_f32_16x16x32_bf16 v[96:99], v[182:185], v[198:201], v[96:99]
	v_mfma_f32_16x16x32_bf16 v[84:87], v[172:175], v[206:209], v[84:87]
	v_mfma_f32_16x16x32_bf16 v[80:83], v[182:185], v[206:209], v[80:83]
	s_setprio 2
	s_barrier
	v_mfma_f32_16x16x32_bf16 v[68:71], v[172:175], v[214:217], v[68:71]
	v_mfma_f32_16x16x32_bf16 v[64:67], v[182:185], v[214:217], v[64:67]
	s_setprio 0
	s_add_i32 s80, s66, s40
	v_lshl_add_u64 v[146:147], s[54:55], 0, v[130:131]
	s_mov_b32 m0, s80
	ds_read_b128 v[186:189], v151 offset:16384
	ds_read_b128 v[190:193], v151 offset:17408
	ds_read_b128 v[194:197], v151 offset:18432
	ds_read_b128 v[198:201], v151 offset:19456
	ds_read_b128 v[202:205], v151 offset:20480
	ds_read_b128 v[206:209], v151 offset:21504
	ds_read_b128 v[210:213], v151 offset:22528
	ds_read_b128 v[214:217], v151 offset:23552
	global_load_lds_dwordx4 v[146:147], off
	s_add_i32 m0, s80, 0x2000
	s_add_u32 s80, s54, 0x160000
	v_lshl_add_u64 v[218:219], s[54:55], 0, v[134:135]
	s_addc_u32 s81, s55, 0
	s_add_i32 s82, s67, s40
	global_load_lds_dwordx4 v[218:219], off
	v_lshl_add_u64 v[220:221], s[80:81], 0, v[130:131]
	s_mov_b32 m0, s82
	v_lshl_add_u64 v[222:223], s[56:57], 0, v[132:133]
	global_load_lds_dwordx4 v[220:221], off
	v_lshl_add_u64 v[220:221], s[80:81], 0, v[134:135]
	s_add_i32 m0, s82, 0x2000
	s_nop 0
	global_load_lds_dwordx4 v[220:221], off
	v_lshl_add_u64 v[220:221], s[56:57], 0, v[128:129]
	s_mov_b32 m0, s41
	s_nop 0
	global_load_lds_dwordx4 v[220:221], off
	s_mov_b32 m0, s58
	s_nop 0
	global_load_lds_dwordx4 v[222:223], off
	s_waitcnt vmcnt(8)
	s_waitcnt lgkmcnt(0)
	s_barrier
; #define PG8_STAGE(bufoff, gbase, voff) do { _Pragma("unroll") for (int _i = 0; _i < 2; ++_i) \
;         __builtin_amdgcn_global_load_lds((const unsigned*)((const char*)(gbase) + (voff)[_i]), (LAS unsigned*)(lds + (bufoff) + ldsw + _i * 8192), 16, 0, 0); } while (0)
; #define PG8_LDA(dst, b, h) do { _Pragma("unroll") for (int m = 0; m < 4; ++m) _Pragma("unroll") for (int k = 0; k < 2; ++k) dst[m][k] = *(const LAS bf16x8*)(lds + PG8_SA(b, h) + aoff + m * 2048 + k * 1024); } while (0)
; #define PG8_LDB(dst, b, h) do { _Pragma("unroll") for (int n = 0; n < 2; ++n) _Pragma("unroll") for (int k = 0; k < 2; ++k) dst[n][k] = *(const LAS bf16x8*)(lds + PG8_SB(b, h) + boff + n * 2048 + k * 1024); } while (0)
; #define PG8_MMA(ai, bj, At, Bt) do { __builtin_amdgcn_s_setprio(1); _Pragma("unroll") for (int m = 0; m < 4; ++m) _Pragma("unroll") for (int n = 0; n < 2; ++n) _Pragma("unroll") for (int k = 0; k < 2; ++k) \
;         acc[ai][bj][m][n] = __builtin_amdgcn_mfma_f32_16x16x32_bf16(Bt[n][k], At[m][k], acc[ai][bj][m][n], 0, 0, 0); __builtin_amdgcn_s_setprio(0); } while (0)
; #define PG8_WAIT_V(n) asm volatile("s_waitcnt vmcnt(" #n ")" ::: "memory")
; #define PG8_WAIT_L(n) asm volatile("s_waitcnt lgkmcnt(" #n ")" ::: "memory")
; #define PG8_BAR __builtin_amdgcn_s_barrier()
; #define PG8_SCHED __builtin_amdgcn_sched_barrier(0)
; template <class Epi, class Sched, bool ALIGN_EPI = true, bool SP2 = true>
; __device__ __forceinline__ void gemm_phase(LAS unsigned char* lds, const bf16_t* Ag, const bf16_t* Btg, const int K, const int lda, const int ldb, const Sched& S, const Epi& E) {
;     ...
;             PG8_WAIT_V(8); PG8_WAIT_L(0); PG8_BAR; PG8_MMA(1, 0, At, B0); PG8_MMA(1, 1, At, B1); PG8_BAR; PG8_SCHED;
;             PG8_LDB(B0, 1, 0); PG8_LDB(B1, 1, 1); PG8_SCHED; PG8_LDA(At, 1, 0); PG8_STAGE(PG8_SA(0, 1), a2 + hstepA, voffA);
;             PG8_WAIT_V(8); PG8_WAIT_L(0); PG8_BAR; PG8_MMA(0, 0, At, B0); PG8_MMA(0, 1, At, B1); PG8_BAR; PG8_SCHED;
	s_setprio 1
	s_waitcnt lgkmcnt(0)
	v_mfma_f32_16x16x32_bf16 v[60:63], v[152:155], v[186:189], v[60:63]
	v_mfma_f32_16x16x32_bf16 v[56:59], v[160:163], v[186:189], v[56:59]
	v_mfma_f32_16x16x32_bf16 v[44:47], v[152:155], v[194:197], v[44:47]
	v_mfma_f32_16x16x32_bf16 v[40:43], v[160:163], v[194:197], v[40:43]
	v_mfma_f32_16x16x32_bf16 v[28:31], v[152:155], v[202:205], v[28:31]
	v_mfma_f32_16x16x32_bf16 v[24:27], v[160:163], v[202:205], v[24:27]
	v_mfma_f32_16x16x32_bf16 v[12:15], v[152:155], v[210:213], v[12:15]
	v_mfma_f32_16x16x32_bf16 v[8:11], v[160:163], v[210:213], v[8:11]
	v_mfma_f32_16x16x32_bf16 v[60:63], v[156:159], v[190:193], v[60:63]
	v_mfma_f32_16x16x32_bf16 v[56:59], v[164:167], v[190:193], v[56:59]
	v_mfma_f32_16x16x32_bf16 v[44:47], v[156:159], v[198:201], v[44:47]
	v_mfma_f32_16x16x32_bf16 v[40:43], v[164:167], v[198:201], v[40:43]
	v_mfma_f32_16x16x32_bf16 v[28:31], v[156:159], v[206:209], v[28:31]
	v_mfma_f32_16x16x32_bf16 v[24:27], v[164:167], v[206:209], v[24:27]
	v_mfma_f32_16x16x32_bf16 v[12:15], v[156:159], v[214:217], v[12:15]
	v_mfma_f32_16x16x32_bf16 v[8:11], v[164:167], v[214:217], v[8:11]
	v_mfma_f32_16x16x32_bf16 v[52:55], v[168:171], v[186:189], v[52:55]
	v_mfma_f32_16x16x32_bf16 v[48:51], v[178:181], v[186:189], v[48:51]
	v_mfma_f32_16x16x32_bf16 v[36:39], v[168:171], v[194:197], v[36:39]
	v_mfma_f32_16x16x32_bf16 v[32:35], v[178:181], v[194:197], v[32:35]
	v_mfma_f32_16x16x32_bf16 v[20:23], v[168:171], v[202:205], v[20:23]
	v_mfma_f32_16x16x32_bf16 v[16:19], v[178:181], v[202:205], v[16:19]
	v_mfma_f32_16x16x32_bf16 v[4:7], v[168:171], v[210:213], v[4:7]
	v_mfma_f32_16x16x32_bf16 v[0:3], v[178:181], v[210:213], v[0:3]
	v_mfma_f32_16x16x32_bf16 v[52:55], v[172:175], v[190:193], v[52:55]
	v_mfma_f32_16x16x32_bf16 v[48:51], v[182:185], v[190:193], v[48:51]
	v_mfma_f32_16x16x32_bf16 v[36:39], v[172:175], v[198:201], v[36:39]
	v_mfma_f32_16x16x32_bf16 v[32:35], v[182:185], v[198:201], v[32:35]
	v_mfma_f32_16x16x32_bf16 v[20:23], v[172:175], v[206:209], v[20:23]
	v_mfma_f32_16x16x32_bf16 v[16:19], v[182:185], v[206:209], v[16:19]
	s_setprio 2
	s_barrier
	v_mfma_f32_16x16x32_bf16 v[4:7], v[172:175], v[214:217], v[4:7]
	v_mfma_f32_16x16x32_bf16 v[0:3], v[182:185], v[214:217], v[0:3]
	s_setprio 0
	s_add_i32 s80, 0, 0x18000
	s_add_i32 s81, 0, 0x1c000
	v_add_u32_e32 v164, s80, v148
	v_add_u32_e32 v177, s81, v148
	ds_read_b128 v[152:155], v164
	ds_read_b128 v[156:159], v164 offset:1024
	ds_read_b128 v[160:163], v164 offset:2048
	ds_read_b128 v[164:167], v164 offset:3072
	ds_read_b128 v[168:171], v177
	ds_read_b128 v[172:175], v177 offset:1024
	ds_read_b128 v[178:181], v177 offset:2048
	ds_read_b128 v[182:185], v177 offset:3072
	s_add_u32 s56, s56, 0x160000
	s_addc_u32 s57, s57, 0
	s_mov_b32 m0, s59
	v_lshl_add_u64 v[224:225], s[56:57], 0, v[128:129]
	ds_read_b128 v[186:189], v151 offset:32768
	ds_read_b128 v[190:193], v151 offset:33792
	ds_read_b128 v[194:197], v151 offset:34816
	ds_read_b128 v[198:201], v151 offset:35840
	ds_read_b128 v[202:205], v151 offset:36864
	ds_read_b128 v[206:209], v151 offset:37888
	ds_read_b128 v[210:213], v151 offset:38912
	ds_read_b128 v[214:217], v151 offset:39936
	global_load_lds_dwordx4 v[224:225], off
	v_lshl_add_u64 v[224:225], s[56:57], 0, v[132:133]
	s_mov_b32 m0, s60
	s_nop 0
	global_load_lds_dwordx4 v[224:225], off
	s_waitcnt vmcnt(8)
	s_waitcnt lgkmcnt(0)
	s_barrier
	s_setprio 1
	s_waitcnt lgkmcnt(0)
	v_mfma_f32_16x16x32_bf16 v[124:127], v[152:155], v[186:189], v[124:127]
	v_mfma_f32_16x16x32_bf16 v[120:123], v[160:163], v[186:189], v[120:123]
	v_mfma_f32_16x16x32_bf16 v[108:111], v[152:155], v[194:197], v[108:111]
	v_mfma_f32_16x16x32_bf16 v[104:107], v[160:163], v[194:197], v[104:107]
	v_mfma_f32_16x16x32_bf16 v[92:95], v[152:155], v[202:205], v[92:95]
	v_mfma_f32_16x16x32_bf16 v[88:91], v[160:163], v[202:205], v[88:91]
	v_mfma_f32_16x16x32_bf16 v[76:79], v[152:155], v[210:213], v[76:79]
	v_mfma_f32_16x16x32_bf16 v[72:75], v[160:163], v[210:213], v[72:75]
	v_mfma_f32_16x16x32_bf16 v[124:127], v[156:159], v[190:193], v[124:127]
	v_mfma_f32_16x16x32_bf16 v[120:123], v[164:167], v[190:193], v[120:123]
	v_mfma_f32_16x16x32_bf16 v[108:111], v[156:159], v[198:201], v[108:111]
	v_mfma_f32_16x16x32_bf16 v[104:107], v[164:167], v[198:201], v[104:107]
	v_mfma_f32_16x16x32_bf16 v[92:95], v[156:159], v[206:209], v[92:95]
	v_mfma_f32_16x16x32_bf16 v[88:91], v[164:167], v[206:209], v[88:91]
	v_mfma_f32_16x16x32_bf16 v[76:79], v[156:159], v[214:217], v[76:79]
	v_mfma_f32_16x16x32_bf16 v[72:75], v[164:167], v[214:217], v[72:75]
	v_mfma_f32_16x16x32_bf16 v[116:119], v[168:171], v[186:189], v[116:119]
	v_mfma_f32_16x16x32_bf16 v[112:115], v[178:181], v[186:189], v[112:115]
	v_mfma_f32_16x16x32_bf16 v[100:103], v[168:171], v[194:197], v[100:103]
	v_mfma_f32_16x16x32_bf16 v[96:99], v[178:181], v[194:197], v[96:99]
	v_mfma_f32_16x16x32_bf16 v[84:87], v[168:171], v[202:205], v[84:87]
	v_mfma_f32_16x16x32_bf16 v[80:83], v[178:181], v[202:205], v[80:83]
	v_mfma_f32_16x16x32_bf16 v[68:71], v[168:171], v[210:213], v[68:71]
	v_mfma_f32_16x16x32_bf16 v[64:67], v[178:181], v[210:213], v[64:67]
	v_mfma_f32_16x16x32_bf16 v[116:119], v[172:175], v[190:193], v[116:119]
	v_mfma_f32_16x16x32_bf16 v[112:115], v[182:185], v[190:193], v[112:115]
	v_mfma_f32_16x16x32_bf16 v[100:103], v[172:175], v[198:201], v[100:103]
	v_mfma_f32_16x16x32_bf16 v[96:99], v[182:185], v[198:201], v[96:99]
	v_mfma_f32_16x16x32_bf16 v[84:87], v[172:175], v[206:209], v[84:87]
	v_mfma_f32_16x16x32_bf16 v[80:83], v[182:185], v[206:209], v[80:83]
	s_setprio 2
	s_barrier
; #define PG8_STAGE(bufoff, gbase, voff) do { _Pragma("unroll") for (int _i = 0; _i < 2; ++_i) \
;         __builtin_amdgcn_global_load_lds((const unsigned*)((const char*)(gbase) + (voff)[_i]), (LAS unsigned*)(lds + (bufoff) + ldsw + _i * 8192), 16, 0, 0); } while (0)
; #define PG8_LDA(dst, b, h) do { _Pragma("unroll") for (int m = 0; m < 4; ++m) _Pragma("unroll") for (int k = 0; k < 2; ++k) dst[m][k] = *(const LAS bf16x8*)(lds + PG8_SA(b, h) + aoff + m * 2048 + k * 1024); } while (0)
; #define PG8_LDB(dst, b, h) do { _Pragma("unroll") for (int n = 0; n < 2; ++n) _Pragma("unroll") for (int k = 0; k < 2; ++k) dst[n][k] = *(const LAS bf16x8*)(lds + PG8_SB(b, h) + boff + n * 2048 + k * 1024); } while (0)
; template <class Epi, class Sched, bool ALIGN_EPI = true, bool SP2 = true>
; __device__ __forceinline__ void gemm_phase(LAS unsigned char* lds, const bf16_t* Ag, const bf16_t* Btg, const int K, const int lda, const int ldb, const Sched& S, const Epi& E) {
;     ...
;         for (int t = 0; t < nt; t += 2) {
;             const bool last = (t == nt - 2);
;             const char* a1 = cA + (size_t)(t + 1) * kstep;
;             const char* a2 = last ? nA : cA + (size_t)(t + 2) * kstep; const char* b2 = last ? nB : cB + (size_t)(t + 2) * kstep;
;             const char* a3 = a2 + kstep; const char* b3 = b2 + kstep;
;             if constexpr (SP2) {
;             PG8_LDB(B0, 0, 0); PG8_LDB(B1, 0, 1); PG8_SCHED; PG8_LDA(At, 0, 0); PG8_STAGE(PG8_SA(1, 1), a1 + hstepA, voffA);
;             PG8_WAIT_V(8); PG8_WAIT_L(0); PG8_BAR; PG8_MMA(0, 0, At, B0); PG8_MMA(0, 1, At, B1); PG8_BAR; PG8_SCHED;
;             PG8_LDA(At, 0, 1); PG8_STAGE(PG8_SB(0, 0), b2, voffB); PG8_STAGE(PG8_SB(0, 1), b2 + hstepB, voffB); PG8_STAGE(PG8_SA(0, 0), a2, voffA);
;             PG8_WAIT_V(8); PG8_WAIT_L(0); PG8_BAR; PG8_MMA(1, 0, At, B0); PG8_MMA(1, 1, At, B1); PG8_BAR; PG8_SCHED;
;             PG8_LDB(B0, 1, 0); PG8_LDB(B1, 1, 1); PG8_SCHED; PG8_LDA(At, 1, 0); PG8_STAGE(PG8_SA(0, 1), a2 + hstepA, voffA);
;             PG8_WAIT_V(8); PG8_WAIT_L(0); PG8_BAR; PG8_MMA(0, 0, At, B0); PG8_MMA(0, 1, At, B1); PG8_BAR; PG8_SCHED;
;             PG8_LDA(At, 1, 1); PG8_STAGE(PG8_SB(1, 0), b3, voffB); PG8_STAGE(PG8_SB(1, 1), b3 + hstepB, voffB); PG8_STAGE(PG8_SA(1, 0), a3, voffA);
;             PG8_WAIT_V(8); PG8_WAIT_L(0); PG8_BAR; PG8_MMA(1, 0, At, B0); PG8_MMA(1, 1, At, B1); PG8_BAR; PG8_SCHED;
	v_mfma_f32_16x16x32_bf16 v[68:71], v[172:175], v[214:217], v[68:71]
	v_mfma_f32_16x16x32_bf16 v[64:67], v[182:185], v[214:217], v[64:67]
	s_setprio 0
	s_add_i32 s56, s80, s40
	v_lshl_add_u64 v[146:147], v[146:147], 0, s[6:7]
	s_mov_b32 m0, s56
	ds_read_b128 v[186:189], v151 offset:49152
	ds_read_b128 v[190:193], v151 offset:50176
	ds_read_b128 v[194:197], v151 offset:51200
	ds_read_b128 v[198:201], v151 offset:52224
	ds_read_b128 v[202:205], v151 offset:53248
	ds_read_b128 v[206:209], v151 offset:54272
	ds_read_b128 v[210:213], v151 offset:55296
	ds_read_b128 v[214:217], v151 offset:56320
	global_load_lds_dwordx4 v[146:147], off
	s_add_i32 m0, s56, 0x2000
	s_add_u32 s54, s54, 0x160080
	v_lshl_add_u64 v[146:147], v[218:219], 0, s[6:7]
	s_addc_u32 s55, s55, 0
	s_add_i32 s56, s81, s40
	global_load_lds_dwordx4 v[146:147], off
	v_lshl_add_u64 v[146:147], s[54:55], 0, v[130:131]
	s_mov_b32 m0, s56
	s_nop 0
	global_load_lds_dwordx4 v[146:147], off
	v_lshl_add_u64 v[146:147], s[54:55], 0, v[134:135]
	s_add_i32 m0, s56, 0x2000
	s_nop 0
	global_load_lds_dwordx4 v[146:147], off
	v_lshl_add_u64 v[146:147], v[220:221], 0, s[6:7]
	s_mov_b32 m0, s62
	s_nop 0
	global_load_lds_dwordx4 v[146:147], off
	v_lshl_add_u64 v[146:147], v[222:223], 0, s[6:7]
	s_mov_b32 m0, s63
	s_nop 0
	global_load_lds_dwordx4 v[146:147], off
	s_waitcnt vmcnt(8)
	s_waitcnt lgkmcnt(0)
	s_barrier
	s_setprio 1
	s_waitcnt lgkmcnt(0)
	v_mfma_f32_16x16x32_bf16 v[60:63], v[152:155], v[186:189], v[60:63]
	v_mfma_f32_16x16x32_bf16 v[56:59], v[160:163], v[186:189], v[56:59]
	v_mfma_f32_16x16x32_bf16 v[44:47], v[152:155], v[194:197], v[44:47]
	v_mfma_f32_16x16x32_bf16 v[40:43], v[160:163], v[194:197], v[40:43]
	v_mfma_f32_16x16x32_bf16 v[28:31], v[152:155], v[202:205], v[28:31]
	v_mfma_f32_16x16x32_bf16 v[24:27], v[160:163], v[202:205], v[24:27]
	v_mfma_f32_16x16x32_bf16 v[12:15], v[152:155], v[210:213], v[12:15]
	v_mfma_f32_16x16x32_bf16 v[8:11], v[160:163], v[210:213], v[8:11]
	v_mfma_f32_16x16x32_bf16 v[60:63], v[156:159], v[190:193], v[60:63]
	v_mfma_f32_16x16x32_bf16 v[56:59], v[164:167], v[190:193], v[56:59]
	v_mfma_f32_16x16x32_bf16 v[44:47], v[156:159], v[198:201], v[44:47]
	v_mfma_f32_16x16x32_bf16 v[40:43], v[164:167], v[198:201], v[40:43]
	v_mfma_f32_16x16x32_bf16 v[28:31], v[156:159], v[206:209], v[28:31]
	v_mfma_f32_16x16x32_bf16 v[24:27], v[164:167], v[206:209], v[24:27]
	v_mfma_f32_16x16x32_bf16 v[12:15], v[156:159], v[214:217], v[12:15]
	v_mfma_f32_16x16x32_bf16 v[8:11], v[164:167], v[214:217], v[8:11]
	v_mfma_f32_16x16x32_bf16 v[52:55], v[168:171], v[186:189], v[52:55]
	v_mfma_f32_16x16x32_bf16 v[48:51], v[178:181], v[186:189], v[48:51]
	v_mfma_f32_16x16x32_bf16 v[36:39], v[168:171], v[194:197], v[36:39]
	v_mfma_f32_16x16x32_bf16 v[32:35], v[178:181], v[194:197], v[32:35]
	v_mfma_f32_16x16x32_bf16 v[20:23], v[168:171], v[202:205], v[20:23]
	v_mfma_f32_16x16x32_bf16 v[16:19], v[178:181], v[202:205], v[16:19]
	v_mfma_f32_16x16x32_bf16 v[4:7], v[168:171], v[210:213], v[4:7]
	v_mfma_f32_16x16x32_bf16 v[0:3], v[178:181], v[210:213], v[0:3]
	v_mfma_f32_16x16x32_bf16 v[52:55], v[172:175], v[190:193], v[52:55]
	v_mfma_f32_16x16x32_bf16 v[48:51], v[182:185], v[190:193], v[48:51]
	v_mfma_f32_16x16x32_bf16 v[36:39], v[172:175], v[198:201], v[36:39]
	v_mfma_f32_16x16x32_bf16 v[32:35], v[182:185], v[198:201], v[32:35]
	v_mfma_f32_16x16x32_bf16 v[20:23], v[172:175], v[206:209], v[20:23]
	v_mfma_f32_16x16x32_bf16 v[16:19], v[182:185], v[206:209], v[16:19]
	s_setprio 2
	s_barrier
	v_mfma_f32_16x16x32_bf16 v[4:7], v[172:175], v[214:217], v[4:7]
	v_mfma_f32_16x16x32_bf16 v[0:3], v[182:185], v[214:217], v[0:3]
	s_setprio 0
	s_add_i32 s79, s79, 2
	s_add_u32 s52, s52, 0x100
	s_addc_u32 s53, s53, 0
	s_add_u32 s77, s77, 0x100
	s_addc_u32 s78, s78, 0
	s_cmpk_gt_u32 s79, 0x55
	s_cbranch_scc0 .LBB0_1448
	s_and_b64 vcc, exec, s[8:9]
	s_cbranch_vccz .LBB0_1451
	s_barrier
